# seams Wo->GU0, GU0->D0, GU1->D1 made XCD-local barriers (row panels stay on their XCD: no L2 write-back / cross-XCD round / sc1 invalidate; L1 dropped with buffer_inv sc0, consumer LDS-DMA loads sc0)
# speedup vs baseline: 1.0057x; 1.0057x over previous
; __device__ __forceinline__ unsigned xb_ld(unsigned* p)              { return __hip_atomic_load(p, __ATOMIC_RELAXED, __HIP_MEMORY_SCOPE_AGENT); }
; __device__ __forceinline__ unsigned xb_add(unsigned* p, unsigned v) { return __hip_atomic_fetch_add(p, v, __ATOMIC_RELAXED, __HIP_MEMORY_SCOPE_AGENT); }
; #define XB_SPIN(cond, bar) do { unsigned _sp = 0; while (cond) { __builtin_amdgcn_s_sleep(1); \
;     if ((++_sp & 255u) == 0u) { if (xb_ld(&(bar)[XB_TMO])) break; if (_sp > XB_SPIN_CAP) { atomicAdd(&(bar)[XB_TMO], 1u); break; } } } } while (0)
; __device__ __forceinline__ void xcd_barrier(const XcdBarrier& b) {
;     asm volatile("s_waitcnt vmcnt(0)" ::: "memory");
;     __syncthreads();
;     if (threadIdx.x == 0) {
;         unsigned* bar = b.bar;
;         __builtin_amdgcn_s_waitcnt(0);
;         unsigned nloc = b.st[0], nx = b.st[1];
;         if (nloc == 0u) { xcd_barrier_complete(bar, b.x, nloc, nx); b.st[0] = nloc; b.st[1] = nx; }
;         const unsigned old = xb_add(&bar[XB_XSUB(b.x)], 1u);
;         const unsigned gen = old / nloc;
;         if (old + 1u == (gen + 1u) * nloc) {
;             __builtin_amdgcn_fence(__ATOMIC_RELEASE, "agent");
;             asm volatile("s_waitcnt vmcnt(0)" ::: "memory");
;             const unsigned og = xb_add(&bar[XB_TOP], 1u);
;             const unsigned tg = og / nx;
;             if (og + 1u == (tg + 1u) * nx) xb_add(&bar[XB_TOPGEN], 1u);
;             else XB_SPIN(xb_ld(&bar[XB_TOPGEN]) == tg, bar);
;             __builtin_amdgcn_fence(__ATOMIC_ACQUIRE, "agent");
;             xb_add(&bar[XB_XGEN(b.x)], 1u);
;             asm volatile("s_waitcnt vmcnt(0)" ::: "memory");
;         } else {
;             XB_SPIN(xb_ld(&bar[XB_XGEN(b.x)]) == gen, bar);
;             __builtin_amdgcn_fence(__ATOMIC_ACQUIRE, "agent");
;             asm volatile("s_waitcnt vmcnt(0)" ::: "memory");
;         }
;     }
;     __syncthreads();
; }
.LBB0_448:
	s_or_b64 exec, exec, s[16:17]
	s_waitcnt vmcnt(0)
	buffer_inv sc0
	s_waitcnt vmcnt(0)
.LBB0_449:
	s_andn2_saveexec_b64 s[12:13], s[12:13]
	s_cbranch_execz .LBB0_469
	s_mov_b64 s[12:13], exec
	s_mov_b64 s[12:13], exec
	v_mbcnt_lo_u32_b32 v0, s12, 0
	v_mbcnt_hi_u32_b32 v0, s13, v0
	v_cmp_eq_u32_e32 vcc, 0, v0
	s_waitcnt vmcnt(0)
	buffer_inv sc0
	s_and_saveexec_b64 s[16:17], vcc
	s_cbranch_execz .LBB0_468
	s_bcnt1_i32_b64 s12, s[12:13]
	v_mov_b32_e32 v0, 0x2000
	v_mov_b32_e32 v1, s12
	global_atomic_add v0, v1, s[8:9] offset:1024

; #define PG8_STAGE(bufoff, gbase, voff) do { _Pragma("unroll") for (int _i = 0; _i < 2; ++_i) \
;         __builtin_amdgcn_global_load_lds((const unsigned*)((const char*)(gbase) + (voff)[_i]), (PG8_LAS unsigned*)(lds + (bufoff) + ldsw + _i * 8192), 16, 0, 0); } while (0)
; #define PG8_WAIT_V(n) asm volatile("s_waitcnt vmcnt(" #n ")" ::: "memory")
; #define PG8_BAR __builtin_amdgcn_s_barrier()
; template <class Epi, class Sched, bool ALIGN_EPI = false, bool SP2 = false>
; __device__ __forceinline__ void gemm_phase(PG8_LAS unsigned char* lds, const Gemm g, const Sched& S, const Epi& E) {
;     const int tid = threadIdx.x, wid = __builtin_amdgcn_readfirstlane(tid >> 6), lane = tid & 63, wr = wid >> 2, wc = wid & 3, fr = lane & 15, fq = lane >> 4;
;     const int K = g.K, nt = K / BK;
;     unsigned voffA[2], voffB[2];
; #pragma unroll
;     for (int i = 0; i < 2; ++i) { int R, C; stage_rc(tid * 16 + i * 8192, R, C); const int Rb = Epi::PERM ? ((R & ~31) + perm32(R & 31)) : R;
;         voffA[i] = (unsigned)(R * K + C) * 2u; voffB[i] = (unsigned)(Rb * K + C) * 2u; }
;     const size_t kstep = (size_t)(BK * 2);
;     const size_t hstep = (size_t)HALF * K * 2;
;     const size_t tstep = 2 * hstep;
;     const unsigned ldsw = (unsigned)wid * 1024u;
;     const int aoff = lds_byte(wr * 64 + fr, fq * 8), boff = lds_byte(wc * 32 + fr, fq * 8);
;     ...
;     Unit cur, nxt; int ui = 0;
;     if (!S.next(0, cur)) return;
;     f32x4 acc[2][2][4][2];
; #pragma unroll
;     for (int a = 0; a < 2; ++a)
; #pragma unroll
;         for (int b = 0; b < 2; ++b)
; #pragma unroll
;             for (int m = 0; m < 4; ++m)
; #pragma unroll
;                 for (int n = 0; n < 2; ++n) acc[a][b][m][n] = (f32x4){0.f, 0.f, 0.f, 0.f};
;     bf16x8 At[4][2], B0[2][2], B1[2][2];
;     const char* cA = (const char*)g.A + (size_t)cur.pm * tstep; const char* cB = (const char*)g.Bt + (size_t)cur.pn * tstep;
;     S.a_ready(cur);
;     if constexpr (SP2) {
;         PG8_STAGE(PG8_SB(0, 0), cB, voffB); PG8_STAGE(PG8_SB(0, 1), cB + hstep, voffB); PG8_STAGE(PG8_SA(0, 0), cA, voffA); PG8_STAGE(PG8_SA(0, 1), cA + hstep, voffA);
;         if (wr == 1) PG8_BAR;
;         PG8_WAIT_V(2); PG8_BAR;
;         PG8_STAGE(PG8_SB(1, 0), cB + kstep, voffB); PG8_STAGE(PG8_SA(1, 0), cA + kstep, voffA); PG8_STAGE(PG8_SB(1, 1), cB + hstep + kstep, voffB);
;         PG8_WAIT_V(6); PG8_BAR;
.LBB0_470:
	s_cmp_lt_i32 s72, 5
	s_cselect_b64 s[4:5], -1, 0
	s_and_b64 s[0:1], s[4:5], s[0:1]
	s_andn2_b64 vcc, exec, s[0:1]
	s_cbranch_vccnz .LBB0_489
	s_abs_i32 s4, s74
	v_cvt_f32_u32_e32 v0, s4
	s_add_i32 s5, s74, 0x2bff
	s_sub_i32 s8, 0xffffd401, s74
	s_xor_b32 s9, s5, s74
	v_rcp_iflag_f32_e32 v0, v0
	s_max_i32 s5, s5, s8
	s_sub_i32 s8, 0, s4
	s_ashr_i32 s9, s9, 31
	v_mul_f32_e32 v0, 0x4f7ffffe, v0
	v_cvt_u32_f32_e32 v0, v0
	s_nop 0
	v_readfirstlane_b32 s12, v0
	s_mul_i32 s8, s8, s12
	s_mul_hi_u32 s8, s12, s8
	s_add_i32 s12, s12, s8
	s_mul_hi_u32 s8, s5, s12
	s_mul_i32 s12, s8, s4
	s_sub_i32 s5, s5, s12
	s_add_i32 s13, s8, 1
	s_sub_i32 s12, s5, s4
	s_cmp_ge_u32 s5, s4
	s_cselect_b32 s8, s13, s8
	s_cselect_b32 s5, s12, s5
	s_add_i32 s12, s8, 1
	s_cmp_ge_u32 s5, s4
	s_cselect_b32 s4, s12, s8
	s_xor_b32 s4, s4, s9
	s_sub_i32 s22, s4, s9
	s_cmp_lt_i32 s22, 1
	v_readfirstlane_b32 s13, v230
	s_cbranch_scc1 .LBB0_489
	s_cmpk_gt_i32 s2, 0x2bff
	s_cbranch_scc1 .LBB0_489
	v_lshrrev_b32_e32 v2, 1, v230
	v_lshrrev_b32_e32 v3, 5, v230
	v_and_b32_e32 v2, 24, v2
	v_and_b32_e32 v3, 4, v3
	v_bfe_u32 v4, v230, 2, 2
	v_lshlrev_b32_e32 v0, 4, v230
	s_waitcnt lgkmcnt(0)
	v_and_b32_e32 v1, 32, v230
	v_bfe_u32 v10, v230, 2, 4
	v_or3_b32 v2, v3, v4, v2
	v_lshrrev_b32_e32 v3, 3, v230
	s_movk_i32 s4, 0x70
	v_bitop3_b32 v8, v0, v1, 48 bitop3:0x6c
	v_and_b32_e32 v9, 64, v230
	v_and_or_b32 v4, v3, s4, v10
	s_movk_i32 s4, 0x60
	v_add_u32_e32 v11, 0x2000, v0
	s_add_u32 s23, s70, 0x3c680000
	v_or_b32_e32 v1, v8, v9
	v_and_or_b32 v3, v3, s4, v2
	v_lshrrev_b32_e32 v0, 7, v11
	s_movk_i32 s4, 0xf0
	s_addc_u32 s24, s71, 0
	v_lshl_or_b32 v130, v3, 11, v1
	v_and_or_b32 v3, v0, s4, v10
	s_movk_i32 s4, 0xe0
	s_ashr_i32 s26, s2, 31
	v_and_or_b32 v0, v0, s4, v2
	s_lshr_b32 s4, s26, 29
	s_add_i32 s4, s2, s4
	s_lshr_b32 s8, s13, 6
	s_ashr_i32 s5, s4, 3
	s_and_b32 s4, s4, -8
	s_lshr_b32 s16, s13, 8
	s_lshl_b32 s25, s8, 10
	s_sub_i32 s4, s2, s4
	s_cmp_lt_i32 s4, 0
	s_movk_i32 s27, 0x581
	s_cselect_b32 s9, s27, 0x580
	s_mul_i32 s4, s4, s9
	s_add_i32 s4, s4, s5
	s_mul_hi_i32 s5, s4, 0x2e8ba2e9
	s_lshr_b32 s9, s5, 31
	s_ashr_i32 s5, s5, 5
	s_add_i32 s5, s5, s9
	s_lshl_b32 s9, s5, 3
	s_mulk_i32 s5, 0xb0
	s_sub_i32 s4, s4, s5
	s_bfe_u32 s5, s4, 0x3001c
	s_add_i32 s5, s4, s5
	s_and_b32 s12, s5, 0xfff8
	s_sub_i32 s4, s4, s12
	s_sext_i32_i16 s4, s4
	s_add_i32 s40, s9, s4
	s_sext_i32_i16 s4, s5
	s_lshr_b32 s12, s4, 3
	s_ashr_i32 s41, s40, 31
	s_bfe_i64 s[18:19], s[12:13], 0x100000
	s_lshl_b64 s[4:5], s[40:41], 19
	s_lshl_b64 s[18:19], s[18:19], 19
	s_add_u32 s44, s23, s18
	s_addc_u32 s45, s24, s19
	s_add_i32 s28, s25, 0
	s_add_i32 m0, s28, 0x10000
	v_lshl_or_b32 v134, v0, 11, v1
	global_load_lds_dwordx4 v130, s[44:45] sc0
	s_add_i32 m0, s28, 0x12000
	s_add_u32 s18, s44, 0x40000
	global_load_lds_dwordx4 v134, s[44:45] sc0
	s_addc_u32 s19, s45, 0
	s_add_i32 m0, s28, 0x14000
	v_lshl_or_b32 v128, v4, 11, v1
	global_load_lds_dwordx4 v130, s[18:19] sc0
	s_add_i32 m0, s28, 0x16000
	s_add_u32 s42, s70, s4
	s_addc_u32 s43, s71, s5
	s_add_i32 s29, s28, 0x2000
	global_load_lds_dwordx4 v134, s[18:19] sc0
	s_mov_b32 m0, s28
	s_add_u32 s4, s42, 0x40000
	v_lshl_or_b32 v132, v3, 11, v1
	global_load_lds_dwordx4 v128, s[42:43] sc0
	s_mov_b32 m0, s29
	s_addc_u32 s5, s43, 0
	s_add_i32 s30, s28, 0x4000
	global_load_lds_dwordx4 v132, s[42:43] sc0
	s_mov_b32 m0, s30
	s_add_i32 s31, s28, 0x6000
	global_load_lds_dwordx4 v128, s[4:5] sc0
	s_mov_b32 m0, s31
	v_mov_b32_e32 v131, 0
	global_load_lds_dwordx4 v132, s[4:5] sc0
	v_mov_b32_e32 v135, v131
	v_mov_b32_e32 v129, v131
	v_mov_b32_e32 v133, v131
	s_cmp_eq_u32 s16, 1
	s_mov_b32 s33, 0
	v_lshl_add_u64 v[6:7], s[44:45], 0, v[130:131]
	v_lshl_add_u64 v[4:5], s[44:45], 0, v[134:135]
	v_lshl_add_u64 v[0:1], s[42:43], 0, v[128:129]
	s_cselect_b64 s[4:5], -1, 0
	s_cmp_lg_u32 s16, 1
	v_lshl_add_u64 v[2:3], s[42:43], 0, v[132:133]
	s_cbranch_scc1 .LBB0_475
	s_barrier
.LBB0_475:
	s_lshl_b32 s8, s8, 5
	s_and_b32 s20, s8, 0x60
	s_mov_b64 s[8:9], 0x80
	s_add_i32 m0, s28, 0x18000
	v_lshl_add_u64 v[6:7], v[6:7], 0, s[8:9]
	s_ashr_i32 s41, s74, 31
	s_lshl_b32 s17, s16, 13
	s_lshl_b32 s21, s20, 7
	s_waitcnt vmcnt(2)
	s_barrier
	global_load_lds_dwordx4 v[6:7], off sc0
	v_lshl_add_u64 v[4:5], v[4:5], 0, s[8:9]
	s_add_i32 m0, s28, 0x1a000
	s_add_i32 s48, s28, 0x8000
	s_add_i32 s49, s28, 0xa000
	global_load_lds_dwordx4 v[4:5], off sc0
	v_lshl_add_u64 v[0:1], v[0:1], 0, s[8:9]
	s_mov_b32 m0, s48
	s_add_u32 s18, s44, 0x40080
	global_load_lds_dwordx4 v[0:1], off sc0
	v_lshl_add_u64 v[0:1], v[2:3], 0, s[8:9]
	s_mov_b32 m0, s49
	s_addc_u32 s19, s45, 0
	global_load_lds_dwordx4 v[0:1], off sc0
	s_add_i32 m0, s28, 0x1c000
	v_lshl_add_u64 v[0:1], s[18:19], 0, v[130:131]
	global_load_lds_dwordx4 v[0:1], off sc0
	v_lshl_add_u64 v[0:1], s[18:19], 0, v[134:135]
	s_add_i32 m0, s28, 0x1e000
	v_bfe_u32 v2, v230, 4, 2
	global_load_lds_dwordx4 v[0:1], off sc0
	v_and_b32_e32 v1, 15, v230
	v_lshlrev_b32_e32 v0, 4, v2
	v_lshlrev_b32_e32 v3, 2, v230
	v_lshl_or_b32 v149, s16, 6, v1
	v_lshl_or_b32 v1, v1, 6, v0
	v_and_b32_e32 v3, 32, v3
	s_sext_i32_i16 s54, s12
	v_bitop3_b32 v4, v1, s17, v3 bitop3:0xde
	v_lshlrev_b32_e32 v1, 6, v230
	s_movk_i32 s12, 0x3c0
	v_and_or_b32 v1, v1, s12, v0
	v_bitop3_b32 v153, s21, v1, v3 bitop3:0xf6
	v_mov_b32_e32 v1, v131
	v_lshl_add_u64 v[136:137], s[34:35], 0, v[0:1]
	v_lshlrev_b32_e32 v0, 8, v230
	v_and_b32_e32 v0, 0x38000, v0
	v_lshlrev_b32_e32 v1, 11, v10
	v_or3_b32 v0, v8, v0, v1
	v_add_u32_e32 v138, v0, v9
	v_lshlrev_b32_e32 v0, 4, v11
	v_and_b32_e32 v0, 0x78000, v0
	s_waitcnt vmcnt(6)
	s_cmpk_lt_u32 s13, 0x100
	v_or3_b32 v0, v8, v0, v1
	s_cselect_b64 s[12:13], -1, 0
	v_add_u32_e32 v140, v0, v9
	s_add_i32 s51, 0, 0x10000
	s_add_i32 s52, 0, 0x14000
	v_mbcnt_lo_u32_b32 v0, -1, 0
	s_mov_b32 s50, s74
	v_lshl_or_b32 v157, v2, 3, s20
	v_mov_b32_e32 v139, v131
	v_mov_b32_e32 v141, v131
	v_add_u32_e32 v161, s51, v153
	v_add_u32_e32 v165, s52, v153
	v_add_u32_e32 v169, 0, v4
	v_mbcnt_hi_u32_b32 v175, -1, v0
	v_mov_b32_e32 v176, 0x358637bd
	s_movk_i32 s53, 0x1600
	v_mov_b64_e32 v[142:143], 0x2bff
	s_barrier
	s_branch .LBB0_478

; #define PG8_STAGE(bufoff, gbase, voff) do { _Pragma("unroll") for (int _i = 0; _i < 2; ++_i) \
;         __builtin_amdgcn_global_load_lds((const unsigned*)((const char*)(gbase) + (voff)[_i]), (PG8_LAS unsigned*)(lds + (bufoff) + ldsw + _i * 8192), 16, 0, 0); } while (0)
; #define PG8_LDA(dst, b, h) do { _Pragma("unroll") for (int m = 0; m < 4; ++m) _Pragma("unroll") for (int k = 0; k < 2; ++k) dst[m][k] = *(const PG8_LAS bf16x8*)(lds + PG8_SA(b, h) + aoff + m * 2048 + k * 1024); } while (0)
; #define PG8_LDB(dst, b, h) do { _Pragma("unroll") for (int n = 0; n < 2; ++n) _Pragma("unroll") for (int k = 0; k < 2; ++k) dst[n][k] = *(const PG8_LAS bf16x8*)(lds + PG8_SB(b, h) + boff + n * 2048 + k * 1024); } while (0)
; #define PG8_MMA(ai, bj, At, Bt) do { __builtin_amdgcn_s_setprio(1); _Pragma("unroll") for (int m = 0; m < 4; ++m) _Pragma("unroll") for (int n = 0; n < 2; ++n) _Pragma("unroll") for (int k = 0; k < 2; ++k) \
;         acc[ai][bj][m][n] = __builtin_amdgcn_mfma_f32_16x16x32_bf16(Bt[n][k], At[m][k], acc[ai][bj][m][n], 0, 0, 0); __builtin_amdgcn_s_setprio(0); } while (0)
; #define PG8_WAIT_V(n) asm volatile("s_waitcnt vmcnt(" #n ")" ::: "memory")
; #define PG8_BAR __builtin_amdgcn_s_barrier()
; template <class Epi, class Sched, bool ALIGN_EPI = false, bool SP2 = false>
; __device__ __forceinline__ void gemm_phase(PG8_LAS unsigned char* lds, const Gemm g, const Sched& S, const Epi& E) {
;     ...
;         for (int t = 0; t < nt; t += 2) {
;             const bool last = (t == nt - 2);
;             const char* a1 = cA + (size_t)(t + 1) * kstep;
;             const char* a2 = last ? nA : cA + (size_t)(t + 2) * kstep; const char* b2 = last ? nB : cB + (size_t)(t + 2) * kstep;
;             const char* a3 = a2 + kstep; const char* b3 = b2 + kstep;
;             if (last && has_next) S.a_ready(nxt);
;             if constexpr (SP2) {
;             PG8_LDB(B0, 0, 0); PG8_LDB(B1, 0, 1); PG8_SCHED; PG8_LDA(At, 0, 0); PG8_STAGE(PG8_SA(1, 1), a1 + hstep, voffA);
;             PG8_WAIT_V(8); PG8_WAIT_L(0); PG8_BAR; PG8_MMA(0, 0, At, B0); PG8_MMA(0, 1, At, B1); PG8_BAR; PG8_SCHED;
;             PG8_LDA(At, 0, 1); PG8_STAGE(PG8_SB(0, 0), b2, voffB); PG8_STAGE(PG8_SB(0, 1), b2 + hstep, voffB); PG8_STAGE(PG8_SA(0, 0), a2, voffA);
;             PG8_WAIT_V(8); PG8_WAIT_L(0); PG8_BAR; PG8_MMA(1, 0, At, B0); PG8_MMA(1, 1, At, B1); PG8_BAR; PG8_SCHED;
.LBB0_481:
	s_ashr_i32 s19, s18, 31
	s_lshl_b64 s[36:37], s[18:19], 19
	s_add_u32 s36, s70, s36
	s_addc_u32 s37, s71, s37
	s_and_b64 s[38:39], s[20:21], exec
	s_cselect_b32 s19, s37, s43
	s_cselect_b32 s55, s36, s42
	s_ashr_i32 s17, s16, 31
	s_lshl_b64 s[38:39], s[16:17], 19
	s_add_u32 s38, s23, s38
	s_addc_u32 s39, s24, s39
	s_and_b64 s[46:47], s[20:21], exec
	s_cselect_b32 s17, s39, s45
	s_cselect_b32 s56, s38, s44
	s_add_u32 s42, s42, 0x40080
	s_addc_u32 s43, s43, 0
	s_add_u32 s57, s44, 0x100
	s_addc_u32 s58, s45, 0
	s_mov_b32 s59, -2
	ds_read_b128 v[144:147], v161
	ds_read_b128 v[170:173], v161 offset:1024
	ds_read_b128 v[178:181], v161 offset:2048
	ds_read_b128 v[182:185], v161 offset:3072
	ds_read_b128 v[186:189], v165
	ds_read_b128 v[190:193], v165 offset:1024
	ds_read_b128 v[194:197], v165 offset:2048
	ds_read_b128 v[198:201], v165 offset:3072
	s_add_u32 s44, s42, 0xfffc0080
	s_addc_u32 s45, s43, -1
	s_cmp_eq_u32 s59, 12
	s_cselect_b32 s47, s19, s45
	s_cselect_b32 s46, s55, s44
	s_cselect_b32 s45, s17, s58
	s_cselect_b32 s44, s56, s57
	v_lshl_add_u64 v[150:151], s[42:43], 0, v[138:139]
	s_add_i32 m0, s28, 0xc000
	ds_read_b128 v[202:205], v169
	ds_read_b128 v[206:209], v169 offset:1024
	ds_read_b128 v[210:213], v169 offset:2048
	ds_read_b128 v[214:217], v169 offset:3072
	ds_read_b128 v[218:221], v169 offset:4096
	ds_read_b128 v[222:225], v169 offset:5120
	ds_read_b128 v[226:229], v169 offset:6144
	ds_read_b128 v[232:235], v169 offset:7168
	global_load_lds_dwordx4 v[150:151], off sc0
	v_lshl_add_u64 v[150:151], s[42:43], 0, v[140:141]
	s_add_i32 m0, s28, 0xe000
	s_nop 0
	global_load_lds_dwordx4 v[150:151], off sc0
	s_waitcnt vmcnt(8)
	s_waitcnt lgkmcnt(0)
	s_barrier
	s_setprio 1
	s_waitcnt lgkmcnt(0)
	v_mfma_f32_16x16x32_bf16 v[124:127], v[144:147], v[202:205], 0
	v_mfma_f32_16x16x32_bf16 v[116:119], v[178:181], v[202:205], 0
	v_mfma_f32_16x16x32_bf16 v[108:111], v[144:147], v[210:213], 0
	v_mfma_f32_16x16x32_bf16 v[100:103], v[178:181], v[210:213], 0
	v_mfma_f32_16x16x32_bf16 v[92:95], v[144:147], v[218:221], 0
	v_mfma_f32_16x16x32_bf16 v[84:87], v[178:181], v[218:221], 0
	v_mfma_f32_16x16x32_bf16 v[76:79], v[144:147], v[226:229], 0
	v_mfma_f32_16x16x32_bf16 v[68:71], v[178:181], v[226:229], 0
	v_mfma_f32_16x16x32_bf16 v[124:127], v[170:173], v[206:209], v[124:127]
	v_mfma_f32_16x16x32_bf16 v[116:119], v[182:185], v[206:209], v[116:119]
	v_mfma_f32_16x16x32_bf16 v[108:111], v[170:173], v[214:217], v[108:111]
	v_mfma_f32_16x16x32_bf16 v[100:103], v[182:185], v[214:217], v[100:103]
	v_mfma_f32_16x16x32_bf16 v[92:95], v[170:173], v[222:225], v[92:95]
	v_mfma_f32_16x16x32_bf16 v[84:87], v[182:185], v[222:225], v[84:87]
	v_mfma_f32_16x16x32_bf16 v[76:79], v[170:173], v[232:235], v[76:79]
	v_mfma_f32_16x16x32_bf16 v[68:71], v[182:185], v[232:235], v[68:71]
	s_setprio 0
	s_setprio 1
	v_mfma_f32_16x16x32_bf16 v[120:123], v[186:189], v[202:205], 0
	v_mfma_f32_16x16x32_bf16 v[112:115], v[194:197], v[202:205], 0
	v_mfma_f32_16x16x32_bf16 v[104:107], v[186:189], v[210:213], 0
	v_mfma_f32_16x16x32_bf16 v[96:99], v[194:197], v[210:213], 0
	v_mfma_f32_16x16x32_bf16 v[88:91], v[186:189], v[218:221], 0
	v_mfma_f32_16x16x32_bf16 v[80:83], v[194:197], v[218:221], 0
	v_mfma_f32_16x16x32_bf16 v[72:75], v[186:189], v[226:229], 0
	v_mfma_f32_16x16x32_bf16 v[64:67], v[194:197], v[226:229], 0
	v_mfma_f32_16x16x32_bf16 v[120:123], v[190:193], v[206:209], v[120:123]
	v_mfma_f32_16x16x32_bf16 v[112:115], v[198:201], v[206:209], v[112:115]
	v_mfma_f32_16x16x32_bf16 v[104:107], v[190:193], v[214:217], v[104:107]
	v_mfma_f32_16x16x32_bf16 v[96:99], v[198:201], v[214:217], v[96:99]
	v_mfma_f32_16x16x32_bf16 v[88:91], v[190:193], v[222:225], v[88:91]
	v_mfma_f32_16x16x32_bf16 v[80:83], v[198:201], v[222:225], v[80:83]
	v_mfma_f32_16x16x32_bf16 v[72:75], v[190:193], v[232:235], v[72:75]
	v_mfma_f32_16x16x32_bf16 v[64:67], v[198:201], v[232:235], v[64:67]
	s_setprio 0
	s_barrier
	s_add_i32 s60, s51, s25
	v_lshl_add_u64 v[150:151], s[44:45], 0, v[130:131]
	s_mov_b32 m0, s60
	ds_read_b128 v[202:205], v169 offset:16384
	ds_read_b128 v[206:209], v169 offset:17408
	ds_read_b128 v[210:213], v169 offset:18432
	ds_read_b128 v[214:217], v169 offset:19456
	ds_read_b128 v[218:221], v169 offset:20480
	ds_read_b128 v[222:225], v169 offset:21504
	ds_read_b128 v[226:229], v169 offset:22528
	ds_read_b128 v[232:235], v169 offset:23552
	global_load_lds_dwordx4 v[150:151], off sc0
	s_add_i32 m0, s60, 0x2000
	s_add_u32 s60, s44, 0x40000
	v_lshl_add_u64 v[154:155], s[44:45], 0, v[134:135]
	s_addc_u32 s61, s45, 0
	s_add_i32 s62, s52, s25
	global_load_lds_dwordx4 v[154:155], off sc0
	v_lshl_add_u64 v[158:159], s[60:61], 0, v[130:131]
	s_mov_b32 m0, s62
	v_lshl_add_u64 v[162:163], s[46:47], 0, v[132:133]
	global_load_lds_dwordx4 v[158:159], off sc0
	v_lshl_add_u64 v[158:159], s[60:61], 0, v[134:135]
	s_add_i32 m0, s62, 0x2000
	s_nop 0
	global_load_lds_dwordx4 v[158:159], off sc0
	v_lshl_add_u64 v[158:159], s[46:47], 0, v[128:129]
	s_mov_b32 m0, s28
	s_nop 0
	global_load_lds_dwordx4 v[158:159], off sc0
	s_mov_b32 m0, s29
	s_nop 0
	global_load_lds_dwordx4 v[162:163], off sc0
	s_cmp_lg_i32 s59, -2
	s_cbranch_scc1 .Lrsa_a_pl
	v_lshrrev_b32_e32 v250, 6, v230
	v_lshlrev_b32_e32 v250, 11, v250
	v_and_b32_e32 v251, 63, v230
	v_lshl_or_b32 v250, v251, 4, v250
	v_lshl_add_u32 v250, s40, 14, v250
	v_readfirstlane_b32 s98, v230
	s_lshr_b32 s98, s98, 6
	s_lshl_b32 s98, s98, 11
	s_add_i32 m0, s98, 0x20000
	s_add_u32 s100, s70, 0x3f000000
	s_addc_u32 s101, s71, 0
	global_load_lds_dwordx4 v250, s[100:101] sc0
	global_load_lds_dwordx4 v250, s[100:101] offset:1024 sc0
	s_waitcnt vmcnt(10)
	s_branch .Lrsa_b_pl

; #define PG8_STAGE(bufoff, gbase, voff) do { _Pragma("unroll") for (int _i = 0; _i < 2; ++_i) \
;         __builtin_amdgcn_global_load_lds((const unsigned*)((const char*)(gbase) + (voff)[_i]), (PG8_LAS unsigned*)(lds + (bufoff) + ldsw + _i * 8192), 16, 0, 0); } while (0)
; #define PG8_LDA(dst, b, h) do { _Pragma("unroll") for (int m = 0; m < 4; ++m) _Pragma("unroll") for (int k = 0; k < 2; ++k) dst[m][k] = *(const PG8_LAS bf16x8*)(lds + PG8_SA(b, h) + aoff + m * 2048 + k * 1024); } while (0)
; #define PG8_LDB(dst, b, h) do { _Pragma("unroll") for (int n = 0; n < 2; ++n) _Pragma("unroll") for (int k = 0; k < 2; ++k) dst[n][k] = *(const PG8_LAS bf16x8*)(lds + PG8_SB(b, h) + boff + n * 2048 + k * 1024); } while (0)
; #define PG8_MMA(ai, bj, At, Bt) do { __builtin_amdgcn_s_setprio(1); _Pragma("unroll") for (int m = 0; m < 4; ++m) _Pragma("unroll") for (int n = 0; n < 2; ++n) _Pragma("unroll") for (int k = 0; k < 2; ++k) \
;         acc[ai][bj][m][n] = __builtin_amdgcn_mfma_f32_16x16x32_bf16(Bt[n][k], At[m][k], acc[ai][bj][m][n], 0, 0, 0); __builtin_amdgcn_s_setprio(0); } while (0)
; #define PG8_WAIT_V(n) asm volatile("s_waitcnt vmcnt(" #n ")" ::: "memory")
; #define PG8_WAIT_L(n) asm volatile("s_waitcnt lgkmcnt(" #n ")" ::: "memory")
; #define PG8_BAR __builtin_amdgcn_s_barrier()
; #define PG8_SCHED __builtin_amdgcn_sched_barrier(0)
; template <class Epi, class Sched, bool ALIGN_EPI = false, bool SP2 = false>
; __device__ __forceinline__ void gemm_phase(PG8_LAS unsigned char* lds, const Gemm g, const Sched& S, const Epi& E) {
;     ...
;             PG8_WAIT_V(8); PG8_WAIT_L(0); PG8_BAR; PG8_MMA(1, 0, At, B0); PG8_MMA(1, 1, At, B1); PG8_BAR; PG8_SCHED;
;             PG8_LDB(B0, 1, 0); PG8_LDB(B1, 1, 1); PG8_SCHED; PG8_LDA(At, 1, 0); PG8_STAGE(PG8_SA(0, 1), a2 + hstep, voffA);
;             PG8_WAIT_V(8); PG8_WAIT_L(0); PG8_BAR; PG8_MMA(0, 0, At, B0); PG8_MMA(0, 1, At, B1); PG8_BAR; PG8_SCHED;
.Lrsa_b_pl:
	s_waitcnt lgkmcnt(0)
	s_barrier
	s_setprio 1
	s_waitcnt lgkmcnt(0)
	v_mfma_f32_16x16x32_bf16 v[60:63], v[144:147], v[202:205], 0
	v_mfma_f32_16x16x32_bf16 v[52:55], v[178:181], v[202:205], 0
	v_mfma_f32_16x16x32_bf16 v[44:47], v[144:147], v[210:213], 0
	v_mfma_f32_16x16x32_bf16 v[36:39], v[178:181], v[210:213], 0
	v_mfma_f32_16x16x32_bf16 v[28:31], v[144:147], v[218:221], 0
	v_mfma_f32_16x16x32_bf16 v[20:23], v[178:181], v[218:221], 0
	v_mfma_f32_16x16x32_bf16 v[12:15], v[144:147], v[226:229], 0
	v_mfma_f32_16x16x32_bf16 v[4:7], v[178:181], v[226:229], 0
	v_mfma_f32_16x16x32_bf16 v[60:63], v[170:173], v[206:209], v[60:63]
	v_mfma_f32_16x16x32_bf16 v[52:55], v[182:185], v[206:209], v[52:55]
	v_mfma_f32_16x16x32_bf16 v[44:47], v[170:173], v[214:217], v[44:47]
	v_mfma_f32_16x16x32_bf16 v[36:39], v[182:185], v[214:217], v[36:39]
	v_mfma_f32_16x16x32_bf16 v[28:31], v[170:173], v[222:225], v[28:31]
	v_mfma_f32_16x16x32_bf16 v[20:23], v[182:185], v[222:225], v[20:23]
	v_mfma_f32_16x16x32_bf16 v[12:15], v[170:173], v[232:235], v[12:15]
	v_mfma_f32_16x16x32_bf16 v[4:7], v[182:185], v[232:235], v[4:7]
	s_setprio 0
	s_setprio 1
	v_mfma_f32_16x16x32_bf16 v[56:59], v[186:189], v[202:205], 0
	v_mfma_f32_16x16x32_bf16 v[48:51], v[194:197], v[202:205], 0
	v_mfma_f32_16x16x32_bf16 v[40:43], v[186:189], v[210:213], 0
	v_mfma_f32_16x16x32_bf16 v[32:35], v[194:197], v[210:213], 0
	v_mfma_f32_16x16x32_bf16 v[24:27], v[186:189], v[218:221], 0
	v_mfma_f32_16x16x32_bf16 v[16:19], v[194:197], v[218:221], 0
	v_mfma_f32_16x16x32_bf16 v[8:11], v[186:189], v[226:229], 0
	v_mfma_f32_16x16x32_bf16 v[0:3], v[194:197], v[226:229], 0
	v_mfma_f32_16x16x32_bf16 v[56:59], v[190:193], v[206:209], v[56:59]
	v_mfma_f32_16x16x32_bf16 v[48:51], v[198:201], v[206:209], v[48:51]
	v_mfma_f32_16x16x32_bf16 v[40:43], v[190:193], v[214:217], v[40:43]
	v_mfma_f32_16x16x32_bf16 v[32:35], v[198:201], v[214:217], v[32:35]
	v_mfma_f32_16x16x32_bf16 v[24:27], v[190:193], v[222:225], v[24:27]
	v_mfma_f32_16x16x32_bf16 v[16:19], v[198:201], v[222:225], v[16:19]
	v_mfma_f32_16x16x32_bf16 v[8:11], v[190:193], v[232:235], v[8:11]
	v_mfma_f32_16x16x32_bf16 v[0:3], v[198:201], v[232:235], v[0:3]
	s_setprio 0
	s_barrier
	s_add_i32 s60, 0, 0x18000
	v_add_u32_e32 v148, s60, v153
	s_add_i32 s61, 0, 0x1c000
	ds_read_b128 v[144:147], v148
	ds_read_b128 v[170:173], v148 offset:1024
	ds_read_b128 v[178:181], v148 offset:2048
	ds_read_b128 v[182:185], v148 offset:3072
	v_add_u32_e32 v148, s61, v153
	ds_read_b128 v[186:189], v148
	ds_read_b128 v[190:193], v148 offset:1024
	ds_read_b128 v[194:197], v148 offset:2048
	ds_read_b128 v[198:201], v148 offset:3072
	s_add_u32 s46, s46, 0x40000
	s_addc_u32 s47, s47, 0
	s_mov_b32 m0, s30
	v_lshl_add_u64 v[166:167], s[46:47], 0, v[128:129]
	ds_read_b128 v[202:205], v169 offset:32768
	ds_read_b128 v[206:209], v169 offset:33792
	ds_read_b128 v[210:213], v169 offset:34816
	ds_read_b128 v[214:217], v169 offset:35840
	ds_read_b128 v[218:221], v169 offset:36864
	ds_read_b128 v[222:225], v169 offset:37888
	ds_read_b128 v[226:229], v169 offset:38912
	ds_read_b128 v[232:235], v169 offset:39936
	global_load_lds_dwordx4 v[166:167], off sc0
	v_lshl_add_u64 v[166:167], s[46:47], 0, v[132:133]
	s_mov_b32 m0, s31
	s_nop 0
	global_load_lds_dwordx4 v[166:167], off sc0
	s_cmp_lg_i32 s59, -2
	s_cbranch_scc1 .Lrsa_c_pl
	s_waitcnt vmcnt(10)
	s_branch .Lrsa_d_pl

; #define PG8_STAGE(bufoff, gbase, voff) do { _Pragma("unroll") for (int _i = 0; _i < 2; ++_i) \
;         __builtin_amdgcn_global_load_lds((const unsigned*)((const char*)(gbase) + (voff)[_i]), (PG8_LAS unsigned*)(lds + (bufoff) + ldsw + _i * 8192), 16, 0, 0); } while (0)
; #define PG8_LDA(dst, b, h) do { _Pragma("unroll") for (int m = 0; m < 4; ++m) _Pragma("unroll") for (int k = 0; k < 2; ++k) dst[m][k] = *(const PG8_LAS bf16x8*)(lds + PG8_SA(b, h) + aoff + m * 2048 + k * 1024); } while (0)
; #define PG8_MMA(ai, bj, At, Bt) do { __builtin_amdgcn_s_setprio(1); _Pragma("unroll") for (int m = 0; m < 4; ++m) _Pragma("unroll") for (int n = 0; n < 2; ++n) _Pragma("unroll") for (int k = 0; k < 2; ++k) \
;         acc[ai][bj][m][n] = __builtin_amdgcn_mfma_f32_16x16x32_bf16(Bt[n][k], At[m][k], acc[ai][bj][m][n], 0, 0, 0); __builtin_amdgcn_s_setprio(0); } while (0)
; #define PG8_WAIT_V(n) asm volatile("s_waitcnt vmcnt(" #n ")" ::: "memory")
; #define PG8_WAIT_L(n) asm volatile("s_waitcnt lgkmcnt(" #n ")" ::: "memory")
; #define PG8_BAR __builtin_amdgcn_s_barrier()
; #define PG8_SCHED __builtin_amdgcn_sched_barrier(0)
; template <class Epi, class Sched, bool ALIGN_EPI = false, bool SP2 = false>
; __device__ __forceinline__ void gemm_phase(PG8_LAS unsigned char* lds, const Gemm g, const Sched& S, const Epi& E) {
;     ...
;             PG8_WAIT_V(8); PG8_WAIT_L(0); PG8_BAR; PG8_MMA(0, 0, At, B0); PG8_MMA(0, 1, At, B1); PG8_BAR; PG8_SCHED;
;             PG8_LDA(At, 1, 1); PG8_STAGE(PG8_SB(1, 0), b3, voffB); PG8_STAGE(PG8_SB(1, 1), b3 + hstep, voffB); PG8_STAGE(PG8_SA(1, 0), a3, voffA);
;             PG8_WAIT_V(8); PG8_WAIT_L(0); PG8_BAR; PG8_MMA(1, 0, At, B0); PG8_MMA(1, 1, At, B1); PG8_BAR; PG8_SCHED;
.Lrsa_d_pl:
	s_waitcnt lgkmcnt(0)
	s_barrier
	s_setprio 1
	s_waitcnt lgkmcnt(0)
	v_mfma_f32_16x16x32_bf16 v[124:127], v[144:147], v[202:205], v[124:127]
	v_mfma_f32_16x16x32_bf16 v[116:119], v[178:181], v[202:205], v[116:119]
	v_mfma_f32_16x16x32_bf16 v[108:111], v[144:147], v[210:213], v[108:111]
	v_mfma_f32_16x16x32_bf16 v[100:103], v[178:181], v[210:213], v[100:103]
	v_mfma_f32_16x16x32_bf16 v[92:95], v[144:147], v[218:221], v[92:95]
	v_mfma_f32_16x16x32_bf16 v[84:87], v[178:181], v[218:221], v[84:87]
	v_mfma_f32_16x16x32_bf16 v[76:79], v[144:147], v[226:229], v[76:79]
	v_mfma_f32_16x16x32_bf16 v[68:71], v[178:181], v[226:229], v[68:71]
	v_mfma_f32_16x16x32_bf16 v[124:127], v[170:173], v[206:209], v[124:127]
	v_mfma_f32_16x16x32_bf16 v[116:119], v[182:185], v[206:209], v[116:119]
	v_mfma_f32_16x16x32_bf16 v[108:111], v[170:173], v[214:217], v[108:111]
	v_mfma_f32_16x16x32_bf16 v[100:103], v[182:185], v[214:217], v[100:103]
	v_mfma_f32_16x16x32_bf16 v[92:95], v[170:173], v[222:225], v[92:95]
	v_mfma_f32_16x16x32_bf16 v[84:87], v[182:185], v[222:225], v[84:87]
	v_mfma_f32_16x16x32_bf16 v[76:79], v[170:173], v[232:235], v[76:79]
	v_mfma_f32_16x16x32_bf16 v[68:71], v[182:185], v[232:235], v[68:71]
	s_setprio 0
	s_setprio 1
	v_mfma_f32_16x16x32_bf16 v[120:123], v[186:189], v[202:205], v[120:123]
	v_mfma_f32_16x16x32_bf16 v[112:115], v[194:197], v[202:205], v[112:115]
	v_mfma_f32_16x16x32_bf16 v[104:107], v[186:189], v[210:213], v[104:107]
	v_mfma_f32_16x16x32_bf16 v[96:99], v[194:197], v[210:213], v[96:99]
	v_mfma_f32_16x16x32_bf16 v[88:91], v[186:189], v[218:221], v[88:91]
	v_mfma_f32_16x16x32_bf16 v[80:83], v[194:197], v[218:221], v[80:83]
	v_mfma_f32_16x16x32_bf16 v[72:75], v[186:189], v[226:229], v[72:75]
	v_mfma_f32_16x16x32_bf16 v[64:67], v[194:197], v[226:229], v[64:67]
	v_mfma_f32_16x16x32_bf16 v[120:123], v[190:193], v[206:209], v[120:123]
	v_mfma_f32_16x16x32_bf16 v[112:115], v[198:201], v[206:209], v[112:115]
	v_mfma_f32_16x16x32_bf16 v[104:107], v[190:193], v[214:217], v[104:107]
	v_mfma_f32_16x16x32_bf16 v[96:99], v[198:201], v[214:217], v[96:99]
	v_mfma_f32_16x16x32_bf16 v[88:91], v[190:193], v[222:225], v[88:91]
	v_mfma_f32_16x16x32_bf16 v[80:83], v[198:201], v[222:225], v[80:83]
	v_mfma_f32_16x16x32_bf16 v[72:75], v[190:193], v[232:235], v[72:75]
	v_mfma_f32_16x16x32_bf16 v[64:67], v[198:201], v[232:235], v[64:67]
	s_setprio 0
	s_barrier
	s_add_i32 s46, s60, s25
	v_lshl_add_u64 v[150:151], v[150:151], 0, s[8:9]
	s_mov_b32 m0, s46
	ds_read_b128 v[202:205], v169 offset:49152
	ds_read_b128 v[206:209], v169 offset:50176
	ds_read_b128 v[210:213], v169 offset:51200
	ds_read_b128 v[214:217], v169 offset:52224
	ds_read_b128 v[218:221], v169 offset:53248
	ds_read_b128 v[222:225], v169 offset:54272
	ds_read_b128 v[226:229], v169 offset:55296
	ds_read_b128 v[232:235], v169 offset:56320
	global_load_lds_dwordx4 v[150:151], off sc0
	s_add_i32 m0, s46, 0x2000
	s_add_u32 s44, s44, 0x40080
	v_lshl_add_u64 v[150:151], v[154:155], 0, s[8:9]
	s_addc_u32 s45, s45, 0
	s_add_i32 s46, s61, s25
	global_load_lds_dwordx4 v[150:151], off sc0
	v_lshl_add_u64 v[150:151], s[44:45], 0, v[130:131]
	s_mov_b32 m0, s46
	s_nop 0
	global_load_lds_dwordx4 v[150:151], off sc0
	v_lshl_add_u64 v[150:151], s[44:45], 0, v[134:135]
	s_add_i32 m0, s46, 0x2000
	s_nop 0
	global_load_lds_dwordx4 v[150:151], off sc0
	v_lshl_add_u64 v[150:151], v[158:159], 0, s[8:9]
	s_mov_b32 m0, s48
	s_nop 0
	global_load_lds_dwordx4 v[150:151], off sc0
	v_lshl_add_u64 v[150:151], v[162:163], 0, s[8:9]
	s_mov_b32 m0, s49
	s_nop 0
	global_load_lds_dwordx4 v[150:151], off sc0
	s_waitcnt vmcnt(8)
	s_waitcnt lgkmcnt(0)
	s_barrier
	s_setprio 1
	s_waitcnt lgkmcnt(0)
	v_mfma_f32_16x16x32_bf16 v[60:63], v[144:147], v[202:205], v[60:63]
	v_mfma_f32_16x16x32_bf16 v[52:55], v[178:181], v[202:205], v[52:55]
	v_mfma_f32_16x16x32_bf16 v[44:47], v[144:147], v[210:213], v[44:47]
	v_mfma_f32_16x16x32_bf16 v[36:39], v[178:181], v[210:213], v[36:39]
	v_mfma_f32_16x16x32_bf16 v[28:31], v[144:147], v[218:221], v[28:31]
	v_mfma_f32_16x16x32_bf16 v[20:23], v[178:181], v[218:221], v[20:23]
	v_mfma_f32_16x16x32_bf16 v[12:15], v[144:147], v[226:229], v[12:15]
	v_mfma_f32_16x16x32_bf16 v[4:7], v[178:181], v[226:229], v[4:7]
	v_mfma_f32_16x16x32_bf16 v[60:63], v[170:173], v[206:209], v[60:63]
	v_mfma_f32_16x16x32_bf16 v[52:55], v[182:185], v[206:209], v[52:55]
	v_mfma_f32_16x16x32_bf16 v[44:47], v[170:173], v[214:217], v[44:47]
	v_mfma_f32_16x16x32_bf16 v[36:39], v[182:185], v[214:217], v[36:39]
	v_mfma_f32_16x16x32_bf16 v[28:31], v[170:173], v[222:225], v[28:31]
	v_mfma_f32_16x16x32_bf16 v[20:23], v[182:185], v[222:225], v[20:23]
	v_mfma_f32_16x16x32_bf16 v[12:15], v[170:173], v[232:235], v[12:15]
	v_mfma_f32_16x16x32_bf16 v[4:7], v[182:185], v[232:235], v[4:7]
	s_setprio 0
	s_setprio 1
	v_mfma_f32_16x16x32_bf16 v[56:59], v[186:189], v[202:205], v[56:59]
	v_mfma_f32_16x16x32_bf16 v[48:51], v[194:197], v[202:205], v[48:51]
	v_mfma_f32_16x16x32_bf16 v[40:43], v[186:189], v[210:213], v[40:43]
	v_mfma_f32_16x16x32_bf16 v[32:35], v[194:197], v[210:213], v[32:35]
	v_mfma_f32_16x16x32_bf16 v[24:27], v[186:189], v[218:221], v[24:27]
	v_mfma_f32_16x16x32_bf16 v[16:19], v[194:197], v[218:221], v[16:19]
	v_mfma_f32_16x16x32_bf16 v[8:11], v[186:189], v[226:229], v[8:11]
	v_mfma_f32_16x16x32_bf16 v[0:3], v[194:197], v[226:229], v[0:3]
	v_mfma_f32_16x16x32_bf16 v[56:59], v[190:193], v[206:209], v[56:59]
	v_mfma_f32_16x16x32_bf16 v[48:51], v[198:201], v[206:209], v[48:51]
	v_mfma_f32_16x16x32_bf16 v[40:43], v[190:193], v[214:217], v[40:43]
	v_mfma_f32_16x16x32_bf16 v[32:35], v[198:201], v[214:217], v[32:35]
	v_mfma_f32_16x16x32_bf16 v[24:27], v[190:193], v[222:225], v[24:27]
	v_mfma_f32_16x16x32_bf16 v[16:19], v[198:201], v[222:225], v[16:19]
	v_mfma_f32_16x16x32_bf16 v[8:11], v[190:193], v[232:235], v[8:11]
	v_mfma_f32_16x16x32_bf16 v[0:3], v[198:201], v[232:235], v[0:3]
	s_setprio 0
	s_barrier
	s_add_i32 s59, s59, 2
	s_add_u32 s42, s42, 0x100
	s_addc_u32 s43, s43, 0
	s_add_u32 s57, s57, 0x100
	s_addc_u32 s58, s58, 0
	s_cmp_gt_u32 s59, 13
; #define PG8_STAGE(bufoff, gbase, voff) do { _Pragma("unroll") for (int _i = 0; _i < 2; ++_i) \
;         __builtin_amdgcn_global_load_lds((const unsigned*)((const char*)(gbase) + (voff)[_i]), (PG8_LAS unsigned*)(lds + (bufoff) + ldsw + _i * 8192), 16, 0, 0); } while (0)
; #define PG8_LDA(dst, b, h) do { _Pragma("unroll") for (int m = 0; m < 4; ++m) _Pragma("unroll") for (int k = 0; k < 2; ++k) dst[m][k] = *(const PG8_LAS bf16x8*)(lds + PG8_SA(b, h) + aoff + m * 2048 + k * 1024); } while (0)
; #define PG8_LDB(dst, b, h) do { _Pragma("unroll") for (int n = 0; n < 2; ++n) _Pragma("unroll") for (int k = 0; k < 2; ++k) dst[n][k] = *(const PG8_LAS bf16x8*)(lds + PG8_SB(b, h) + boff + n * 2048 + k * 1024); } while (0)
; #define PG8_MMA(ai, bj, At, Bt) do { __builtin_amdgcn_s_setprio(1); _Pragma("unroll") for (int m = 0; m < 4; ++m) _Pragma("unroll") for (int n = 0; n < 2; ++n) _Pragma("unroll") for (int k = 0; k < 2; ++k) \
;         acc[ai][bj][m][n] = __builtin_amdgcn_mfma_f32_16x16x32_bf16(Bt[n][k], At[m][k], acc[ai][bj][m][n], 0, 0, 0); __builtin_amdgcn_s_setprio(0); } while (0)
; #define PG8_WAIT_V(n) asm volatile("s_waitcnt vmcnt(" #n ")" ::: "memory")
; #define PG8_WAIT_L(n) asm volatile("s_waitcnt lgkmcnt(" #n ")" ::: "memory")
; #define PG8_BAR __builtin_amdgcn_s_barrier()
; #define PG8_SCHED __builtin_amdgcn_sched_barrier(0)
; template <class Epi, class Sched, bool ALIGN_EPI = false, bool SP2 = false>
; __device__ __forceinline__ void gemm_phase(PG8_LAS unsigned char* lds, const Gemm g, const Sched& S, const Epi& E) {
;     ...
;             PG8_LDB(B0, 0, 0); PG8_LDB(B1, 0, 1); PG8_SCHED; PG8_LDA(At, 0, 0); PG8_STAGE(PG8_SA(1, 1), a1 + hstep, voffA);
;             PG8_WAIT_V(8); PG8_WAIT_L(0); PG8_BAR; PG8_MMA(0, 0, At, B0); PG8_MMA(0, 1, At, B1); PG8_BAR; PG8_SCHED;
;             PG8_LDA(At, 0, 1); PG8_STAGE(PG8_SB(0, 0), b2, voffB); PG8_STAGE(PG8_SB(0, 1), b2 + hstep, voffB); PG8_STAGE(PG8_SA(0, 0), a2, voffA);
;             PG8_WAIT_V(8); PG8_WAIT_L(0); PG8_BAR; PG8_MMA(1, 0, At, B0); PG8_MMA(1, 1, At, B1); PG8_BAR; PG8_SCHED;
.LBB0_482:
	ds_read_b128 v[144:147], v161
	ds_read_b128 v[170:173], v161 offset:1024
	ds_read_b128 v[178:181], v161 offset:2048
	ds_read_b128 v[182:185], v161 offset:3072
	ds_read_b128 v[186:189], v165
	ds_read_b128 v[190:193], v165 offset:1024
	ds_read_b128 v[194:197], v165 offset:2048
	ds_read_b128 v[198:201], v165 offset:3072
	s_add_u32 s44, s42, 0xfffc0080
	s_addc_u32 s45, s43, -1
	s_cmp_eq_u32 s59, 12
	s_cselect_b32 s47, s19, s45
	s_cselect_b32 s46, s55, s44
	s_cselect_b32 s45, s17, s58
	s_cselect_b32 s44, s56, s57
	v_lshl_add_u64 v[150:151], s[42:43], 0, v[138:139]
	s_add_i32 m0, s28, 0xc000
	ds_read_b128 v[202:205], v169
	ds_read_b128 v[206:209], v169 offset:1024
	ds_read_b128 v[210:213], v169 offset:2048
	ds_read_b128 v[214:217], v169 offset:3072
	ds_read_b128 v[218:221], v169 offset:4096
	ds_read_b128 v[222:225], v169 offset:5120
	ds_read_b128 v[226:229], v169 offset:6144
	ds_read_b128 v[232:235], v169 offset:7168
	global_load_lds_dwordx4 v[150:151], off sc0
	v_lshl_add_u64 v[150:151], s[42:43], 0, v[140:141]
	s_add_i32 m0, s28, 0xe000
	s_nop 0
	global_load_lds_dwordx4 v[150:151], off sc0
	s_waitcnt vmcnt(8)
	s_waitcnt lgkmcnt(0)
	s_barrier
	s_setprio 1
	s_waitcnt lgkmcnt(0)
	v_mfma_f32_16x16x32_bf16 v[124:127], v[144:147], v[202:205], v[124:127]
	v_mfma_f32_16x16x32_bf16 v[116:119], v[178:181], v[202:205], v[116:119]
	v_mfma_f32_16x16x32_bf16 v[108:111], v[144:147], v[210:213], v[108:111]
	v_mfma_f32_16x16x32_bf16 v[100:103], v[178:181], v[210:213], v[100:103]
	v_mfma_f32_16x16x32_bf16 v[92:95], v[144:147], v[218:221], v[92:95]
	v_mfma_f32_16x16x32_bf16 v[84:87], v[178:181], v[218:221], v[84:87]
	v_mfma_f32_16x16x32_bf16 v[76:79], v[144:147], v[226:229], v[76:79]
	v_mfma_f32_16x16x32_bf16 v[68:71], v[178:181], v[226:229], v[68:71]
	v_mfma_f32_16x16x32_bf16 v[124:127], v[170:173], v[206:209], v[124:127]
	v_mfma_f32_16x16x32_bf16 v[116:119], v[182:185], v[206:209], v[116:119]
	v_mfma_f32_16x16x32_bf16 v[108:111], v[170:173], v[214:217], v[108:111]
	v_mfma_f32_16x16x32_bf16 v[100:103], v[182:185], v[214:217], v[100:103]
	v_mfma_f32_16x16x32_bf16 v[92:95], v[170:173], v[222:225], v[92:95]
	v_mfma_f32_16x16x32_bf16 v[84:87], v[182:185], v[222:225], v[84:87]
	v_mfma_f32_16x16x32_bf16 v[76:79], v[170:173], v[232:235], v[76:79]
	v_mfma_f32_16x16x32_bf16 v[68:71], v[182:185], v[232:235], v[68:71]
	s_setprio 0
	s_setprio 1
	v_mfma_f32_16x16x32_bf16 v[120:123], v[186:189], v[202:205], v[120:123]
	v_mfma_f32_16x16x32_bf16 v[112:115], v[194:197], v[202:205], v[112:115]
	v_mfma_f32_16x16x32_bf16 v[104:107], v[186:189], v[210:213], v[104:107]
	v_mfma_f32_16x16x32_bf16 v[96:99], v[194:197], v[210:213], v[96:99]
	v_mfma_f32_16x16x32_bf16 v[88:91], v[186:189], v[218:221], v[88:91]
	v_mfma_f32_16x16x32_bf16 v[80:83], v[194:197], v[218:221], v[80:83]
	v_mfma_f32_16x16x32_bf16 v[72:75], v[186:189], v[226:229], v[72:75]
	v_mfma_f32_16x16x32_bf16 v[64:67], v[194:197], v[226:229], v[64:67]
	v_mfma_f32_16x16x32_bf16 v[120:123], v[190:193], v[206:209], v[120:123]
	v_mfma_f32_16x16x32_bf16 v[112:115], v[198:201], v[206:209], v[112:115]
	v_mfma_f32_16x16x32_bf16 v[104:107], v[190:193], v[214:217], v[104:107]
	v_mfma_f32_16x16x32_bf16 v[96:99], v[198:201], v[214:217], v[96:99]
	v_mfma_f32_16x16x32_bf16 v[88:91], v[190:193], v[222:225], v[88:91]
	v_mfma_f32_16x16x32_bf16 v[80:83], v[198:201], v[222:225], v[80:83]
	v_mfma_f32_16x16x32_bf16 v[72:75], v[190:193], v[232:235], v[72:75]
	v_mfma_f32_16x16x32_bf16 v[64:67], v[198:201], v[232:235], v[64:67]
	s_setprio 0
	s_barrier
	s_add_i32 s60, s51, s25
	v_lshl_add_u64 v[150:151], s[44:45], 0, v[130:131]
	s_mov_b32 m0, s60
	ds_read_b128 v[202:205], v169 offset:16384
	ds_read_b128 v[206:209], v169 offset:17408
	ds_read_b128 v[210:213], v169 offset:18432
	ds_read_b128 v[214:217], v169 offset:19456
	ds_read_b128 v[218:221], v169 offset:20480
	ds_read_b128 v[222:225], v169 offset:21504
	ds_read_b128 v[226:229], v169 offset:22528
	ds_read_b128 v[232:235], v169 offset:23552
	global_load_lds_dwordx4 v[150:151], off sc0
	s_add_i32 m0, s60, 0x2000
	s_add_u32 s60, s44, 0x40000
	v_lshl_add_u64 v[154:155], s[44:45], 0, v[134:135]
	s_addc_u32 s61, s45, 0
	s_add_i32 s62, s52, s25
	global_load_lds_dwordx4 v[154:155], off sc0
	v_lshl_add_u64 v[158:159], s[60:61], 0, v[130:131]
	s_mov_b32 m0, s62
	v_lshl_add_u64 v[162:163], s[46:47], 0, v[132:133]
	global_load_lds_dwordx4 v[158:159], off sc0
	v_lshl_add_u64 v[158:159], s[60:61], 0, v[134:135]
	s_add_i32 m0, s62, 0x2000
	s_nop 0
	global_load_lds_dwordx4 v[158:159], off sc0
	v_lshl_add_u64 v[158:159], s[46:47], 0, v[128:129]
	s_mov_b32 m0, s28
	s_nop 0
	global_load_lds_dwordx4 v[158:159], off sc0
	s_mov_b32 m0, s29
	s_nop 0
	global_load_lds_dwordx4 v[162:163], off sc0
	s_cmp_lg_i32 s59, -2
	s_cbranch_scc1 .Lrsa_a
	v_lshrrev_b32_e32 v250, 6, v230
	v_lshlrev_b32_e32 v250, 11, v250
	v_and_b32_e32 v251, 63, v230
	v_lshl_or_b32 v250, v251, 4, v250
	v_lshl_add_u32 v250, s40, 14, v250
	v_readfirstlane_b32 s98, v230
	s_lshr_b32 s98, s98, 6
	s_lshl_b32 s98, s98, 11
	s_add_i32 m0, s98, 0x20000
	s_add_u32 s100, s70, 0x3f000000
	s_addc_u32 s101, s71, 0
	global_load_lds_dwordx4 v250, s[100:101] sc0
	global_load_lds_dwordx4 v250, s[100:101] offset:1024 sc0
	s_waitcnt vmcnt(10)
	s_branch .Lrsa_b

; #define PG8_STAGE(bufoff, gbase, voff) do { _Pragma("unroll") for (int _i = 0; _i < 2; ++_i) \
;         __builtin_amdgcn_global_load_lds((const unsigned*)((const char*)(gbase) + (voff)[_i]), (PG8_LAS unsigned*)(lds + (bufoff) + ldsw + _i * 8192), 16, 0, 0); } while (0)
; #define PG8_LDA(dst, b, h) do { _Pragma("unroll") for (int m = 0; m < 4; ++m) _Pragma("unroll") for (int k = 0; k < 2; ++k) dst[m][k] = *(const PG8_LAS bf16x8*)(lds + PG8_SA(b, h) + aoff + m * 2048 + k * 1024); } while (0)
; #define PG8_LDB(dst, b, h) do { _Pragma("unroll") for (int n = 0; n < 2; ++n) _Pragma("unroll") for (int k = 0; k < 2; ++k) dst[n][k] = *(const PG8_LAS bf16x8*)(lds + PG8_SB(b, h) + boff + n * 2048 + k * 1024); } while (0)
; #define PG8_MMA(ai, bj, At, Bt) do { __builtin_amdgcn_s_setprio(1); _Pragma("unroll") for (int m = 0; m < 4; ++m) _Pragma("unroll") for (int n = 0; n < 2; ++n) _Pragma("unroll") for (int k = 0; k < 2; ++k) \
;         acc[ai][bj][m][n] = __builtin_amdgcn_mfma_f32_16x16x32_bf16(Bt[n][k], At[m][k], acc[ai][bj][m][n], 0, 0, 0); __builtin_amdgcn_s_setprio(0); } while (0)
; #define PG8_WAIT_V(n) asm volatile("s_waitcnt vmcnt(" #n ")" ::: "memory")
; #define PG8_WAIT_L(n) asm volatile("s_waitcnt lgkmcnt(" #n ")" ::: "memory")
; #define PG8_BAR __builtin_amdgcn_s_barrier()
; #define PG8_SCHED __builtin_amdgcn_sched_barrier(0)
; template <class Epi, class Sched, bool ALIGN_EPI = false, bool SP2 = false>
; __device__ __forceinline__ void gemm_phase(PG8_LAS unsigned char* lds, const Gemm g, const Sched& S, const Epi& E) {
;     ...
;             PG8_WAIT_V(8); PG8_WAIT_L(0); PG8_BAR; PG8_MMA(1, 0, At, B0); PG8_MMA(1, 1, At, B1); PG8_BAR; PG8_SCHED;
;             PG8_LDB(B0, 1, 0); PG8_LDB(B1, 1, 1); PG8_SCHED; PG8_LDA(At, 1, 0); PG8_STAGE(PG8_SA(0, 1), a2 + hstep, voffA);
;             PG8_WAIT_V(8); PG8_WAIT_L(0); PG8_BAR; PG8_MMA(0, 0, At, B0); PG8_MMA(0, 1, At, B1); PG8_BAR; PG8_SCHED;
.Lrsa_b:
	s_waitcnt lgkmcnt(0)
	s_barrier
	s_setprio 1
	s_waitcnt lgkmcnt(0)
	v_mfma_f32_16x16x32_bf16 v[60:63], v[144:147], v[202:205], v[60:63]
	v_mfma_f32_16x16x32_bf16 v[52:55], v[178:181], v[202:205], v[52:55]
	v_mfma_f32_16x16x32_bf16 v[44:47], v[144:147], v[210:213], v[44:47]
	v_mfma_f32_16x16x32_bf16 v[36:39], v[178:181], v[210:213], v[36:39]
	v_mfma_f32_16x16x32_bf16 v[28:31], v[144:147], v[218:221], v[28:31]
	v_mfma_f32_16x16x32_bf16 v[20:23], v[178:181], v[218:221], v[20:23]
	v_mfma_f32_16x16x32_bf16 v[12:15], v[144:147], v[226:229], v[12:15]
	v_mfma_f32_16x16x32_bf16 v[4:7], v[178:181], v[226:229], v[4:7]
	v_mfma_f32_16x16x32_bf16 v[60:63], v[170:173], v[206:209], v[60:63]
	v_mfma_f32_16x16x32_bf16 v[52:55], v[182:185], v[206:209], v[52:55]
	v_mfma_f32_16x16x32_bf16 v[44:47], v[170:173], v[214:217], v[44:47]
	v_mfma_f32_16x16x32_bf16 v[36:39], v[182:185], v[214:217], v[36:39]
	v_mfma_f32_16x16x32_bf16 v[28:31], v[170:173], v[222:225], v[28:31]
	v_mfma_f32_16x16x32_bf16 v[20:23], v[182:185], v[222:225], v[20:23]
	v_mfma_f32_16x16x32_bf16 v[12:15], v[170:173], v[232:235], v[12:15]
	v_mfma_f32_16x16x32_bf16 v[4:7], v[182:185], v[232:235], v[4:7]
	s_setprio 0
	s_setprio 1
	v_mfma_f32_16x16x32_bf16 v[56:59], v[186:189], v[202:205], v[56:59]
	v_mfma_f32_16x16x32_bf16 v[48:51], v[194:197], v[202:205], v[48:51]
	v_mfma_f32_16x16x32_bf16 v[40:43], v[186:189], v[210:213], v[40:43]
	v_mfma_f32_16x16x32_bf16 v[32:35], v[194:197], v[210:213], v[32:35]
	v_mfma_f32_16x16x32_bf16 v[24:27], v[186:189], v[218:221], v[24:27]
	v_mfma_f32_16x16x32_bf16 v[16:19], v[194:197], v[218:221], v[16:19]
	v_mfma_f32_16x16x32_bf16 v[8:11], v[186:189], v[226:229], v[8:11]
	v_mfma_f32_16x16x32_bf16 v[0:3], v[194:197], v[226:229], v[0:3]
	v_mfma_f32_16x16x32_bf16 v[56:59], v[190:193], v[206:209], v[56:59]
	v_mfma_f32_16x16x32_bf16 v[48:51], v[198:201], v[206:209], v[48:51]
	v_mfma_f32_16x16x32_bf16 v[40:43], v[190:193], v[214:217], v[40:43]
	v_mfma_f32_16x16x32_bf16 v[32:35], v[198:201], v[214:217], v[32:35]
	v_mfma_f32_16x16x32_bf16 v[24:27], v[190:193], v[222:225], v[24:27]
	v_mfma_f32_16x16x32_bf16 v[16:19], v[198:201], v[222:225], v[16:19]
	v_mfma_f32_16x16x32_bf16 v[8:11], v[190:193], v[232:235], v[8:11]
	v_mfma_f32_16x16x32_bf16 v[0:3], v[198:201], v[232:235], v[0:3]
	s_setprio 0
	s_barrier
	s_add_i32 s60, 0, 0x18000
	v_add_u32_e32 v148, s60, v153
	s_add_i32 s61, 0, 0x1c000
	ds_read_b128 v[144:147], v148
	ds_read_b128 v[170:173], v148 offset:1024
	ds_read_b128 v[178:181], v148 offset:2048
	ds_read_b128 v[182:185], v148 offset:3072
	v_add_u32_e32 v148, s61, v153
	ds_read_b128 v[186:189], v148
	ds_read_b128 v[190:193], v148 offset:1024
	ds_read_b128 v[194:197], v148 offset:2048
	ds_read_b128 v[198:201], v148 offset:3072
	s_add_u32 s46, s46, 0x40000
	s_addc_u32 s47, s47, 0
	s_mov_b32 m0, s30
	v_lshl_add_u64 v[166:167], s[46:47], 0, v[128:129]
	ds_read_b128 v[202:205], v169 offset:32768
	ds_read_b128 v[206:209], v169 offset:33792
	ds_read_b128 v[210:213], v169 offset:34816
	ds_read_b128 v[214:217], v169 offset:35840
	ds_read_b128 v[218:221], v169 offset:36864
	ds_read_b128 v[222:225], v169 offset:37888
	ds_read_b128 v[226:229], v169 offset:38912
	ds_read_b128 v[232:235], v169 offset:39936
	global_load_lds_dwordx4 v[166:167], off sc0
	v_lshl_add_u64 v[166:167], s[46:47], 0, v[132:133]
	s_mov_b32 m0, s31
	s_nop 0
	global_load_lds_dwordx4 v[166:167], off sc0
	s_cmp_lg_i32 s59, -2
	s_cbranch_scc1 .Lrsa_c
	s_waitcnt vmcnt(10)
	s_branch .Lrsa_d

; #define PG8_STAGE(bufoff, gbase, voff) do { _Pragma("unroll") for (int _i = 0; _i < 2; ++_i) \
;         __builtin_amdgcn_global_load_lds((const unsigned*)((const char*)(gbase) + (voff)[_i]), (PG8_LAS unsigned*)(lds + (bufoff) + ldsw + _i * 8192), 16, 0, 0); } while (0)
; #define PG8_LDA(dst, b, h) do { _Pragma("unroll") for (int m = 0; m < 4; ++m) _Pragma("unroll") for (int k = 0; k < 2; ++k) dst[m][k] = *(const PG8_LAS bf16x8*)(lds + PG8_SA(b, h) + aoff + m * 2048 + k * 1024); } while (0)
; #define PG8_MMA(ai, bj, At, Bt) do { __builtin_amdgcn_s_setprio(1); _Pragma("unroll") for (int m = 0; m < 4; ++m) _Pragma("unroll") for (int n = 0; n < 2; ++n) _Pragma("unroll") for (int k = 0; k < 2; ++k) \
;         acc[ai][bj][m][n] = __builtin_amdgcn_mfma_f32_16x16x32_bf16(Bt[n][k], At[m][k], acc[ai][bj][m][n], 0, 0, 0); __builtin_amdgcn_s_setprio(0); } while (0)
; #define PG8_WAIT_V(n) asm volatile("s_waitcnt vmcnt(" #n ")" ::: "memory")
; #define PG8_WAIT_L(n) asm volatile("s_waitcnt lgkmcnt(" #n ")" ::: "memory")
; #define PG8_BAR __builtin_amdgcn_s_barrier()
; #define PG8_SCHED __builtin_amdgcn_sched_barrier(0)
; template <class Epi, class Sched, bool ALIGN_EPI = false, bool SP2 = false>
; __device__ __forceinline__ void gemm_phase(PG8_LAS unsigned char* lds, const Gemm g, const Sched& S, const Epi& E) {
;     ...
;             PG8_WAIT_V(8); PG8_WAIT_L(0); PG8_BAR; PG8_MMA(0, 0, At, B0); PG8_MMA(0, 1, At, B1); PG8_BAR; PG8_SCHED;
;             PG8_LDA(At, 1, 1); PG8_STAGE(PG8_SB(1, 0), b3, voffB); PG8_STAGE(PG8_SB(1, 1), b3 + hstep, voffB); PG8_STAGE(PG8_SA(1, 0), a3, voffA);
;             PG8_WAIT_V(8); PG8_WAIT_L(0); PG8_BAR; PG8_MMA(1, 0, At, B0); PG8_MMA(1, 1, At, B1); PG8_BAR; PG8_SCHED;
.Lrsa_d:
	s_waitcnt lgkmcnt(0)
	s_barrier
	s_setprio 1
	s_waitcnt lgkmcnt(0)
	v_mfma_f32_16x16x32_bf16 v[124:127], v[144:147], v[202:205], v[124:127]
	v_mfma_f32_16x16x32_bf16 v[116:119], v[178:181], v[202:205], v[116:119]
	v_mfma_f32_16x16x32_bf16 v[108:111], v[144:147], v[210:213], v[108:111]
	v_mfma_f32_16x16x32_bf16 v[100:103], v[178:181], v[210:213], v[100:103]
	v_mfma_f32_16x16x32_bf16 v[92:95], v[144:147], v[218:221], v[92:95]
	v_mfma_f32_16x16x32_bf16 v[84:87], v[178:181], v[218:221], v[84:87]
	v_mfma_f32_16x16x32_bf16 v[76:79], v[144:147], v[226:229], v[76:79]
	v_mfma_f32_16x16x32_bf16 v[68:71], v[178:181], v[226:229], v[68:71]
	v_mfma_f32_16x16x32_bf16 v[124:127], v[170:173], v[206:209], v[124:127]
	v_mfma_f32_16x16x32_bf16 v[116:119], v[182:185], v[206:209], v[116:119]
	v_mfma_f32_16x16x32_bf16 v[108:111], v[170:173], v[214:217], v[108:111]
	v_mfma_f32_16x16x32_bf16 v[100:103], v[182:185], v[214:217], v[100:103]
	v_mfma_f32_16x16x32_bf16 v[92:95], v[170:173], v[222:225], v[92:95]
	v_mfma_f32_16x16x32_bf16 v[84:87], v[182:185], v[222:225], v[84:87]
	v_mfma_f32_16x16x32_bf16 v[76:79], v[170:173], v[232:235], v[76:79]
	v_mfma_f32_16x16x32_bf16 v[68:71], v[182:185], v[232:235], v[68:71]
	s_setprio 0
	s_setprio 1
	v_mfma_f32_16x16x32_bf16 v[120:123], v[186:189], v[202:205], v[120:123]
	v_mfma_f32_16x16x32_bf16 v[112:115], v[194:197], v[202:205], v[112:115]
	v_mfma_f32_16x16x32_bf16 v[104:107], v[186:189], v[210:213], v[104:107]
	v_mfma_f32_16x16x32_bf16 v[96:99], v[194:197], v[210:213], v[96:99]
	v_mfma_f32_16x16x32_bf16 v[88:91], v[186:189], v[218:221], v[88:91]
	v_mfma_f32_16x16x32_bf16 v[80:83], v[194:197], v[218:221], v[80:83]
	v_mfma_f32_16x16x32_bf16 v[72:75], v[186:189], v[226:229], v[72:75]
	v_mfma_f32_16x16x32_bf16 v[64:67], v[194:197], v[226:229], v[64:67]
	v_mfma_f32_16x16x32_bf16 v[120:123], v[190:193], v[206:209], v[120:123]
	v_mfma_f32_16x16x32_bf16 v[112:115], v[198:201], v[206:209], v[112:115]
	v_mfma_f32_16x16x32_bf16 v[104:107], v[190:193], v[214:217], v[104:107]
	v_mfma_f32_16x16x32_bf16 v[96:99], v[198:201], v[214:217], v[96:99]
	v_mfma_f32_16x16x32_bf16 v[88:91], v[190:193], v[222:225], v[88:91]
	v_mfma_f32_16x16x32_bf16 v[80:83], v[198:201], v[222:225], v[80:83]
	v_mfma_f32_16x16x32_bf16 v[72:75], v[190:193], v[232:235], v[72:75]
	v_mfma_f32_16x16x32_bf16 v[64:67], v[198:201], v[232:235], v[64:67]
	s_setprio 0
	s_barrier
	s_add_i32 s46, s60, s25
	v_lshl_add_u64 v[150:151], v[150:151], 0, s[8:9]
	s_mov_b32 m0, s46
	ds_read_b128 v[202:205], v169 offset:49152
	ds_read_b128 v[206:209], v169 offset:50176
	ds_read_b128 v[210:213], v169 offset:51200
	ds_read_b128 v[214:217], v169 offset:52224
	ds_read_b128 v[218:221], v169 offset:53248
	ds_read_b128 v[222:225], v169 offset:54272
	ds_read_b128 v[226:229], v169 offset:55296
	ds_read_b128 v[232:235], v169 offset:56320
	global_load_lds_dwordx4 v[150:151], off sc0
	s_add_i32 m0, s46, 0x2000
	s_add_u32 s44, s44, 0x40080
	v_lshl_add_u64 v[150:151], v[154:155], 0, s[8:9]
	s_addc_u32 s45, s45, 0
	s_add_i32 s46, s61, s25
	global_load_lds_dwordx4 v[150:151], off sc0
	v_lshl_add_u64 v[150:151], s[44:45], 0, v[130:131]
	s_mov_b32 m0, s46
	s_nop 0
	global_load_lds_dwordx4 v[150:151], off sc0
	v_lshl_add_u64 v[150:151], s[44:45], 0, v[134:135]
	s_add_i32 m0, s46, 0x2000
	s_nop 0
	global_load_lds_dwordx4 v[150:151], off sc0
	v_lshl_add_u64 v[150:151], v[158:159], 0, s[8:9]
	s_mov_b32 m0, s48
	s_nop 0
	global_load_lds_dwordx4 v[150:151], off sc0
	v_lshl_add_u64 v[150:151], v[162:163], 0, s[8:9]
	s_mov_b32 m0, s49
	s_nop 0
	global_load_lds_dwordx4 v[150:151], off sc0
	s_waitcnt vmcnt(8)
	s_waitcnt lgkmcnt(0)
	s_barrier
	s_setprio 1
	s_waitcnt lgkmcnt(0)
	v_mfma_f32_16x16x32_bf16 v[60:63], v[144:147], v[202:205], v[60:63]
	v_mfma_f32_16x16x32_bf16 v[52:55], v[178:181], v[202:205], v[52:55]
	v_mfma_f32_16x16x32_bf16 v[44:47], v[144:147], v[210:213], v[44:47]
	v_mfma_f32_16x16x32_bf16 v[36:39], v[178:181], v[210:213], v[36:39]
	v_mfma_f32_16x16x32_bf16 v[28:31], v[144:147], v[218:221], v[28:31]
	v_mfma_f32_16x16x32_bf16 v[20:23], v[178:181], v[218:221], v[20:23]
	v_mfma_f32_16x16x32_bf16 v[12:15], v[144:147], v[226:229], v[12:15]
	v_mfma_f32_16x16x32_bf16 v[4:7], v[178:181], v[226:229], v[4:7]
	v_mfma_f32_16x16x32_bf16 v[60:63], v[170:173], v[206:209], v[60:63]
	v_mfma_f32_16x16x32_bf16 v[52:55], v[182:185], v[206:209], v[52:55]
	v_mfma_f32_16x16x32_bf16 v[44:47], v[170:173], v[214:217], v[44:47]
	v_mfma_f32_16x16x32_bf16 v[36:39], v[182:185], v[214:217], v[36:39]
	v_mfma_f32_16x16x32_bf16 v[28:31], v[170:173], v[222:225], v[28:31]
	v_mfma_f32_16x16x32_bf16 v[20:23], v[182:185], v[222:225], v[20:23]
	v_mfma_f32_16x16x32_bf16 v[12:15], v[170:173], v[232:235], v[12:15]
	v_mfma_f32_16x16x32_bf16 v[4:7], v[182:185], v[232:235], v[4:7]
	s_setprio 0
	s_setprio 1
	v_mfma_f32_16x16x32_bf16 v[56:59], v[186:189], v[202:205], v[56:59]
	v_mfma_f32_16x16x32_bf16 v[48:51], v[194:197], v[202:205], v[48:51]
	v_mfma_f32_16x16x32_bf16 v[40:43], v[186:189], v[210:213], v[40:43]
	v_mfma_f32_16x16x32_bf16 v[32:35], v[194:197], v[210:213], v[32:35]
	v_mfma_f32_16x16x32_bf16 v[24:27], v[186:189], v[218:221], v[24:27]
	v_mfma_f32_16x16x32_bf16 v[16:19], v[194:197], v[218:221], v[16:19]
	v_mfma_f32_16x16x32_bf16 v[8:11], v[186:189], v[226:229], v[8:11]
	v_mfma_f32_16x16x32_bf16 v[0:3], v[194:197], v[226:229], v[0:3]
	v_mfma_f32_16x16x32_bf16 v[56:59], v[190:193], v[206:209], v[56:59]
	v_mfma_f32_16x16x32_bf16 v[48:51], v[198:201], v[206:209], v[48:51]
	v_mfma_f32_16x16x32_bf16 v[40:43], v[190:193], v[214:217], v[40:43]
	v_mfma_f32_16x16x32_bf16 v[32:35], v[198:201], v[214:217], v[32:35]
	v_mfma_f32_16x16x32_bf16 v[24:27], v[190:193], v[222:225], v[24:27]
	v_mfma_f32_16x16x32_bf16 v[16:19], v[198:201], v[222:225], v[16:19]
	v_mfma_f32_16x16x32_bf16 v[8:11], v[190:193], v[232:235], v[8:11]
	v_mfma_f32_16x16x32_bf16 v[0:3], v[198:201], v[232:235], v[0:3]
	s_setprio 0
	s_barrier
	s_add_i32 s59, s59, 2
	s_add_u32 s42, s42, 0x100
	s_addc_u32 s43, s43, 0
	s_add_u32 s57, s57, 0x100
	s_addc_u32 s58, s58, 0
	s_cmp_gt_u32 s59, 13
	s_cbranch_scc0 .LBB0_482
	s_and_b64 vcc, exec, s[12:13]
	s_cbranch_vccz .LBB0_485
	s_barrier

; #define PG8_STAGE(bufoff, gbase, voff) do { _Pragma("unroll") for (int _i = 0; _i < 2; ++_i) \
;         __builtin_amdgcn_global_load_lds((const unsigned*)((const char*)(gbase) + (voff)[_i]), (PG8_LAS unsigned*)(lds + (bufoff) + ldsw + _i * 8192), 16, 0, 0); } while (0)
; #define PG8_WAIT_V(n) asm volatile("s_waitcnt vmcnt(" #n ")" ::: "memory")
; #define PG8_BAR __builtin_amdgcn_s_barrier()
; template <class Epi, class Sched, bool ALIGN_EPI = false, bool SP2 = false>
; __device__ __forceinline__ void gemm_phase(PG8_LAS unsigned char* lds, const Gemm g, const Sched& S, const Epi& E) {
;     const int tid = threadIdx.x, wid = __builtin_amdgcn_readfirstlane(tid >> 6), lane = tid & 63, wr = wid >> 2, wc = wid & 3, fr = lane & 15, fq = lane >> 4;
;     const int K = g.K, nt = K / BK;
;     unsigned voffA[2], voffB[2];
; #pragma unroll
;     for (int i = 0; i < 2; ++i) { int R, C; stage_rc(tid * 16 + i * 8192, R, C); const int Rb = Epi::PERM ? ((R & ~31) + perm32(R & 31)) : R;
;         voffA[i] = (unsigned)(R * K + C) * 2u; voffB[i] = (unsigned)(Rb * K + C) * 2u; }
;     const size_t kstep = (size_t)(BK * 2);
;     const size_t hstep = (size_t)HALF * K * 2;
;     const size_t tstep = 2 * hstep;
;     const unsigned ldsw = (unsigned)wid * 1024u;
;     const int aoff = lds_byte(wr * 64 + fr, fq * 8), boff = lds_byte(wc * 32 + fr, fq * 8);
;     ...
;     Unit cur, nxt; int ui = 0;
;     if (!S.next(0, cur)) return;
;     f32x4 acc[2][2][4][2];
; #pragma unroll
;     for (int a = 0; a < 2; ++a)
; #pragma unroll
;         for (int b = 0; b < 2; ++b)
; #pragma unroll
;             for (int m = 0; m < 4; ++m)
; #pragma unroll
;                 for (int n = 0; n < 2; ++n) acc[a][b][m][n] = (f32x4){0.f, 0.f, 0.f, 0.f};
;     bf16x8 At[4][2], B0[2][2], B1[2][2];
;     const char* cA = (const char*)g.A + (size_t)cur.pm * tstep; const char* cB = (const char*)g.Bt + (size_t)cur.pn * tstep;
;     S.a_ready(cur);
;     if constexpr (SP2) {
;         PG8_STAGE(PG8_SB(0, 0), cB, voffB); PG8_STAGE(PG8_SB(0, 1), cB + hstep, voffB); PG8_STAGE(PG8_SA(0, 0), cA, voffA); PG8_STAGE(PG8_SA(0, 1), cA + hstep, voffA);
;         if (wr == 1) PG8_BAR;
;         PG8_WAIT_V(2); PG8_BAR;
;         PG8_STAGE(PG8_SB(1, 0), cB + kstep, voffB); PG8_STAGE(PG8_SA(1, 0), cA + kstep, voffA); PG8_STAGE(PG8_SB(1, 1), cB + hstep + kstep, voffB);
;         PG8_WAIT_V(6); PG8_BAR;
.LBB0_553:
	v_lshrrev_b32_e32 v3, 1, v230
	v_lshrrev_b32_e32 v4, 5, v230
	v_and_b32_e32 v3, 24, v3
	v_and_b32_e32 v4, 4, v4
	v_bfe_u32 v5, v230, 2, 2
	v_lshlrev_b32_e32 v0, 4, v230
	s_waitcnt lgkmcnt(0)
	v_and_b32_e32 v1, 32, v230
	v_bfe_u32 v2, v230, 2, 4
	v_or3_b32 v3, v4, v5, v3
	v_lshrrev_b32_e32 v4, 3, v230
	s_movk_i32 s0, 0x70
	v_bitop3_b32 v8, v0, v1, 48 bitop3:0x6c
	v_and_or_b32 v5, v4, s0, v2
	s_movk_i32 s0, 0x60
	v_add_u32_e32 v0, 0x2000, v0
	s_add_u32 s23, s70, 0x3dc80000
	v_and_or_b32 v4, v4, s0, v3
	v_lshrrev_b32_e32 v0, 7, v0
	s_movk_i32 s0, 0xf0
	s_addc_u32 s24, s71, 0
	s_lshr_b32 s1, s4, 6
	v_and_b32_e32 v9, 64, v230
	v_and_or_b32 v2, v0, s0, v2
	s_movk_i32 s0, 0xe0
	v_or_b32_e32 v1, v8, v9
	v_and_or_b32 v0, v0, s0, v3
	s_lshr_b32 s0, s4, 8
	s_lshl_b32 s25, s1, 10
	s_mul_i32 s19, s16, 0x160000
	v_lshrrev_b32_e32 v1, 1, v1
	v_mul_u32_u24_e32 v4, 0xb00, v4
	s_mul_hi_i32 s18, s16, 0x160000
	s_add_u32 s44, s23, s19
	v_or_b32_e32 v4, v4, v1
	s_addc_u32 s45, s24, s18
	s_add_i32 s26, s25, 0
	v_lshlrev_b32_e32 v186, 1, v4
	v_mul_u32_u24_e32 v0, 0xb00, v0
	s_add_i32 m0, s26, 0x10000
	v_or_b32_e32 v0, v0, v1
	global_load_lds_dwordx4 v186, s[44:45] sc0
	s_add_i32 m0, s26, 0x12000
	v_lshlrev_b32_e32 v190, 1, v0
	s_add_u32 s18, s44, 0xb0000
	global_load_lds_dwordx4 v190, s[44:45] sc0
	s_addc_u32 s19, s45, 0
	s_add_i32 m0, s26, 0x14000
	s_mul_i32 s17, s55, 0x160000
	global_load_lds_dwordx4 v186, s[18:19] sc0
	s_add_i32 m0, s26, 0x16000
	v_mul_u32_u24_e32 v10, 0xb00, v5
	s_mul_hi_i32 s5, s55, 0x160000
	s_add_u32 s42, s6, s17
	v_or_b32_e32 v5, v1, v10
	v_mul_u32_u24_e32 v11, 0xb00, v2
	s_addc_u32 s43, s7, s5
	s_add_i32 s27, s26, 0x2000
	v_lshlrev_b32_e32 v184, 1, v5
	v_or_b32_e32 v2, v11, v1
	global_load_lds_dwordx4 v190, s[18:19] sc0
	s_mov_b32 m0, s26
	s_add_u32 s18, s42, 0xb0000
	v_lshlrev_b32_e32 v188, 1, v2
	global_load_lds_dwordx4 v184, s[42:43] sc0
	s_mov_b32 m0, s27
	s_addc_u32 s19, s43, 0
	s_add_i32 s28, s26, 0x4000
	global_load_lds_dwordx4 v188, s[42:43] sc0
	s_mov_b32 m0, s28
	s_add_i32 s29, s26, 0x6000
	global_load_lds_dwordx4 v184, s[18:19] sc0
	s_mov_b32 m0, s29
	v_mov_b32_e32 v187, 0
	global_load_lds_dwordx4 v188, s[18:19] sc0
	v_mov_b32_e32 v191, v187
	v_mov_b32_e32 v185, v187
	v_mov_b32_e32 v189, v187
	s_cmp_eq_u32 s0, 1
	s_mov_b32 s17, 0
	v_lshl_add_u64 v[6:7], s[44:45], 0, v[186:187]
	v_lshl_add_u64 v[4:5], s[44:45], 0, v[190:191]
	v_lshl_add_u64 v[0:1], s[42:43], 0, v[184:185]
	s_cselect_b64 s[18:19], -1, 0
	s_cmp_lg_u32 s0, 1
	v_lshl_add_u64 v[2:3], s[42:43], 0, v[188:189]
	s_cbranch_scc1 .LBB0_555
	s_barrier
.LBB0_555:
	s_mov_b64 s[20:21], 0x80
	s_and_b32 s30, s1, 3
	s_add_i32 m0, s26, 0x18000
	v_lshl_add_u64 v[6:7], v[6:7], 0, s[20:21]
	s_lshl_b32 s1, s0, 13
	s_lshl_b32 s5, s30, 12
	s_waitcnt vmcnt(2)
	s_barrier
	global_load_lds_dwordx4 v[6:7], off sc0
	v_lshl_add_u64 v[4:5], v[4:5], 0, s[20:21]
	s_add_i32 m0, s26, 0x1a000
	s_add_i32 s31, s26, 0x8000
	s_add_i32 s33, s26, 0xa000
	global_load_lds_dwordx4 v[4:5], off sc0
	v_lshl_add_u64 v[0:1], v[0:1], 0, s[20:21]
	s_mov_b32 m0, s31
	s_add_u32 s36, s44, 0xb0080
	global_load_lds_dwordx4 v[0:1], off sc0
	v_lshl_add_u64 v[0:1], v[2:3], 0, s[20:21]
	s_mov_b32 m0, s33
	s_addc_u32 s37, s45, 0
	global_load_lds_dwordx4 v[0:1], off sc0
	s_add_i32 m0, s26, 0x1c000
	v_lshl_add_u64 v[0:1], s[36:37], 0, v[186:187]
	global_load_lds_dwordx4 v[0:1], off sc0
	v_lshl_add_u64 v[0:1], s[36:37], 0, v[190:191]
	s_add_i32 m0, s26, 0x1e000
	v_lshlrev_b32_e32 v4, 2, v230
	global_load_lds_dwordx4 v[0:1], off sc0
	v_bfe_u32 v0, v230, 4, 2
	v_and_b32_e32 v1, 15, v230
	v_lshlrev_b32_e32 v3, 4, v0
	v_lshl_or_b32 v231, s0, 6, v1
	v_lshl_or_b32 v1, v1, 6, v3
	v_and_b32_e32 v4, 32, v4
	v_lshlrev_b32_e32 v5, 6, v230
	s_movk_i32 s0, 0x3c0
	v_lshlrev_b32_e32 v2, 3, v0
	v_bitop3_b32 v1, v1, s1, v4 bitop3:0xde
	v_and_or_b32 v3, v5, s0, v3
	v_cmp_eq_u32_e64 s[0:1], 0, v0
	v_add_u16_e32 v0, v8, v9
	s_waitcnt vmcnt(6)
	s_cmpk_lt_u32 s4, 0x100
	v_lshrrev_b16_e32 v0, 1, v0
	v_bitop3_b32 v232, s5, v3, v4 bitop3:0xf6
	s_cselect_b64 s[36:37], -1, 0
	v_add_lshl_u32 v192, v10, v0, 1
	v_add_lshl_u32 v194, v11, v0, 1
	s_add_i32 s50, 0, 0x10000
	s_add_i32 s51, 0, 0x14000
	v_mbcnt_lo_u32_b32 v0, -1, 0
	v_lshl_or_b32 v233, s30, 5, v2
	s_add_i32 s48, s22, -2
	s_ashr_i32 s49, s2, 31
	v_mov_b32_e32 v193, v187
	v_mov_b32_e32 v195, v187
	v_add_u32_e32 v234, s50, v232
	v_add_u32_e32 v235, s51, v232
	v_add_u32_e32 v236, 0, v1
	v_mbcnt_hi_u32_b32 v237, -1, v0
	v_mov_b64_e32 v[196:197], 0x7ff
	s_mov_b32 s4, 0
	s_barrier
	s_branch .LBB0_558

; #define PG8_STAGE(bufoff, gbase, voff) do { _Pragma("unroll") for (int _i = 0; _i < 2; ++_i) \
;         __builtin_amdgcn_global_load_lds((const unsigned*)((const char*)(gbase) + (voff)[_i]), (PG8_LAS unsigned*)(lds + (bufoff) + ldsw + _i * 8192), 16, 0, 0); } while (0)
; #define PG8_LDA(dst, b, h) do { _Pragma("unroll") for (int m = 0; m < 4; ++m) _Pragma("unroll") for (int k = 0; k < 2; ++k) dst[m][k] = *(const PG8_LAS bf16x8*)(lds + PG8_SA(b, h) + aoff + m * 2048 + k * 1024); } while (0)
; #define PG8_LDB(dst, b, h) do { _Pragma("unroll") for (int n = 0; n < 2; ++n) _Pragma("unroll") for (int k = 0; k < 2; ++k) dst[n][k] = *(const PG8_LAS bf16x8*)(lds + PG8_SB(b, h) + boff + n * 2048 + k * 1024); } while (0)
; #define PG8_MMA(ai, bj, At, Bt) do { __builtin_amdgcn_s_setprio(1); _Pragma("unroll") for (int m = 0; m < 4; ++m) _Pragma("unroll") for (int n = 0; n < 2; ++n) _Pragma("unroll") for (int k = 0; k < 2; ++k) \
;         acc[ai][bj][m][n] = __builtin_amdgcn_mfma_f32_16x16x32_bf16(Bt[n][k], At[m][k], acc[ai][bj][m][n], 0, 0, 0); __builtin_amdgcn_s_setprio(0); } while (0)
; #define PG8_WAIT_V(n) asm volatile("s_waitcnt vmcnt(" #n ")" ::: "memory")
; #define PG8_WAIT_L(n) asm volatile("s_waitcnt lgkmcnt(" #n ")" ::: "memory")
; #define PG8_BAR __builtin_amdgcn_s_barrier()
; #define PG8_SCHED __builtin_amdgcn_sched_barrier(0)
; template <class Epi, class Sched, bool ALIGN_EPI = false, bool SP2 = false>
; __device__ __forceinline__ void gemm_phase(PG8_LAS unsigned char* lds, const Gemm g, const Sched& S, const Epi& E) {
;     ...
;             PG8_LDB(B0, 0, 0); PG8_LDB(B1, 0, 1); PG8_SCHED; PG8_LDA(At, 0, 0); PG8_STAGE(PG8_SA(1, 1), a1 + hstep, voffA);
;             PG8_WAIT_V(8); PG8_WAIT_L(0); PG8_BAR; PG8_MMA(0, 0, At, B0); PG8_MMA(0, 1, At, B1); PG8_BAR; PG8_SCHED;
;             PG8_LDA(At, 0, 1); PG8_STAGE(PG8_SB(0, 0), b2, voffB); PG8_STAGE(PG8_SB(0, 1), b2 + hstep, voffB); PG8_STAGE(PG8_SA(0, 0), a2, voffA);
;             PG8_WAIT_V(8); PG8_WAIT_L(0); PG8_BAR; PG8_MMA(1, 0, At, B0); PG8_MMA(1, 1, At, B1); PG8_BAR; PG8_SCHED;
.LBB0_569:
	s_add_u32 s42, s42, 0xb0080
	s_addc_u32 s43, s43, 0
	s_add_u32 s56, s44, 0x100
	s_addc_u32 s57, s45, 0
	s_mov_b32 s58, -2
	s_waitcnt lgkmcnt(0)
	ds_read_b128 v[124:127], v234
	ds_read_b128 v[132:135], v234 offset:1024
	ds_read_b128 v[136:139], v234 offset:2048
	ds_read_b128 v[140:143], v234 offset:3072
	ds_read_b128 v[144:147], v235
	ds_read_b128 v[148:151], v235 offset:1024
	ds_read_b128 v[152:155], v235 offset:2048
	ds_read_b128 v[156:159], v235 offset:3072
	s_add_u32 s44, s42, 0xfff50080
	s_addc_u32 s45, s43, -1
	s_cmp_eq_u32 s58, 40
	s_cselect_b32 s47, s39, s45
	s_cselect_b32 s46, s38, s44
	s_cselect_b32 s45, s41, s57
	s_cselect_b32 s44, s40, s56
	v_lshl_add_u64 v[206:207], s[42:43], 0, v[192:193]
	s_add_i32 m0, s26, 0xc000
	ds_read_b128 v[160:163], v236
	ds_read_b128 v[164:167], v236 offset:1024
	ds_read_b128 v[168:171], v236 offset:2048
	ds_read_b128 v[172:175], v236 offset:3072
	ds_read_b128 v[176:179], v236 offset:4096
	ds_read_b128 v[180:183], v236 offset:5120
	ds_read_b128 v[198:201], v236 offset:6144
	ds_read_b128 v[202:205], v236 offset:7168
	global_load_lds_dwordx4 v[206:207], off sc0
	v_lshl_add_u64 v[206:207], s[42:43], 0, v[194:195]
	s_add_i32 m0, s26, 0xe000
	s_nop 0
	global_load_lds_dwordx4 v[206:207], off sc0
	s_waitcnt vmcnt(8)
	s_waitcnt lgkmcnt(0)
	s_barrier
	s_setprio 1
	s_waitcnt lgkmcnt(0)
	v_mfma_f32_16x16x32_bf16 v[128:131], v[124:127], v[160:163], 0
	v_mfma_f32_16x16x32_bf16 v[120:123], v[136:139], v[160:163], 0
	v_mfma_f32_16x16x32_bf16 v[108:111], v[124:127], v[168:171], 0
	v_mfma_f32_16x16x32_bf16 v[104:107], v[136:139], v[168:171], 0
	v_mfma_f32_16x16x32_bf16 v[92:95], v[124:127], v[176:179], 0
	v_mfma_f32_16x16x32_bf16 v[88:91], v[136:139], v[176:179], 0
	v_mfma_f32_16x16x32_bf16 v[76:79], v[124:127], v[198:201], 0
	v_mfma_f32_16x16x32_bf16 v[72:75], v[136:139], v[198:201], 0
	v_mfma_f32_16x16x32_bf16 v[128:131], v[132:135], v[164:167], v[128:131]
	v_mfma_f32_16x16x32_bf16 v[120:123], v[140:143], v[164:167], v[120:123]
	v_mfma_f32_16x16x32_bf16 v[108:111], v[132:135], v[172:175], v[108:111]
	v_mfma_f32_16x16x32_bf16 v[104:107], v[140:143], v[172:175], v[104:107]
	v_mfma_f32_16x16x32_bf16 v[92:95], v[132:135], v[180:183], v[92:95]
	v_mfma_f32_16x16x32_bf16 v[88:91], v[140:143], v[180:183], v[88:91]
	v_mfma_f32_16x16x32_bf16 v[76:79], v[132:135], v[202:205], v[76:79]
	v_mfma_f32_16x16x32_bf16 v[72:75], v[140:143], v[202:205], v[72:75]
	s_setprio 0
	s_setprio 1
	v_mfma_f32_16x16x32_bf16 v[116:119], v[144:147], v[160:163], 0
	v_mfma_f32_16x16x32_bf16 v[112:115], v[152:155], v[160:163], 0
	v_mfma_f32_16x16x32_bf16 v[100:103], v[144:147], v[168:171], 0
	v_mfma_f32_16x16x32_bf16 v[96:99], v[152:155], v[168:171], 0
	v_mfma_f32_16x16x32_bf16 v[84:87], v[144:147], v[176:179], 0
	v_mfma_f32_16x16x32_bf16 v[80:83], v[152:155], v[176:179], 0
	v_mfma_f32_16x16x32_bf16 v[68:71], v[144:147], v[198:201], 0
	v_mfma_f32_16x16x32_bf16 v[64:67], v[152:155], v[198:201], 0
	v_mfma_f32_16x16x32_bf16 v[116:119], v[148:151], v[164:167], v[116:119]
	v_mfma_f32_16x16x32_bf16 v[112:115], v[156:159], v[164:167], v[112:115]
	v_mfma_f32_16x16x32_bf16 v[100:103], v[148:151], v[172:175], v[100:103]
	v_mfma_f32_16x16x32_bf16 v[96:99], v[156:159], v[172:175], v[96:99]
	v_mfma_f32_16x16x32_bf16 v[84:87], v[148:151], v[180:183], v[84:87]
	v_mfma_f32_16x16x32_bf16 v[80:83], v[156:159], v[180:183], v[80:83]
	v_mfma_f32_16x16x32_bf16 v[68:71], v[148:151], v[202:205], v[68:71]
	v_mfma_f32_16x16x32_bf16 v[64:67], v[156:159], v[202:205], v[64:67]
	s_setprio 0
	s_barrier
	s_add_i32 s59, s50, s25
	v_lshl_add_u64 v[206:207], s[44:45], 0, v[186:187]
	s_mov_b32 m0, s59
	ds_read_b128 v[160:163], v236 offset:16384
	ds_read_b128 v[164:167], v236 offset:17408
	ds_read_b128 v[168:171], v236 offset:18432
	ds_read_b128 v[172:175], v236 offset:19456
	ds_read_b128 v[176:179], v236 offset:20480
	ds_read_b128 v[180:183], v236 offset:21504
	ds_read_b128 v[198:201], v236 offset:22528
	ds_read_b128 v[202:205], v236 offset:23552
	global_load_lds_dwordx4 v[206:207], off sc0
	s_add_i32 m0, s59, 0x2000
	s_add_u32 s60, s44, 0xb0000
	v_lshl_add_u64 v[208:209], s[44:45], 0, v[190:191]
	s_addc_u32 s61, s45, 0
	s_add_i32 s59, s51, s25
	global_load_lds_dwordx4 v[208:209], off sc0
	v_lshl_add_u64 v[210:211], s[60:61], 0, v[186:187]
	s_mov_b32 m0, s59
	v_lshl_add_u64 v[212:213], s[46:47], 0, v[188:189]
	global_load_lds_dwordx4 v[210:211], off sc0
	v_lshl_add_u64 v[210:211], s[60:61], 0, v[190:191]
	s_add_i32 m0, s59, 0x2000
	s_nop 0
	global_load_lds_dwordx4 v[210:211], off sc0
	v_lshl_add_u64 v[210:211], s[46:47], 0, v[184:185]
	s_mov_b32 m0, s26
	s_nop 0
	global_load_lds_dwordx4 v[210:211], off sc0
	s_mov_b32 m0, s27
	s_nop 0
	global_load_lds_dwordx4 v[212:213], off sc0
	s_waitcnt vmcnt(8)
	s_waitcnt lgkmcnt(0)
	s_barrier
; #define PG8_STAGE(bufoff, gbase, voff) do { _Pragma("unroll") for (int _i = 0; _i < 2; ++_i) \
;         __builtin_amdgcn_global_load_lds((const unsigned*)((const char*)(gbase) + (voff)[_i]), (PG8_LAS unsigned*)(lds + (bufoff) + ldsw + _i * 8192), 16, 0, 0); } while (0)
; #define PG8_LDA(dst, b, h) do { _Pragma("unroll") for (int m = 0; m < 4; ++m) _Pragma("unroll") for (int k = 0; k < 2; ++k) dst[m][k] = *(const PG8_LAS bf16x8*)(lds + PG8_SA(b, h) + aoff + m * 2048 + k * 1024); } while (0)
; #define PG8_LDB(dst, b, h) do { _Pragma("unroll") for (int n = 0; n < 2; ++n) _Pragma("unroll") for (int k = 0; k < 2; ++k) dst[n][k] = *(const PG8_LAS bf16x8*)(lds + PG8_SB(b, h) + boff + n * 2048 + k * 1024); } while (0)
; #define PG8_MMA(ai, bj, At, Bt) do { __builtin_amdgcn_s_setprio(1); _Pragma("unroll") for (int m = 0; m < 4; ++m) _Pragma("unroll") for (int n = 0; n < 2; ++n) _Pragma("unroll") for (int k = 0; k < 2; ++k) \
;         acc[ai][bj][m][n] = __builtin_amdgcn_mfma_f32_16x16x32_bf16(Bt[n][k], At[m][k], acc[ai][bj][m][n], 0, 0, 0); __builtin_amdgcn_s_setprio(0); } while (0)
; #define PG8_WAIT_V(n) asm volatile("s_waitcnt vmcnt(" #n ")" ::: "memory")
; #define PG8_WAIT_L(n) asm volatile("s_waitcnt lgkmcnt(" #n ")" ::: "memory")
; #define PG8_BAR __builtin_amdgcn_s_barrier()
; #define PG8_SCHED __builtin_amdgcn_sched_barrier(0)
; template <class Epi, class Sched, bool ALIGN_EPI = false, bool SP2 = false>
; __device__ __forceinline__ void gemm_phase(PG8_LAS unsigned char* lds, const Gemm g, const Sched& S, const Epi& E) {
;     ...
;             PG8_WAIT_V(8); PG8_WAIT_L(0); PG8_BAR; PG8_MMA(1, 0, At, B0); PG8_MMA(1, 1, At, B1); PG8_BAR; PG8_SCHED;
;             PG8_LDB(B0, 1, 0); PG8_LDB(B1, 1, 1); PG8_SCHED; PG8_LDA(At, 1, 0); PG8_STAGE(PG8_SA(0, 1), a2 + hstep, voffA);
;             PG8_WAIT_V(8); PG8_WAIT_L(0); PG8_BAR; PG8_MMA(0, 0, At, B0); PG8_MMA(0, 1, At, B1); PG8_BAR; PG8_SCHED;
;             PG8_LDA(At, 1, 1); PG8_STAGE(PG8_SB(1, 0), b3, voffB); PG8_STAGE(PG8_SB(1, 1), b3 + hstep, voffB); PG8_STAGE(PG8_SA(1, 0), a3, voffA);
	s_setprio 1
	s_waitcnt lgkmcnt(0)
	v_mfma_f32_16x16x32_bf16 v[60:63], v[124:127], v[160:163], 0
	v_mfma_f32_16x16x32_bf16 v[56:59], v[136:139], v[160:163], 0
	v_mfma_f32_16x16x32_bf16 v[44:47], v[124:127], v[168:171], 0
	v_mfma_f32_16x16x32_bf16 v[40:43], v[136:139], v[168:171], 0
	v_mfma_f32_16x16x32_bf16 v[28:31], v[124:127], v[176:179], 0
	v_mfma_f32_16x16x32_bf16 v[24:27], v[136:139], v[176:179], 0
	v_mfma_f32_16x16x32_bf16 v[12:15], v[124:127], v[198:201], 0
	v_mfma_f32_16x16x32_bf16 v[8:11], v[136:139], v[198:201], 0
	v_mfma_f32_16x16x32_bf16 v[60:63], v[132:135], v[164:167], v[60:63]
	v_mfma_f32_16x16x32_bf16 v[56:59], v[140:143], v[164:167], v[56:59]
	v_mfma_f32_16x16x32_bf16 v[44:47], v[132:135], v[172:175], v[44:47]
	v_mfma_f32_16x16x32_bf16 v[40:43], v[140:143], v[172:175], v[40:43]
	v_mfma_f32_16x16x32_bf16 v[28:31], v[132:135], v[180:183], v[28:31]
	v_mfma_f32_16x16x32_bf16 v[24:27], v[140:143], v[180:183], v[24:27]
	v_mfma_f32_16x16x32_bf16 v[12:15], v[132:135], v[202:205], v[12:15]
	v_mfma_f32_16x16x32_bf16 v[8:11], v[140:143], v[202:205], v[8:11]
	s_setprio 0
	s_setprio 1
	v_mfma_f32_16x16x32_bf16 v[52:55], v[144:147], v[160:163], 0
	v_mfma_f32_16x16x32_bf16 v[48:51], v[152:155], v[160:163], 0
	v_mfma_f32_16x16x32_bf16 v[36:39], v[144:147], v[168:171], 0
	v_mfma_f32_16x16x32_bf16 v[32:35], v[152:155], v[168:171], 0
	v_mfma_f32_16x16x32_bf16 v[20:23], v[144:147], v[176:179], 0
	v_mfma_f32_16x16x32_bf16 v[16:19], v[152:155], v[176:179], 0
	v_mfma_f32_16x16x32_bf16 v[4:7], v[144:147], v[198:201], 0
	v_mfma_f32_16x16x32_bf16 v[0:3], v[152:155], v[198:201], 0
	v_mfma_f32_16x16x32_bf16 v[52:55], v[148:151], v[164:167], v[52:55]
	v_mfma_f32_16x16x32_bf16 v[48:51], v[156:159], v[164:167], v[48:51]
	v_mfma_f32_16x16x32_bf16 v[36:39], v[148:151], v[172:175], v[36:39]
	v_mfma_f32_16x16x32_bf16 v[32:35], v[156:159], v[172:175], v[32:35]
	v_mfma_f32_16x16x32_bf16 v[20:23], v[148:151], v[180:183], v[20:23]
	v_mfma_f32_16x16x32_bf16 v[16:19], v[156:159], v[180:183], v[16:19]
	v_mfma_f32_16x16x32_bf16 v[4:7], v[148:151], v[202:205], v[4:7]
	v_mfma_f32_16x16x32_bf16 v[0:3], v[156:159], v[202:205], v[0:3]
	s_setprio 0
	s_barrier
	s_add_i32 s59, 0, 0x18000
	s_add_i32 s60, 0, 0x1c000
	v_add_u32_e32 v140, s59, v232
	v_add_u32_e32 v156, s60, v232
	ds_read_b128 v[124:127], v140
	ds_read_b128 v[132:135], v140 offset:1024
	ds_read_b128 v[136:139], v140 offset:2048
	ds_read_b128 v[140:143], v140 offset:3072
	ds_read_b128 v[144:147], v156
	ds_read_b128 v[148:151], v156 offset:1024
	ds_read_b128 v[152:155], v156 offset:2048
	ds_read_b128 v[156:159], v156 offset:3072
	s_add_u32 s46, s46, 0xb0000
	s_addc_u32 s47, s47, 0
	s_mov_b32 m0, s28
	v_lshl_add_u64 v[214:215], s[46:47], 0, v[184:185]
	ds_read_b128 v[160:163], v236 offset:32768
	ds_read_b128 v[164:167], v236 offset:33792
	ds_read_b128 v[168:171], v236 offset:34816
	ds_read_b128 v[172:175], v236 offset:35840
	ds_read_b128 v[176:179], v236 offset:36864
	ds_read_b128 v[180:183], v236 offset:37888
	ds_read_b128 v[198:201], v236 offset:38912
	ds_read_b128 v[202:205], v236 offset:39936
	global_load_lds_dwordx4 v[214:215], off sc0
	v_lshl_add_u64 v[214:215], s[46:47], 0, v[188:189]
	s_mov_b32 m0, s29
	s_nop 0
	global_load_lds_dwordx4 v[214:215], off sc0
	s_waitcnt vmcnt(8)
	s_waitcnt lgkmcnt(0)
	s_barrier
	s_setprio 1
	s_waitcnt lgkmcnt(0)
	v_mfma_f32_16x16x32_bf16 v[128:131], v[124:127], v[160:163], v[128:131]
	v_mfma_f32_16x16x32_bf16 v[120:123], v[136:139], v[160:163], v[120:123]
	v_mfma_f32_16x16x32_bf16 v[108:111], v[124:127], v[168:171], v[108:111]
	v_mfma_f32_16x16x32_bf16 v[104:107], v[136:139], v[168:171], v[104:107]
	v_mfma_f32_16x16x32_bf16 v[92:95], v[124:127], v[176:179], v[92:95]
	v_mfma_f32_16x16x32_bf16 v[88:91], v[136:139], v[176:179], v[88:91]
	v_mfma_f32_16x16x32_bf16 v[76:79], v[124:127], v[198:201], v[76:79]
	v_mfma_f32_16x16x32_bf16 v[72:75], v[136:139], v[198:201], v[72:75]
	v_mfma_f32_16x16x32_bf16 v[128:131], v[132:135], v[164:167], v[128:131]
	v_mfma_f32_16x16x32_bf16 v[120:123], v[140:143], v[164:167], v[120:123]
	v_mfma_f32_16x16x32_bf16 v[108:111], v[132:135], v[172:175], v[108:111]
	v_mfma_f32_16x16x32_bf16 v[104:107], v[140:143], v[172:175], v[104:107]
	v_mfma_f32_16x16x32_bf16 v[92:95], v[132:135], v[180:183], v[92:95]
	v_mfma_f32_16x16x32_bf16 v[88:91], v[140:143], v[180:183], v[88:91]
	v_mfma_f32_16x16x32_bf16 v[76:79], v[132:135], v[202:205], v[76:79]
	v_mfma_f32_16x16x32_bf16 v[72:75], v[140:143], v[202:205], v[72:75]
	s_setprio 0
	s_setprio 1
	v_mfma_f32_16x16x32_bf16 v[116:119], v[144:147], v[160:163], v[116:119]
	v_mfma_f32_16x16x32_bf16 v[112:115], v[152:155], v[160:163], v[112:115]
	v_mfma_f32_16x16x32_bf16 v[100:103], v[144:147], v[168:171], v[100:103]
	v_mfma_f32_16x16x32_bf16 v[96:99], v[152:155], v[168:171], v[96:99]
	v_mfma_f32_16x16x32_bf16 v[84:87], v[144:147], v[176:179], v[84:87]
	v_mfma_f32_16x16x32_bf16 v[80:83], v[152:155], v[176:179], v[80:83]
	v_mfma_f32_16x16x32_bf16 v[68:71], v[144:147], v[198:201], v[68:71]
	v_mfma_f32_16x16x32_bf16 v[64:67], v[152:155], v[198:201], v[64:67]
	v_mfma_f32_16x16x32_bf16 v[116:119], v[148:151], v[164:167], v[116:119]
	v_mfma_f32_16x16x32_bf16 v[112:115], v[156:159], v[164:167], v[112:115]
	v_mfma_f32_16x16x32_bf16 v[100:103], v[148:151], v[172:175], v[100:103]
	v_mfma_f32_16x16x32_bf16 v[96:99], v[156:159], v[172:175], v[96:99]
	v_mfma_f32_16x16x32_bf16 v[84:87], v[148:151], v[180:183], v[84:87]
	v_mfma_f32_16x16x32_bf16 v[80:83], v[156:159], v[180:183], v[80:83]
	v_mfma_f32_16x16x32_bf16 v[68:71], v[148:151], v[202:205], v[68:71]
	v_mfma_f32_16x16x32_bf16 v[64:67], v[156:159], v[202:205], v[64:67]
	s_setprio 0
	s_barrier
; #define PG8_STAGE(bufoff, gbase, voff) do { _Pragma("unroll") for (int _i = 0; _i < 2; ++_i) \
;         __builtin_amdgcn_global_load_lds((const unsigned*)((const char*)(gbase) + (voff)[_i]), (PG8_LAS unsigned*)(lds + (bufoff) + ldsw + _i * 8192), 16, 0, 0); } while (0)
; #define PG8_LDA(dst, b, h) do { _Pragma("unroll") for (int m = 0; m < 4; ++m) _Pragma("unroll") for (int k = 0; k < 2; ++k) dst[m][k] = *(const PG8_LAS bf16x8*)(lds + PG8_SA(b, h) + aoff + m * 2048 + k * 1024); } while (0)
; #define PG8_LDB(dst, b, h) do { _Pragma("unroll") for (int n = 0; n < 2; ++n) _Pragma("unroll") for (int k = 0; k < 2; ++k) dst[n][k] = *(const PG8_LAS bf16x8*)(lds + PG8_SB(b, h) + boff + n * 2048 + k * 1024); } while (0)
; #define PG8_MMA(ai, bj, At, Bt) do { __builtin_amdgcn_s_setprio(1); _Pragma("unroll") for (int m = 0; m < 4; ++m) _Pragma("unroll") for (int n = 0; n < 2; ++n) _Pragma("unroll") for (int k = 0; k < 2; ++k) \
;         acc[ai][bj][m][n] = __builtin_amdgcn_mfma_f32_16x16x32_bf16(Bt[n][k], At[m][k], acc[ai][bj][m][n], 0, 0, 0); __builtin_amdgcn_s_setprio(0); } while (0)
; #define PG8_WAIT_V(n) asm volatile("s_waitcnt vmcnt(" #n ")" ::: "memory")
; template <class Epi, class Sched, bool ALIGN_EPI = false, bool SP2 = false>
; __device__ __forceinline__ void gemm_phase(PG8_LAS unsigned char* lds, const Gemm g, const Sched& S, const Epi& E) {
;     ...
;             PG8_LDB(B0, 0, 0); PG8_LDB(B1, 0, 1); PG8_SCHED; PG8_LDA(At, 0, 0); PG8_STAGE(PG8_SA(1, 1), a1 + hstep, voffA);
;             PG8_WAIT_V(8); PG8_WAIT_L(0); PG8_BAR; PG8_MMA(0, 0, At, B0); PG8_MMA(0, 1, At, B1); PG8_BAR; PG8_SCHED;
;             PG8_LDA(At, 0, 1); PG8_STAGE(PG8_SB(0, 0), b2, voffB); PG8_STAGE(PG8_SB(0, 1), b2 + hstep, voffB); PG8_STAGE(PG8_SA(0, 0), a2, voffA);
;             PG8_WAIT_V(8); PG8_WAIT_L(0); PG8_BAR; PG8_MMA(1, 0, At, B0); PG8_MMA(1, 1, At, B1); PG8_BAR; PG8_SCHED;
;             PG8_LDB(B0, 1, 0); PG8_LDB(B1, 1, 1); PG8_SCHED; PG8_LDA(At, 1, 0); PG8_STAGE(PG8_SA(0, 1), a2 + hstep, voffA);
;             PG8_WAIT_V(8); PG8_WAIT_L(0); PG8_BAR; PG8_MMA(0, 0, At, B0); PG8_MMA(0, 1, At, B1); PG8_BAR; PG8_SCHED;
;             PG8_LDA(At, 1, 1); PG8_STAGE(PG8_SB(1, 0), b3, voffB); PG8_STAGE(PG8_SB(1, 1), b3 + hstep, voffB); PG8_STAGE(PG8_SA(1, 0), a3, voffA);
;             PG8_WAIT_V(8); PG8_WAIT_L(0); PG8_BAR; PG8_MMA(1, 0, At, B0); PG8_MMA(1, 1, At, B1); PG8_BAR; PG8_SCHED;
	s_add_i32 s46, s59, s25
	v_lshl_add_u64 v[206:207], v[206:207], 0, s[20:21]
	s_mov_b32 m0, s46
	ds_read_b128 v[160:163], v236 offset:49152
	ds_read_b128 v[164:167], v236 offset:50176
	ds_read_b128 v[168:171], v236 offset:51200
	ds_read_b128 v[172:175], v236 offset:52224
	ds_read_b128 v[176:179], v236 offset:53248
	ds_read_b128 v[180:183], v236 offset:54272
	ds_read_b128 v[198:201], v236 offset:55296
	ds_read_b128 v[202:205], v236 offset:56320
	global_load_lds_dwordx4 v[206:207], off sc0
	s_add_i32 m0, s46, 0x2000
	s_add_u32 s44, s44, 0xb0080
	v_lshl_add_u64 v[206:207], v[208:209], 0, s[20:21]
	s_addc_u32 s45, s45, 0
	s_add_i32 s46, s60, s25
	global_load_lds_dwordx4 v[206:207], off sc0
	v_lshl_add_u64 v[206:207], s[44:45], 0, v[186:187]
	s_mov_b32 m0, s46
	s_nop 0
	global_load_lds_dwordx4 v[206:207], off sc0
	v_lshl_add_u64 v[206:207], s[44:45], 0, v[190:191]
	s_add_i32 m0, s46, 0x2000
	s_nop 0
	global_load_lds_dwordx4 v[206:207], off sc0
	v_lshl_add_u64 v[206:207], v[210:211], 0, s[20:21]
	s_mov_b32 m0, s31
	s_nop 0
	global_load_lds_dwordx4 v[206:207], off sc0
	v_lshl_add_u64 v[206:207], v[212:213], 0, s[20:21]
	s_mov_b32 m0, s33
	s_nop 0
	global_load_lds_dwordx4 v[206:207], off sc0
	s_waitcnt vmcnt(8)
	s_waitcnt lgkmcnt(0)
	s_barrier
	s_setprio 1
	s_waitcnt lgkmcnt(0)
	v_mfma_f32_16x16x32_bf16 v[60:63], v[124:127], v[160:163], v[60:63]
	v_mfma_f32_16x16x32_bf16 v[56:59], v[136:139], v[160:163], v[56:59]
	v_mfma_f32_16x16x32_bf16 v[44:47], v[124:127], v[168:171], v[44:47]
	v_mfma_f32_16x16x32_bf16 v[40:43], v[136:139], v[168:171], v[40:43]
	v_mfma_f32_16x16x32_bf16 v[28:31], v[124:127], v[176:179], v[28:31]
	v_mfma_f32_16x16x32_bf16 v[24:27], v[136:139], v[176:179], v[24:27]
	v_mfma_f32_16x16x32_bf16 v[12:15], v[124:127], v[198:201], v[12:15]
	v_mfma_f32_16x16x32_bf16 v[8:11], v[136:139], v[198:201], v[8:11]
	v_mfma_f32_16x16x32_bf16 v[60:63], v[132:135], v[164:167], v[60:63]
	v_mfma_f32_16x16x32_bf16 v[56:59], v[140:143], v[164:167], v[56:59]
	v_mfma_f32_16x16x32_bf16 v[44:47], v[132:135], v[172:175], v[44:47]
	v_mfma_f32_16x16x32_bf16 v[40:43], v[140:143], v[172:175], v[40:43]
	v_mfma_f32_16x16x32_bf16 v[28:31], v[132:135], v[180:183], v[28:31]
	v_mfma_f32_16x16x32_bf16 v[24:27], v[140:143], v[180:183], v[24:27]
	v_mfma_f32_16x16x32_bf16 v[12:15], v[132:135], v[202:205], v[12:15]
	v_mfma_f32_16x16x32_bf16 v[8:11], v[140:143], v[202:205], v[8:11]
	s_setprio 0
	s_setprio 1
	v_mfma_f32_16x16x32_bf16 v[52:55], v[144:147], v[160:163], v[52:55]
	v_mfma_f32_16x16x32_bf16 v[48:51], v[152:155], v[160:163], v[48:51]
	v_mfma_f32_16x16x32_bf16 v[36:39], v[144:147], v[168:171], v[36:39]
	v_mfma_f32_16x16x32_bf16 v[32:35], v[152:155], v[168:171], v[32:35]
	v_mfma_f32_16x16x32_bf16 v[20:23], v[144:147], v[176:179], v[20:23]
	v_mfma_f32_16x16x32_bf16 v[16:19], v[152:155], v[176:179], v[16:19]
	v_mfma_f32_16x16x32_bf16 v[4:7], v[144:147], v[198:201], v[4:7]
	v_mfma_f32_16x16x32_bf16 v[0:3], v[152:155], v[198:201], v[0:3]
	v_mfma_f32_16x16x32_bf16 v[52:55], v[148:151], v[164:167], v[52:55]
	v_mfma_f32_16x16x32_bf16 v[48:51], v[156:159], v[164:167], v[48:51]
	v_mfma_f32_16x16x32_bf16 v[36:39], v[148:151], v[172:175], v[36:39]
	v_mfma_f32_16x16x32_bf16 v[32:35], v[156:159], v[172:175], v[32:35]
	v_mfma_f32_16x16x32_bf16 v[20:23], v[148:151], v[180:183], v[20:23]
	v_mfma_f32_16x16x32_bf16 v[16:19], v[156:159], v[180:183], v[16:19]
	v_mfma_f32_16x16x32_bf16 v[4:7], v[148:151], v[202:205], v[4:7]
	v_mfma_f32_16x16x32_bf16 v[0:3], v[156:159], v[202:205], v[0:3]
	s_setprio 0
	s_barrier
	s_add_i32 s58, s58, 2
	s_add_u32 s42, s42, 0x100
	s_addc_u32 s43, s43, 0
	s_add_u32 s56, s56, 0x100
	s_addc_u32 s57, s57, 0
	s_cmp_gt_u32 s58, 41
.LBB0_570:
	ds_read_b128 v[124:127], v234
	ds_read_b128 v[132:135], v234 offset:1024
	ds_read_b128 v[136:139], v234 offset:2048
	ds_read_b128 v[140:143], v234 offset:3072
	ds_read_b128 v[144:147], v235
	ds_read_b128 v[148:151], v235 offset:1024
	ds_read_b128 v[152:155], v235 offset:2048
	ds_read_b128 v[156:159], v235 offset:3072
	s_add_u32 s44, s42, 0xfff50080
	s_addc_u32 s45, s43, -1
	s_cmp_eq_u32 s58, 40
	s_cselect_b32 s47, s39, s45
	s_cselect_b32 s46, s38, s44
	s_cselect_b32 s45, s41, s57
	s_cselect_b32 s44, s40, s56
	v_lshl_add_u64 v[206:207], s[42:43], 0, v[192:193]
	s_add_i32 m0, s26, 0xc000
	ds_read_b128 v[160:163], v236
	ds_read_b128 v[164:167], v236 offset:1024
	ds_read_b128 v[168:171], v236 offset:2048
	ds_read_b128 v[172:175], v236 offset:3072
	ds_read_b128 v[176:179], v236 offset:4096
	ds_read_b128 v[180:183], v236 offset:5120
	ds_read_b128 v[198:201], v236 offset:6144
	ds_read_b128 v[202:205], v236 offset:7168
	global_load_lds_dwordx4 v[206:207], off sc0
	v_lshl_add_u64 v[206:207], s[42:43], 0, v[194:195]
	s_add_i32 m0, s26, 0xe000
	s_nop 0
	global_load_lds_dwordx4 v[206:207], off sc0
	s_waitcnt vmcnt(8)
	s_waitcnt lgkmcnt(0)
	s_barrier
; #define PG8_STAGE(bufoff, gbase, voff) do { _Pragma("unroll") for (int _i = 0; _i < 2; ++_i) \
;         __builtin_amdgcn_global_load_lds((const unsigned*)((const char*)(gbase) + (voff)[_i]), (PG8_LAS unsigned*)(lds + (bufoff) + ldsw + _i * 8192), 16, 0, 0); } while (0)
; #define PG8_LDA(dst, b, h) do { _Pragma("unroll") for (int m = 0; m < 4; ++m) _Pragma("unroll") for (int k = 0; k < 2; ++k) dst[m][k] = *(const PG8_LAS bf16x8*)(lds + PG8_SA(b, h) + aoff + m * 2048 + k * 1024); } while (0)
; #define PG8_LDB(dst, b, h) do { _Pragma("unroll") for (int n = 0; n < 2; ++n) _Pragma("unroll") for (int k = 0; k < 2; ++k) dst[n][k] = *(const PG8_LAS bf16x8*)(lds + PG8_SB(b, h) + boff + n * 2048 + k * 1024); } while (0)
; #define PG8_MMA(ai, bj, At, Bt) do { __builtin_amdgcn_s_setprio(1); _Pragma("unroll") for (int m = 0; m < 4; ++m) _Pragma("unroll") for (int n = 0; n < 2; ++n) _Pragma("unroll") for (int k = 0; k < 2; ++k) \
;         acc[ai][bj][m][n] = __builtin_amdgcn_mfma_f32_16x16x32_bf16(Bt[n][k], At[m][k], acc[ai][bj][m][n], 0, 0, 0); __builtin_amdgcn_s_setprio(0); } while (0)
; #define PG8_WAIT_V(n) asm volatile("s_waitcnt vmcnt(" #n ")" ::: "memory")
; #define PG8_WAIT_L(n) asm volatile("s_waitcnt lgkmcnt(" #n ")" ::: "memory")
; #define PG8_BAR __builtin_amdgcn_s_barrier()
; #define PG8_SCHED __builtin_amdgcn_sched_barrier(0)
; template <class Epi, class Sched, bool ALIGN_EPI = false, bool SP2 = false>
; __device__ __forceinline__ void gemm_phase(PG8_LAS unsigned char* lds, const Gemm g, const Sched& S, const Epi& E) {
;     ...
;             PG8_WAIT_V(8); PG8_WAIT_L(0); PG8_BAR; PG8_MMA(0, 0, At, B0); PG8_MMA(0, 1, At, B1); PG8_BAR; PG8_SCHED;
;             PG8_LDA(At, 0, 1); PG8_STAGE(PG8_SB(0, 0), b2, voffB); PG8_STAGE(PG8_SB(0, 1), b2 + hstep, voffB); PG8_STAGE(PG8_SA(0, 0), a2, voffA);
;             PG8_WAIT_V(8); PG8_WAIT_L(0); PG8_BAR; PG8_MMA(1, 0, At, B0); PG8_MMA(1, 1, At, B1); PG8_BAR; PG8_SCHED;
;             PG8_LDB(B0, 1, 0); PG8_LDB(B1, 1, 1); PG8_SCHED; PG8_LDA(At, 1, 0); PG8_STAGE(PG8_SA(0, 1), a2 + hstep, voffA);
;             PG8_WAIT_V(8); PG8_WAIT_L(0); PG8_BAR; PG8_MMA(0, 0, At, B0); PG8_MMA(0, 1, At, B1); PG8_BAR; PG8_SCHED;
	s_setprio 1
	s_waitcnt lgkmcnt(0)
	v_mfma_f32_16x16x32_bf16 v[128:131], v[124:127], v[160:163], v[128:131]
	v_mfma_f32_16x16x32_bf16 v[120:123], v[136:139], v[160:163], v[120:123]
	v_mfma_f32_16x16x32_bf16 v[108:111], v[124:127], v[168:171], v[108:111]
	v_mfma_f32_16x16x32_bf16 v[104:107], v[136:139], v[168:171], v[104:107]
	v_mfma_f32_16x16x32_bf16 v[92:95], v[124:127], v[176:179], v[92:95]
	v_mfma_f32_16x16x32_bf16 v[88:91], v[136:139], v[176:179], v[88:91]
	v_mfma_f32_16x16x32_bf16 v[76:79], v[124:127], v[198:201], v[76:79]
	v_mfma_f32_16x16x32_bf16 v[72:75], v[136:139], v[198:201], v[72:75]
	v_mfma_f32_16x16x32_bf16 v[128:131], v[132:135], v[164:167], v[128:131]
	v_mfma_f32_16x16x32_bf16 v[120:123], v[140:143], v[164:167], v[120:123]
	v_mfma_f32_16x16x32_bf16 v[108:111], v[132:135], v[172:175], v[108:111]
	v_mfma_f32_16x16x32_bf16 v[104:107], v[140:143], v[172:175], v[104:107]
	v_mfma_f32_16x16x32_bf16 v[92:95], v[132:135], v[180:183], v[92:95]
	v_mfma_f32_16x16x32_bf16 v[88:91], v[140:143], v[180:183], v[88:91]
	v_mfma_f32_16x16x32_bf16 v[76:79], v[132:135], v[202:205], v[76:79]
	v_mfma_f32_16x16x32_bf16 v[72:75], v[140:143], v[202:205], v[72:75]
	s_setprio 0
	s_setprio 1
	v_mfma_f32_16x16x32_bf16 v[116:119], v[144:147], v[160:163], v[116:119]
	v_mfma_f32_16x16x32_bf16 v[112:115], v[152:155], v[160:163], v[112:115]
	v_mfma_f32_16x16x32_bf16 v[100:103], v[144:147], v[168:171], v[100:103]
	v_mfma_f32_16x16x32_bf16 v[96:99], v[152:155], v[168:171], v[96:99]
	v_mfma_f32_16x16x32_bf16 v[84:87], v[144:147], v[176:179], v[84:87]
	v_mfma_f32_16x16x32_bf16 v[80:83], v[152:155], v[176:179], v[80:83]
	v_mfma_f32_16x16x32_bf16 v[68:71], v[144:147], v[198:201], v[68:71]
	v_mfma_f32_16x16x32_bf16 v[64:67], v[152:155], v[198:201], v[64:67]
	v_mfma_f32_16x16x32_bf16 v[116:119], v[148:151], v[164:167], v[116:119]
	v_mfma_f32_16x16x32_bf16 v[112:115], v[156:159], v[164:167], v[112:115]
	v_mfma_f32_16x16x32_bf16 v[100:103], v[148:151], v[172:175], v[100:103]
	v_mfma_f32_16x16x32_bf16 v[96:99], v[156:159], v[172:175], v[96:99]
	v_mfma_f32_16x16x32_bf16 v[84:87], v[148:151], v[180:183], v[84:87]
	v_mfma_f32_16x16x32_bf16 v[80:83], v[156:159], v[180:183], v[80:83]
	v_mfma_f32_16x16x32_bf16 v[68:71], v[148:151], v[202:205], v[68:71]
	v_mfma_f32_16x16x32_bf16 v[64:67], v[156:159], v[202:205], v[64:67]
	s_setprio 0
	s_barrier
	s_add_i32 s59, s50, s25
	v_lshl_add_u64 v[206:207], s[44:45], 0, v[186:187]
	s_mov_b32 m0, s59
	ds_read_b128 v[160:163], v236 offset:16384
	ds_read_b128 v[164:167], v236 offset:17408
	ds_read_b128 v[168:171], v236 offset:18432
	ds_read_b128 v[172:175], v236 offset:19456
	ds_read_b128 v[176:179], v236 offset:20480
	ds_read_b128 v[180:183], v236 offset:21504
	ds_read_b128 v[198:201], v236 offset:22528
	ds_read_b128 v[202:205], v236 offset:23552
	global_load_lds_dwordx4 v[206:207], off sc0
	s_add_i32 m0, s59, 0x2000
	s_add_u32 s60, s44, 0xb0000
	v_lshl_add_u64 v[208:209], s[44:45], 0, v[190:191]
	s_addc_u32 s61, s45, 0
	s_add_i32 s59, s51, s25
	global_load_lds_dwordx4 v[208:209], off sc0
	v_lshl_add_u64 v[210:211], s[60:61], 0, v[186:187]
	s_mov_b32 m0, s59
	v_lshl_add_u64 v[212:213], s[46:47], 0, v[188:189]
	global_load_lds_dwordx4 v[210:211], off sc0
	v_lshl_add_u64 v[210:211], s[60:61], 0, v[190:191]
	s_add_i32 m0, s59, 0x2000
	s_nop 0
	global_load_lds_dwordx4 v[210:211], off sc0
	v_lshl_add_u64 v[210:211], s[46:47], 0, v[184:185]
	s_mov_b32 m0, s26
	s_nop 0
	global_load_lds_dwordx4 v[210:211], off sc0
	s_mov_b32 m0, s27
	s_nop 0
	global_load_lds_dwordx4 v[212:213], off sc0
	s_waitcnt vmcnt(8)
	s_waitcnt lgkmcnt(0)
	s_barrier
	s_setprio 1
	s_waitcnt lgkmcnt(0)
	v_mfma_f32_16x16x32_bf16 v[60:63], v[124:127], v[160:163], v[60:63]
	v_mfma_f32_16x16x32_bf16 v[56:59], v[136:139], v[160:163], v[56:59]
	v_mfma_f32_16x16x32_bf16 v[44:47], v[124:127], v[168:171], v[44:47]
	v_mfma_f32_16x16x32_bf16 v[40:43], v[136:139], v[168:171], v[40:43]
	v_mfma_f32_16x16x32_bf16 v[28:31], v[124:127], v[176:179], v[28:31]
	v_mfma_f32_16x16x32_bf16 v[24:27], v[136:139], v[176:179], v[24:27]
	v_mfma_f32_16x16x32_bf16 v[12:15], v[124:127], v[198:201], v[12:15]
	v_mfma_f32_16x16x32_bf16 v[8:11], v[136:139], v[198:201], v[8:11]
	v_mfma_f32_16x16x32_bf16 v[60:63], v[132:135], v[164:167], v[60:63]
	v_mfma_f32_16x16x32_bf16 v[56:59], v[140:143], v[164:167], v[56:59]
	v_mfma_f32_16x16x32_bf16 v[44:47], v[132:135], v[172:175], v[44:47]
	v_mfma_f32_16x16x32_bf16 v[40:43], v[140:143], v[172:175], v[40:43]
	v_mfma_f32_16x16x32_bf16 v[28:31], v[132:135], v[180:183], v[28:31]
	v_mfma_f32_16x16x32_bf16 v[24:27], v[140:143], v[180:183], v[24:27]
	v_mfma_f32_16x16x32_bf16 v[12:15], v[132:135], v[202:205], v[12:15]
	v_mfma_f32_16x16x32_bf16 v[8:11], v[140:143], v[202:205], v[8:11]
	s_setprio 0
	s_setprio 1
	v_mfma_f32_16x16x32_bf16 v[52:55], v[144:147], v[160:163], v[52:55]
	v_mfma_f32_16x16x32_bf16 v[48:51], v[152:155], v[160:163], v[48:51]
	v_mfma_f32_16x16x32_bf16 v[36:39], v[144:147], v[168:171], v[36:39]
	v_mfma_f32_16x16x32_bf16 v[32:35], v[152:155], v[168:171], v[32:35]
	v_mfma_f32_16x16x32_bf16 v[20:23], v[144:147], v[176:179], v[20:23]
	v_mfma_f32_16x16x32_bf16 v[16:19], v[152:155], v[176:179], v[16:19]
	v_mfma_f32_16x16x32_bf16 v[4:7], v[144:147], v[198:201], v[4:7]
	v_mfma_f32_16x16x32_bf16 v[0:3], v[152:155], v[198:201], v[0:3]
	v_mfma_f32_16x16x32_bf16 v[52:55], v[148:151], v[164:167], v[52:55]
	v_mfma_f32_16x16x32_bf16 v[48:51], v[156:159], v[164:167], v[48:51]
	v_mfma_f32_16x16x32_bf16 v[36:39], v[148:151], v[172:175], v[36:39]
	v_mfma_f32_16x16x32_bf16 v[32:35], v[156:159], v[172:175], v[32:35]
	v_mfma_f32_16x16x32_bf16 v[20:23], v[148:151], v[180:183], v[20:23]
	v_mfma_f32_16x16x32_bf16 v[16:19], v[156:159], v[180:183], v[16:19]
	v_mfma_f32_16x16x32_bf16 v[4:7], v[148:151], v[202:205], v[4:7]
	v_mfma_f32_16x16x32_bf16 v[0:3], v[156:159], v[202:205], v[0:3]
	s_setprio 0
	s_barrier
; #define PG8_STAGE(bufoff, gbase, voff) do { _Pragma("unroll") for (int _i = 0; _i < 2; ++_i) \
;         __builtin_amdgcn_global_load_lds((const unsigned*)((const char*)(gbase) + (voff)[_i]), (PG8_LAS unsigned*)(lds + (bufoff) + ldsw + _i * 8192), 16, 0, 0); } while (0)
; #define PG8_LDA(dst, b, h) do { _Pragma("unroll") for (int m = 0; m < 4; ++m) _Pragma("unroll") for (int k = 0; k < 2; ++k) dst[m][k] = *(const PG8_LAS bf16x8*)(lds + PG8_SA(b, h) + aoff + m * 2048 + k * 1024); } while (0)
; #define PG8_LDB(dst, b, h) do { _Pragma("unroll") for (int n = 0; n < 2; ++n) _Pragma("unroll") for (int k = 0; k < 2; ++k) dst[n][k] = *(const PG8_LAS bf16x8*)(lds + PG8_SB(b, h) + boff + n * 2048 + k * 1024); } while (0)
; #define PG8_MMA(ai, bj, At, Bt) do { __builtin_amdgcn_s_setprio(1); _Pragma("unroll") for (int m = 0; m < 4; ++m) _Pragma("unroll") for (int n = 0; n < 2; ++n) _Pragma("unroll") for (int k = 0; k < 2; ++k) \
;         acc[ai][bj][m][n] = __builtin_amdgcn_mfma_f32_16x16x32_bf16(Bt[n][k], At[m][k], acc[ai][bj][m][n], 0, 0, 0); __builtin_amdgcn_s_setprio(0); } while (0)
; #define PG8_WAIT_V(n) asm volatile("s_waitcnt vmcnt(" #n ")" ::: "memory")
; #define PG8_WAIT_L(n) asm volatile("s_waitcnt lgkmcnt(" #n ")" ::: "memory")
; #define PG8_BAR __builtin_amdgcn_s_barrier()
; #define PG8_SCHED __builtin_amdgcn_sched_barrier(0)
; template <class Epi, class Sched, bool ALIGN_EPI = false, bool SP2 = false>
; __device__ __forceinline__ void gemm_phase(PG8_LAS unsigned char* lds, const Gemm g, const Sched& S, const Epi& E) {
;     ...
;             PG8_LDB(B0, 1, 0); PG8_LDB(B1, 1, 1); PG8_SCHED; PG8_LDA(At, 1, 0); PG8_STAGE(PG8_SA(0, 1), a2 + hstep, voffA);
;             PG8_WAIT_V(8); PG8_WAIT_L(0); PG8_BAR; PG8_MMA(0, 0, At, B0); PG8_MMA(0, 1, At, B1); PG8_BAR; PG8_SCHED;
	s_add_i32 s59, 0, 0x18000
	s_add_i32 s60, 0, 0x1c000
	v_add_u32_e32 v140, s59, v232
	v_add_u32_e32 v156, s60, v232
	ds_read_b128 v[124:127], v140
	ds_read_b128 v[132:135], v140 offset:1024
	ds_read_b128 v[136:139], v140 offset:2048
	ds_read_b128 v[140:143], v140 offset:3072
	ds_read_b128 v[144:147], v156
	ds_read_b128 v[148:151], v156 offset:1024
	ds_read_b128 v[152:155], v156 offset:2048
	ds_read_b128 v[156:159], v156 offset:3072
	s_add_u32 s46, s46, 0xb0000
	s_addc_u32 s47, s47, 0
	s_mov_b32 m0, s28
	v_lshl_add_u64 v[214:215], s[46:47], 0, v[184:185]
	ds_read_b128 v[160:163], v236 offset:32768
	ds_read_b128 v[164:167], v236 offset:33792
	ds_read_b128 v[168:171], v236 offset:34816
	ds_read_b128 v[172:175], v236 offset:35840
	ds_read_b128 v[176:179], v236 offset:36864
	ds_read_b128 v[180:183], v236 offset:37888
	ds_read_b128 v[198:201], v236 offset:38912
	ds_read_b128 v[202:205], v236 offset:39936
	global_load_lds_dwordx4 v[214:215], off sc0
	v_lshl_add_u64 v[214:215], s[46:47], 0, v[188:189]
	s_mov_b32 m0, s29
	s_nop 0
	global_load_lds_dwordx4 v[214:215], off sc0
	s_waitcnt vmcnt(8)
	s_waitcnt lgkmcnt(0)
	s_barrier
	s_setprio 1
	s_waitcnt lgkmcnt(0)
	v_mfma_f32_16x16x32_bf16 v[128:131], v[124:127], v[160:163], v[128:131]
	v_mfma_f32_16x16x32_bf16 v[120:123], v[136:139], v[160:163], v[120:123]
	v_mfma_f32_16x16x32_bf16 v[108:111], v[124:127], v[168:171], v[108:111]
	v_mfma_f32_16x16x32_bf16 v[104:107], v[136:139], v[168:171], v[104:107]
	v_mfma_f32_16x16x32_bf16 v[92:95], v[124:127], v[176:179], v[92:95]
	v_mfma_f32_16x16x32_bf16 v[88:91], v[136:139], v[176:179], v[88:91]
	v_mfma_f32_16x16x32_bf16 v[76:79], v[124:127], v[198:201], v[76:79]
	v_mfma_f32_16x16x32_bf16 v[72:75], v[136:139], v[198:201], v[72:75]
	v_mfma_f32_16x16x32_bf16 v[128:131], v[132:135], v[164:167], v[128:131]
	v_mfma_f32_16x16x32_bf16 v[120:123], v[140:143], v[164:167], v[120:123]
	v_mfma_f32_16x16x32_bf16 v[108:111], v[132:135], v[172:175], v[108:111]
	v_mfma_f32_16x16x32_bf16 v[104:107], v[140:143], v[172:175], v[104:107]
	v_mfma_f32_16x16x32_bf16 v[92:95], v[132:135], v[180:183], v[92:95]
	v_mfma_f32_16x16x32_bf16 v[88:91], v[140:143], v[180:183], v[88:91]
	v_mfma_f32_16x16x32_bf16 v[76:79], v[132:135], v[202:205], v[76:79]
	v_mfma_f32_16x16x32_bf16 v[72:75], v[140:143], v[202:205], v[72:75]
	s_setprio 0
	s_setprio 1
	v_mfma_f32_16x16x32_bf16 v[116:119], v[144:147], v[160:163], v[116:119]
	v_mfma_f32_16x16x32_bf16 v[112:115], v[152:155], v[160:163], v[112:115]
	v_mfma_f32_16x16x32_bf16 v[100:103], v[144:147], v[168:171], v[100:103]
	v_mfma_f32_16x16x32_bf16 v[96:99], v[152:155], v[168:171], v[96:99]
	v_mfma_f32_16x16x32_bf16 v[84:87], v[144:147], v[176:179], v[84:87]
	v_mfma_f32_16x16x32_bf16 v[80:83], v[152:155], v[176:179], v[80:83]
	v_mfma_f32_16x16x32_bf16 v[68:71], v[144:147], v[198:201], v[68:71]
	v_mfma_f32_16x16x32_bf16 v[64:67], v[152:155], v[198:201], v[64:67]
	v_mfma_f32_16x16x32_bf16 v[116:119], v[148:151], v[164:167], v[116:119]
	v_mfma_f32_16x16x32_bf16 v[112:115], v[156:159], v[164:167], v[112:115]
	v_mfma_f32_16x16x32_bf16 v[100:103], v[148:151], v[172:175], v[100:103]
	v_mfma_f32_16x16x32_bf16 v[96:99], v[156:159], v[172:175], v[96:99]
	v_mfma_f32_16x16x32_bf16 v[84:87], v[148:151], v[180:183], v[84:87]
	v_mfma_f32_16x16x32_bf16 v[80:83], v[156:159], v[180:183], v[80:83]
	v_mfma_f32_16x16x32_bf16 v[68:71], v[148:151], v[202:205], v[68:71]
	v_mfma_f32_16x16x32_bf16 v[64:67], v[156:159], v[202:205], v[64:67]
	s_setprio 0
	s_barrier
; #define PG8_STAGE(bufoff, gbase, voff) do { _Pragma("unroll") for (int _i = 0; _i < 2; ++_i) \
;         __builtin_amdgcn_global_load_lds((const unsigned*)((const char*)(gbase) + (voff)[_i]), (PG8_LAS unsigned*)(lds + (bufoff) + ldsw + _i * 8192), 16, 0, 0); } while (0)
; #define PG8_LDA(dst, b, h) do { _Pragma("unroll") for (int m = 0; m < 4; ++m) _Pragma("unroll") for (int k = 0; k < 2; ++k) dst[m][k] = *(const PG8_LAS bf16x8*)(lds + PG8_SA(b, h) + aoff + m * 2048 + k * 1024); } while (0)
; #define PG8_MMA(ai, bj, At, Bt) do { __builtin_amdgcn_s_setprio(1); _Pragma("unroll") for (int m = 0; m < 4; ++m) _Pragma("unroll") for (int n = 0; n < 2; ++n) _Pragma("unroll") for (int k = 0; k < 2; ++k) \
;         acc[ai][bj][m][n] = __builtin_amdgcn_mfma_f32_16x16x32_bf16(Bt[n][k], At[m][k], acc[ai][bj][m][n], 0, 0, 0); __builtin_amdgcn_s_setprio(0); } while (0)
; #define PG8_WAIT_V(n) asm volatile("s_waitcnt vmcnt(" #n ")" ::: "memory")
; #define PG8_WAIT_L(n) asm volatile("s_waitcnt lgkmcnt(" #n ")" ::: "memory")
; #define PG8_BAR __builtin_amdgcn_s_barrier()
; #define PG8_SCHED __builtin_amdgcn_sched_barrier(0)
; template <class Epi, class Sched, bool ALIGN_EPI = false, bool SP2 = false>
; __device__ __forceinline__ void gemm_phase(PG8_LAS unsigned char* lds, const Gemm g, const Sched& S, const Epi& E) {
;     ...
;             PG8_LDA(At, 1, 1); PG8_STAGE(PG8_SB(1, 0), b3, voffB); PG8_STAGE(PG8_SB(1, 1), b3 + hstep, voffB); PG8_STAGE(PG8_SA(1, 0), a3, voffA);
;             PG8_WAIT_V(8); PG8_WAIT_L(0); PG8_BAR; PG8_MMA(1, 0, At, B0); PG8_MMA(1, 1, At, B1); PG8_BAR; PG8_SCHED;
	s_add_i32 s46, s59, s25
	v_lshl_add_u64 v[206:207], v[206:207], 0, s[20:21]
	s_mov_b32 m0, s46
	ds_read_b128 v[160:163], v236 offset:49152
	ds_read_b128 v[164:167], v236 offset:50176
	ds_read_b128 v[168:171], v236 offset:51200
	ds_read_b128 v[172:175], v236 offset:52224
	ds_read_b128 v[176:179], v236 offset:53248
	ds_read_b128 v[180:183], v236 offset:54272
	ds_read_b128 v[198:201], v236 offset:55296
	ds_read_b128 v[202:205], v236 offset:56320
	global_load_lds_dwordx4 v[206:207], off sc0
	s_add_i32 m0, s46, 0x2000
	s_add_u32 s44, s44, 0xb0080
	v_lshl_add_u64 v[206:207], v[208:209], 0, s[20:21]
	s_addc_u32 s45, s45, 0
	s_add_i32 s46, s60, s25
	global_load_lds_dwordx4 v[206:207], off sc0
	v_lshl_add_u64 v[206:207], s[44:45], 0, v[186:187]
	s_mov_b32 m0, s46
	s_nop 0
	global_load_lds_dwordx4 v[206:207], off sc0
	v_lshl_add_u64 v[206:207], s[44:45], 0, v[190:191]
	s_add_i32 m0, s46, 0x2000
	s_nop 0
	global_load_lds_dwordx4 v[206:207], off sc0
	v_lshl_add_u64 v[206:207], v[210:211], 0, s[20:21]
	s_mov_b32 m0, s31
	s_nop 0
	global_load_lds_dwordx4 v[206:207], off sc0
	v_lshl_add_u64 v[206:207], v[212:213], 0, s[20:21]
	s_mov_b32 m0, s33
	s_nop 0
	global_load_lds_dwordx4 v[206:207], off sc0
	s_waitcnt vmcnt(8)
	s_waitcnt lgkmcnt(0)
	s_barrier
	s_setprio 1
	s_waitcnt lgkmcnt(0)
	v_mfma_f32_16x16x32_bf16 v[60:63], v[124:127], v[160:163], v[60:63]
	v_mfma_f32_16x16x32_bf16 v[56:59], v[136:139], v[160:163], v[56:59]
	v_mfma_f32_16x16x32_bf16 v[44:47], v[124:127], v[168:171], v[44:47]
	v_mfma_f32_16x16x32_bf16 v[40:43], v[136:139], v[168:171], v[40:43]
	v_mfma_f32_16x16x32_bf16 v[28:31], v[124:127], v[176:179], v[28:31]
	v_mfma_f32_16x16x32_bf16 v[24:27], v[136:139], v[176:179], v[24:27]
	v_mfma_f32_16x16x32_bf16 v[12:15], v[124:127], v[198:201], v[12:15]
	v_mfma_f32_16x16x32_bf16 v[8:11], v[136:139], v[198:201], v[8:11]
	v_mfma_f32_16x16x32_bf16 v[60:63], v[132:135], v[164:167], v[60:63]
	v_mfma_f32_16x16x32_bf16 v[56:59], v[140:143], v[164:167], v[56:59]
	v_mfma_f32_16x16x32_bf16 v[44:47], v[132:135], v[172:175], v[44:47]
	v_mfma_f32_16x16x32_bf16 v[40:43], v[140:143], v[172:175], v[40:43]
	v_mfma_f32_16x16x32_bf16 v[28:31], v[132:135], v[180:183], v[28:31]
	v_mfma_f32_16x16x32_bf16 v[24:27], v[140:143], v[180:183], v[24:27]
	v_mfma_f32_16x16x32_bf16 v[12:15], v[132:135], v[202:205], v[12:15]
	v_mfma_f32_16x16x32_bf16 v[8:11], v[140:143], v[202:205], v[8:11]
	s_setprio 0
	s_setprio 1
	v_mfma_f32_16x16x32_bf16 v[52:55], v[144:147], v[160:163], v[52:55]
	v_mfma_f32_16x16x32_bf16 v[48:51], v[152:155], v[160:163], v[48:51]
	v_mfma_f32_16x16x32_bf16 v[36:39], v[144:147], v[168:171], v[36:39]
	v_mfma_f32_16x16x32_bf16 v[32:35], v[152:155], v[168:171], v[32:35]
	v_mfma_f32_16x16x32_bf16 v[20:23], v[144:147], v[176:179], v[20:23]
	v_mfma_f32_16x16x32_bf16 v[16:19], v[152:155], v[176:179], v[16:19]
	v_mfma_f32_16x16x32_bf16 v[4:7], v[144:147], v[198:201], v[4:7]
	v_mfma_f32_16x16x32_bf16 v[0:3], v[152:155], v[198:201], v[0:3]
	v_mfma_f32_16x16x32_bf16 v[52:55], v[148:151], v[164:167], v[52:55]
	v_mfma_f32_16x16x32_bf16 v[48:51], v[156:159], v[164:167], v[48:51]
	v_mfma_f32_16x16x32_bf16 v[36:39], v[148:151], v[172:175], v[36:39]
	v_mfma_f32_16x16x32_bf16 v[32:35], v[156:159], v[172:175], v[32:35]
	v_mfma_f32_16x16x32_bf16 v[20:23], v[148:151], v[180:183], v[20:23]
	v_mfma_f32_16x16x32_bf16 v[16:19], v[156:159], v[180:183], v[16:19]
	v_mfma_f32_16x16x32_bf16 v[4:7], v[148:151], v[202:205], v[4:7]
	v_mfma_f32_16x16x32_bf16 v[0:3], v[156:159], v[202:205], v[0:3]
	s_setprio 0
	s_barrier
	s_add_i32 s58, s58, 2
	s_add_u32 s42, s42, 0x100
	s_addc_u32 s43, s43, 0
	s_add_u32 s56, s56, 0x100
	s_addc_u32 s57, s57, 0
	s_cmp_gt_u32 s58, 41
	s_cbranch_scc0 .LBB0_570
	s_and_b64 vcc, exec, s[36:37]
	s_cbranch_vccz .LBB0_573
	s_barrier

; __device__ __forceinline__ unsigned xb_ld(unsigned* p)              { return __hip_atomic_load(p, __ATOMIC_RELAXED, __HIP_MEMORY_SCOPE_AGENT); }
; __device__ __forceinline__ unsigned xb_add(unsigned* p, unsigned v) { return __hip_atomic_fetch_add(p, v, __ATOMIC_RELAXED, __HIP_MEMORY_SCOPE_AGENT); }
; #define XB_SPIN(cond, bar) do { unsigned _sp = 0; while (cond) { __builtin_amdgcn_s_sleep(1); \
;     if ((++_sp & 255u) == 0u) { if (xb_ld(&(bar)[XB_TMO])) break; if (_sp > XB_SPIN_CAP) { atomicAdd(&(bar)[XB_TMO], 1u); break; } } } } while (0)
; __device__ __forceinline__ void xcd_barrier(const XcdBarrier& b) {
;     asm volatile("s_waitcnt vmcnt(0)" ::: "memory");
;     __syncthreads();
;     if (threadIdx.x == 0) {
;         unsigned* bar = b.bar;
;         __builtin_amdgcn_s_waitcnt(0);
;         unsigned nloc = b.st[0], nx = b.st[1];
;         if (nloc == 0u) { xcd_barrier_complete(bar, b.x, nloc, nx); b.st[0] = nloc; b.st[1] = nx; }
;         const unsigned old = xb_add(&bar[XB_XSUB(b.x)], 1u);
;         const unsigned gen = old / nloc;
;         if (old + 1u == (gen + 1u) * nloc) {
;             __builtin_amdgcn_fence(__ATOMIC_RELEASE, "agent");
;             asm volatile("s_waitcnt vmcnt(0)" ::: "memory");
;             const unsigned og = xb_add(&bar[XB_TOP], 1u);
;             const unsigned tg = og / nx;
;             if (og + 1u == (tg + 1u) * nx) xb_add(&bar[XB_TOPGEN], 1u);
;             else XB_SPIN(xb_ld(&bar[XB_TOPGEN]) == tg, bar);
;             __builtin_amdgcn_fence(__ATOMIC_ACQUIRE, "agent");
;             xb_add(&bar[XB_XGEN(b.x)], 1u);
;             asm volatile("s_waitcnt vmcnt(0)" ::: "memory");
;         } else {
;             XB_SPIN(xb_ld(&bar[XB_XGEN(b.x)]) == gen, bar);
;             __builtin_amdgcn_fence(__ATOMIC_ACQUIRE, "agent");
;             asm volatile("s_waitcnt vmcnt(0)" ::: "memory");
;         }
;     }
;     __syncthreads();
; }
.LBB0_1016:
	s_or_b64 exec, exec, s[12:13]
	s_waitcnt vmcnt(0)
	buffer_inv sc0
	s_waitcnt vmcnt(0)
.LBB0_1017:
	s_andn2_saveexec_b64 s[10:11], s[10:11]
	s_cbranch_execz .LBB0_1037
	s_mov_b64 s[10:11], exec
	s_mov_b64 s[10:11], exec
	v_mbcnt_lo_u32_b32 v0, s10, 0
	v_mbcnt_hi_u32_b32 v0, s11, v0
	v_cmp_eq_u32_e32 vcc, 0, v0
	s_waitcnt vmcnt(0)
	buffer_inv sc0
	s_and_saveexec_b64 s[12:13], vcc
	s_cbranch_execz .LBB0_1036
	s_bcnt1_i32_b64 s3, s[10:11]
	v_mov_b32_e32 v0, 0x2000
	v_mov_b32_e32 v1, s3
	global_atomic_add v0, v1, s[8:9] offset:1024

; #define PG8_STAGE(bufoff, gbase, voff) do { _Pragma("unroll") for (int _i = 0; _i < 2; ++_i) \
;         __builtin_amdgcn_global_load_lds((const unsigned*)((const char*)(gbase) + (voff)[_i]), (PG8_LAS unsigned*)(lds + (bufoff) + ldsw + _i * 8192), 16, 0, 0); } while (0)
; #define PG8_WAIT_V(n) asm volatile("s_waitcnt vmcnt(" #n ")" ::: "memory")
; #define PG8_BAR __builtin_amdgcn_s_barrier()
; template <class Epi, class Sched, bool ALIGN_EPI = false, bool SP2 = false>
; __device__ __forceinline__ void gemm_phase(PG8_LAS unsigned char* lds, const Gemm g, const Sched& S, const Epi& E) {
;     const int tid = threadIdx.x, wid = __builtin_amdgcn_readfirstlane(tid >> 6), lane = tid & 63, wr = wid >> 2, wc = wid & 3, fr = lane & 15, fq = lane >> 4;
;     const int K = g.K, nt = K / BK;
;     unsigned voffA[2], voffB[2];
; #pragma unroll
;     for (int i = 0; i < 2; ++i) { int R, C; stage_rc(tid * 16 + i * 8192, R, C); const int Rb = Epi::PERM ? ((R & ~31) + perm32(R & 31)) : R;
;         voffA[i] = (unsigned)(R * K + C) * 2u; voffB[i] = (unsigned)(Rb * K + C) * 2u; }
;     const size_t kstep = (size_t)(BK * 2);
;     const size_t hstep = (size_t)HALF * K * 2;
;     const size_t tstep = 2 * hstep;
;     const unsigned ldsw = (unsigned)wid * 1024u;
;     const int aoff = lds_byte(wr * 64 + fr, fq * 8), boff = lds_byte(wc * 32 + fr, fq * 8);
;     ...
;     Unit cur, nxt; int ui = 0;
;     if (!S.next(0, cur)) return;
;     f32x4 acc[2][2][4][2];
; #pragma unroll
;     for (int a = 0; a < 2; ++a)
; #pragma unroll
;         for (int b = 0; b < 2; ++b)
; #pragma unroll
;             for (int m = 0; m < 4; ++m)
; #pragma unroll
;                 for (int n = 0; n < 2; ++n) acc[a][b][m][n] = (f32x4){0.f, 0.f, 0.f, 0.f};
;     bf16x8 At[4][2], B0[2][2], B1[2][2];
;     const char* cA = (const char*)g.A + (size_t)cur.pm * tstep; const char* cB = (const char*)g.Bt + (size_t)cur.pn * tstep;
;     S.a_ready(cur);
;     if constexpr (SP2) {
;         PG8_STAGE(PG8_SB(0, 0), cB, voffB); PG8_STAGE(PG8_SB(0, 1), cB + hstep, voffB); PG8_STAGE(PG8_SA(0, 0), cA, voffA); PG8_STAGE(PG8_SA(0, 1), cA + hstep, voffA);
;         if (wr == 1) PG8_BAR;
;         PG8_WAIT_V(2); PG8_BAR;
;         PG8_STAGE(PG8_SB(1, 0), cB + kstep, voffB); PG8_STAGE(PG8_SA(1, 0), cA + kstep, voffA); PG8_STAGE(PG8_SB(1, 1), cB + hstep + kstep, voffB);
;         PG8_WAIT_V(6); PG8_BAR;
.LBB0_1045:
	s_add_u32 s23, s70, 0x3e200000
	s_addc_u32 s24, s71, 0
	s_add_i32 s4, s4, s5
	s_ashr_i32 s5, s4, 31
	s_lshr_b32 s5, s5, 27
	s_add_i32 s5, s4, s5
	s_ashr_i32 s8, s5, 5
	s_and_b32 s5, s5, 0xffe0
	s_sub_i32 s4, s4, s5
	s_bfe_i32 s5, s4, 0x80000
	s_bfe_u32 s5, s5, 0x3000c
	v_lshrrev_b32_e32 v3, 1, v230
	s_add_i32 s5, s4, s5
	v_and_b32_e32 v10, 24, v3
	v_lshrrev_b32_e32 v3, 5, v230
	s_and_b32 s9, s5, 0xf8
	v_and_b32_e32 v3, 4, v3
	v_bfe_u32 v4, v230, 2, 2
	s_sub_i32 s4, s4, s9
	v_lshlrev_b32_e32 v0, 4, v230
	s_waitcnt lgkmcnt(0)
	v_and_b32_e32 v1, 32, v230
	v_bfe_u32 v2, v230, 2, 4
	v_or3_b32 v3, v3, v4, v10
	v_lshrrev_b32_e32 v4, 3, v230
	s_movk_i32 s1, 0x70
	s_lshl_b32 s8, s8, 3
	s_sext_i32_i8 s4, s4
	v_bitop3_b32 v8, v0, v1, 48 bitop3:0x6c
	v_and_or_b32 v5, v4, s1, v2
	s_movk_i32 s1, 0x60
	v_add_u32_e32 v0, 0x2000, v0
	s_add_i32 s39, s8, s4
	s_bfe_i32 s4, s5, 0x80000
	v_and_or_b32 v4, v4, s1, v3
	v_lshrrev_b32_e32 v0, 7, v0
	s_movk_i32 s1, 0xf0
	s_sext_i32_i16 s4, s4
	v_and_or_b32 v2, v0, s1, v2
	s_movk_i32 s1, 0xe0
	s_ashr_i32 s40, s4, 3
	v_and_b32_e32 v9, 64, v230
	v_and_or_b32 v0, v0, s1, v3
	s_lshr_b32 s1, s10, 6
	s_mul_i32 s4, s40, 0x160000
	s_lshr_b32 s0, s10, 8
	v_or_b32_e32 v1, v8, v9
	s_lshl_b32 s25, s1, 10
	s_ashr_i32 s5, s4, 31
	v_lshrrev_b32_e32 v1, 1, v1
	v_mul_u32_u24_e32 v4, 0xb00, v4
	s_add_u32 s18, s23, s4
	v_or_b32_e32 v4, v4, v1
	s_addc_u32 s19, s24, s5
	s_add_i32 s26, s25, 0
	v_lshlrev_b32_e32 v162, 1, v4
	v_mul_u32_u24_e32 v0, 0xb00, v0
	s_add_i32 m0, s26, 0x10000
	v_or_b32_e32 v0, v0, v1
	global_load_lds_dwordx4 v162, s[18:19] sc0
	s_add_i32 m0, s26, 0x12000
	v_lshlrev_b32_e32 v166, 1, v0
	s_add_u32 s4, s18, 0xb0000
	global_load_lds_dwordx4 v166, s[18:19] sc0
	s_addc_u32 s5, s19, 0
	s_add_i32 m0, s26, 0x14000
	s_mul_i32 s9, s39, 0x160000
	global_load_lds_dwordx4 v162, s[4:5] sc0
	s_add_i32 m0, s26, 0x16000
	v_mul_u32_u24_e32 v11, 0xb00, v5
	s_mul_hi_i32 s8, s39, 0x160000
	s_add_u32 s16, s6, s9
	v_or_b32_e32 v5, v1, v11
	v_mul_u32_u24_e32 v12, 0xb00, v2
	s_addc_u32 s17, s7, s8
	s_add_i32 s27, s26, 0x2000
	v_lshlrev_b32_e32 v160, 1, v5
	v_or_b32_e32 v2, v12, v1
	global_load_lds_dwordx4 v166, s[4:5] sc0
	s_mov_b32 m0, s26
	s_add_u32 s4, s16, 0xb0000
	v_lshlrev_b32_e32 v164, 1, v2
	global_load_lds_dwordx4 v160, s[16:17] sc0
	s_mov_b32 m0, s27
	s_addc_u32 s5, s17, 0
	s_add_i32 s28, s26, 0x4000
	global_load_lds_dwordx4 v164, s[16:17] sc0
	s_mov_b32 m0, s28
	s_add_i32 s29, s26, 0x6000
	global_load_lds_dwordx4 v160, s[4:5] sc0
	s_mov_b32 m0, s29
	v_mov_b32_e32 v163, 0
	global_load_lds_dwordx4 v164, s[4:5] sc0
	v_mov_b32_e32 v167, v163
	v_mov_b32_e32 v161, v163
	v_mov_b32_e32 v165, v163
	s_cmp_eq_u32 s0, 1
	s_mov_b32 s30, 0
	v_lshl_add_u64 v[6:7], s[18:19], 0, v[162:163]
	v_lshl_add_u64 v[4:5], s[18:19], 0, v[166:167]
	v_lshl_add_u64 v[0:1], s[16:17], 0, v[160:161]
	s_cselect_b64 s[4:5], -1, 0
	s_cmp_lg_u32 s0, 1
	v_lshl_add_u64 v[2:3], s[16:17], 0, v[164:165]
	s_cbranch_scc1 .LBB0_1047
	s_barrier
.LBB0_1047:
	s_lshl_b32 s1, s1, 5
	s_mov_b64 s[8:9], 0x80
	s_and_b32 s1, s1, 0x60
	s_add_i32 m0, s26, 0x18000
	v_lshl_add_u64 v[6:7], v[6:7], 0, s[8:9]
	s_ashr_i32 s31, s74, 31
	s_lshl_b32 s11, s0, 13
	s_lshl_b32 s14, s1, 7
	s_waitcnt vmcnt(2)
	s_barrier
	global_load_lds_dwordx4 v[6:7], off sc0
	v_lshl_add_u64 v[4:5], v[4:5], 0, s[8:9]
	s_add_i32 m0, s26, 0x1a000
	s_add_i32 s33, s26, 0x8000
	s_add_i32 s34, s26, 0xa000
	global_load_lds_dwordx4 v[4:5], off sc0
	v_lshl_add_u64 v[0:1], v[0:1], 0, s[8:9]
	s_mov_b32 m0, s33
	s_add_u32 s12, s18, 0xb0080
	global_load_lds_dwordx4 v[0:1], off sc0
	v_lshl_add_u64 v[0:1], v[2:3], 0, s[8:9]
	s_mov_b32 m0, s34
	s_addc_u32 s13, s19, 0
	global_load_lds_dwordx4 v[0:1], off sc0
	s_add_i32 m0, s26, 0x1c000
	v_lshl_add_u64 v[0:1], s[12:13], 0, v[162:163]
	global_load_lds_dwordx4 v[0:1], off sc0
	v_lshl_add_u64 v[0:1], s[12:13], 0, v[166:167]
	s_add_i32 m0, s26, 0x1e000
	v_lshlrev_b32_e32 v2, 2, v230
	global_load_lds_dwordx4 v[0:1], off sc0
	v_and_b32_e32 v0, 15, v230
	v_lshl_or_b32 v186, s0, 6, v0
	v_lshlrev_b32_e32 v1, 1, v10
	v_lshlrev_b32_e32 v3, 6, v230
	s_movk_i32 s0, 0x3c0
	v_lshl_or_b32 v0, v0, 6, v1
	v_and_b32_e32 v2, 32, v2
	v_and_or_b32 v1, v3, s0, v1
	v_bitop3_b32 v187, s14, v1, v2 bitop3:0xf6
	s_waitcnt vmcnt(6)
	s_cmpk_lt_u32 s10, 0x100
	v_add_u16_e32 v1, v8, v9
	v_bitop3_b32 v0, v0, s11, v2 bitop3:0xde
	s_cselect_b64 s[10:11], -1, 0
	v_lshrrev_b16_e32 v1, 1, v1
	s_add_i32 s35, 0, 0x10000
	s_add_i32 s36, 0, 0x14000
	v_or_b32_e32 v188, s1, v10
	v_add_lshl_u32 v168, v11, v1, 1
	v_mov_b32_e32 v169, v163
	v_add_lshl_u32 v170, v12, v1, 1
	v_mov_b32_e32 v171, v163
	v_add_u32_e32 v189, s35, v187
	v_add_u32_e32 v190, s36, v187
	v_add_u32_e32 v191, 0, v0
	v_mov_b64_e32 v[172:173], 0x7ff
	s_barrier
	s_branch .LBB0_1050

; #define PG8_STAGE(bufoff, gbase, voff) do { _Pragma("unroll") for (int _i = 0; _i < 2; ++_i) \
;         __builtin_amdgcn_global_load_lds((const unsigned*)((const char*)(gbase) + (voff)[_i]), (PG8_LAS unsigned*)(lds + (bufoff) + ldsw + _i * 8192), 16, 0, 0); } while (0)
; #define PG8_LDA(dst, b, h) do { _Pragma("unroll") for (int m = 0; m < 4; ++m) _Pragma("unroll") for (int k = 0; k < 2; ++k) dst[m][k] = *(const PG8_LAS bf16x8*)(lds + PG8_SA(b, h) + aoff + m * 2048 + k * 1024); } while (0)
; #define PG8_LDB(dst, b, h) do { _Pragma("unroll") for (int n = 0; n < 2; ++n) _Pragma("unroll") for (int k = 0; k < 2; ++k) dst[n][k] = *(const PG8_LAS bf16x8*)(lds + PG8_SB(b, h) + boff + n * 2048 + k * 1024); } while (0)
; #define PG8_MMA(ai, bj, At, Bt) do { __builtin_amdgcn_s_setprio(1); _Pragma("unroll") for (int m = 0; m < 4; ++m) _Pragma("unroll") for (int n = 0; n < 2; ++n) _Pragma("unroll") for (int k = 0; k < 2; ++k) \
;         acc[ai][bj][m][n] = __builtin_amdgcn_mfma_f32_16x16x32_bf16(Bt[n][k], At[m][k], acc[ai][bj][m][n], 0, 0, 0); __builtin_amdgcn_s_setprio(0); } while (0)
; #define PG8_WAIT_V(n) asm volatile("s_waitcnt vmcnt(" #n ")" ::: "memory")
; #define PG8_WAIT_L(n) asm volatile("s_waitcnt lgkmcnt(" #n ")" ::: "memory")
; #define PG8_BAR __builtin_amdgcn_s_barrier()
; #define PG8_SCHED __builtin_amdgcn_sched_barrier(0)
; template <class Epi, class Sched, bool ALIGN_EPI = false, bool SP2 = false>
; __device__ __forceinline__ void gemm_phase(PG8_LAS unsigned char* lds, const Gemm g, const Sched& S, const Epi& E) {
;     ...
;             PG8_LDB(B0, 0, 0); PG8_LDB(B1, 0, 1); PG8_SCHED; PG8_LDA(At, 0, 0); PG8_STAGE(PG8_SA(1, 1), a1 + hstep, voffA);
;             PG8_WAIT_V(8); PG8_WAIT_L(0); PG8_BAR; PG8_MMA(0, 0, At, B0); PG8_MMA(0, 1, At, B1); PG8_BAR; PG8_SCHED;
;             PG8_LDA(At, 0, 1); PG8_STAGE(PG8_SB(0, 0), b2, voffB); PG8_STAGE(PG8_SB(0, 1), b2 + hstep, voffB); PG8_STAGE(PG8_SA(0, 0), a2, voffA);
;             PG8_WAIT_V(8); PG8_WAIT_L(0); PG8_BAR; PG8_MMA(1, 0, At, B0); PG8_MMA(1, 1, At, B1); PG8_BAR; PG8_SCHED;
.LBB0_1061:
	s_add_u32 s16, s16, 0xb0080
	s_addc_u32 s17, s17, 0
	s_add_u32 s41, s18, 0x100
	s_addc_u32 s42, s19, 0
	s_mov_b32 s43, -2
	ds_read_b128 v[128:131], v189
	ds_read_b128 v[132:135], v189 offset:1024
	ds_read_b128 v[136:139], v189 offset:2048
	ds_read_b128 v[140:143], v189 offset:3072
	ds_read_b128 v[144:147], v190
	ds_read_b128 v[148:151], v190 offset:1024
	ds_read_b128 v[152:155], v190 offset:2048
	ds_read_b128 v[156:159], v190 offset:3072
	s_add_u32 s18, s16, 0xfff50080
	s_addc_u32 s19, s17, -1
	s_cmp_eq_u32 s43, 40
	s_cselect_b32 s21, s13, s19
	s_cselect_b32 s20, s12, s18
	s_cselect_b32 s19, s15, s42
	s_cselect_b32 s18, s14, s41
	v_lshl_add_u64 v[212:213], s[16:17], 0, v[168:169]
	s_add_i32 m0, s26, 0xc000
	ds_read_b128 v[174:177], v191
	ds_read_b128 v[178:181], v191 offset:1024
	ds_read_b128 v[182:185], v191 offset:2048
	ds_read_b128 v[192:195], v191 offset:3072
	ds_read_b128 v[196:199], v191 offset:4096
	ds_read_b128 v[200:203], v191 offset:5120
	ds_read_b128 v[204:207], v191 offset:6144
	ds_read_b128 v[208:211], v191 offset:7168
	global_load_lds_dwordx4 v[212:213], off sc0
	v_lshl_add_u64 v[212:213], s[16:17], 0, v[170:171]
	s_add_i32 m0, s26, 0xe000
	s_nop 0
	global_load_lds_dwordx4 v[212:213], off sc0
	s_waitcnt vmcnt(8)
	s_waitcnt lgkmcnt(0)
	s_barrier
	s_setprio 1
	s_waitcnt lgkmcnt(0)
	v_mfma_f32_16x16x32_bf16 v[124:127], v[128:131], v[174:177], 0
	v_mfma_f32_16x16x32_bf16 v[120:123], v[136:139], v[174:177], 0
	v_mfma_f32_16x16x32_bf16 v[116:119], v[128:131], v[182:185], 0
	v_mfma_f32_16x16x32_bf16 v[104:107], v[136:139], v[182:185], 0
	v_mfma_f32_16x16x32_bf16 v[96:99], v[128:131], v[196:199], 0
	v_mfma_f32_16x16x32_bf16 v[88:91], v[136:139], v[196:199], 0
	v_mfma_f32_16x16x32_bf16 v[80:83], v[128:131], v[204:207], 0
	v_mfma_f32_16x16x32_bf16 v[72:75], v[136:139], v[204:207], 0
	v_mfma_f32_16x16x32_bf16 v[124:127], v[132:135], v[178:181], v[124:127]
	v_mfma_f32_16x16x32_bf16 v[120:123], v[140:143], v[178:181], v[120:123]
	v_mfma_f32_16x16x32_bf16 v[116:119], v[132:135], v[192:195], v[116:119]
	v_mfma_f32_16x16x32_bf16 v[104:107], v[140:143], v[192:195], v[104:107]
	v_mfma_f32_16x16x32_bf16 v[96:99], v[132:135], v[200:203], v[96:99]
	v_mfma_f32_16x16x32_bf16 v[88:91], v[140:143], v[200:203], v[88:91]
	v_mfma_f32_16x16x32_bf16 v[80:83], v[132:135], v[208:211], v[80:83]
	v_mfma_f32_16x16x32_bf16 v[72:75], v[140:143], v[208:211], v[72:75]
	s_setprio 0
	s_setprio 1
	v_mfma_f32_16x16x32_bf16 v[112:115], v[144:147], v[174:177], 0
	v_mfma_f32_16x16x32_bf16 v[108:111], v[152:155], v[174:177], 0
	v_mfma_f32_16x16x32_bf16 v[100:103], v[144:147], v[182:185], 0
	v_mfma_f32_16x16x32_bf16 v[92:95], v[152:155], v[182:185], 0
	v_mfma_f32_16x16x32_bf16 v[84:87], v[144:147], v[196:199], 0
	v_mfma_f32_16x16x32_bf16 v[76:79], v[152:155], v[196:199], 0
	v_mfma_f32_16x16x32_bf16 v[68:71], v[144:147], v[204:207], 0
	v_mfma_f32_16x16x32_bf16 v[64:67], v[152:155], v[204:207], 0
	v_mfma_f32_16x16x32_bf16 v[112:115], v[148:151], v[178:181], v[112:115]
	v_mfma_f32_16x16x32_bf16 v[108:111], v[156:159], v[178:181], v[108:111]
	v_mfma_f32_16x16x32_bf16 v[100:103], v[148:151], v[192:195], v[100:103]
	v_mfma_f32_16x16x32_bf16 v[92:95], v[156:159], v[192:195], v[92:95]
	v_mfma_f32_16x16x32_bf16 v[84:87], v[148:151], v[200:203], v[84:87]
	v_mfma_f32_16x16x32_bf16 v[76:79], v[156:159], v[200:203], v[76:79]
	v_mfma_f32_16x16x32_bf16 v[68:71], v[148:151], v[208:211], v[68:71]
	v_mfma_f32_16x16x32_bf16 v[64:67], v[156:159], v[208:211], v[64:67]
	s_setprio 0
	s_barrier
	s_add_i32 s44, s35, s25
	v_lshl_add_u64 v[212:213], s[18:19], 0, v[162:163]
	s_mov_b32 m0, s44
	ds_read_b128 v[174:177], v191 offset:16384
	ds_read_b128 v[178:181], v191 offset:17408
	ds_read_b128 v[182:185], v191 offset:18432
	ds_read_b128 v[192:195], v191 offset:19456
	ds_read_b128 v[196:199], v191 offset:20480
	ds_read_b128 v[200:203], v191 offset:21504
	ds_read_b128 v[204:207], v191 offset:22528
	ds_read_b128 v[208:211], v191 offset:23552
	global_load_lds_dwordx4 v[212:213], off sc0
	s_add_i32 m0, s44, 0x2000
	s_add_u32 s44, s18, 0xb0000
	v_lshl_add_u64 v[214:215], s[18:19], 0, v[166:167]
	s_addc_u32 s45, s19, 0
	s_add_i32 s46, s36, s25
	global_load_lds_dwordx4 v[214:215], off sc0
	v_lshl_add_u64 v[216:217], s[44:45], 0, v[162:163]
	s_mov_b32 m0, s46
	v_lshl_add_u64 v[218:219], s[20:21], 0, v[164:165]
	global_load_lds_dwordx4 v[216:217], off sc0
	v_lshl_add_u64 v[216:217], s[44:45], 0, v[166:167]
	s_add_i32 m0, s46, 0x2000
	s_nop 0
	global_load_lds_dwordx4 v[216:217], off sc0
	v_lshl_add_u64 v[216:217], s[20:21], 0, v[160:161]
	s_mov_b32 m0, s26
	s_nop 0
	global_load_lds_dwordx4 v[216:217], off sc0
	s_mov_b32 m0, s27
	s_nop 0
	global_load_lds_dwordx4 v[218:219], off sc0
	s_waitcnt vmcnt(8)
	s_waitcnt lgkmcnt(0)
	s_barrier
; #define PG8_STAGE(bufoff, gbase, voff) do { _Pragma("unroll") for (int _i = 0; _i < 2; ++_i) \
;         __builtin_amdgcn_global_load_lds((const unsigned*)((const char*)(gbase) + (voff)[_i]), (PG8_LAS unsigned*)(lds + (bufoff) + ldsw + _i * 8192), 16, 0, 0); } while (0)
; #define PG8_LDA(dst, b, h) do { _Pragma("unroll") for (int m = 0; m < 4; ++m) _Pragma("unroll") for (int k = 0; k < 2; ++k) dst[m][k] = *(const PG8_LAS bf16x8*)(lds + PG8_SA(b, h) + aoff + m * 2048 + k * 1024); } while (0)
; #define PG8_LDB(dst, b, h) do { _Pragma("unroll") for (int n = 0; n < 2; ++n) _Pragma("unroll") for (int k = 0; k < 2; ++k) dst[n][k] = *(const PG8_LAS bf16x8*)(lds + PG8_SB(b, h) + boff + n * 2048 + k * 1024); } while (0)
; #define PG8_MMA(ai, bj, At, Bt) do { __builtin_amdgcn_s_setprio(1); _Pragma("unroll") for (int m = 0; m < 4; ++m) _Pragma("unroll") for (int n = 0; n < 2; ++n) _Pragma("unroll") for (int k = 0; k < 2; ++k) \
;         acc[ai][bj][m][n] = __builtin_amdgcn_mfma_f32_16x16x32_bf16(Bt[n][k], At[m][k], acc[ai][bj][m][n], 0, 0, 0); __builtin_amdgcn_s_setprio(0); } while (0)
; #define PG8_WAIT_V(n) asm volatile("s_waitcnt vmcnt(" #n ")" ::: "memory")
; #define PG8_WAIT_L(n) asm volatile("s_waitcnt lgkmcnt(" #n ")" ::: "memory")
; #define PG8_BAR __builtin_amdgcn_s_barrier()
; #define PG8_SCHED __builtin_amdgcn_sched_barrier(0)
; template <class Epi, class Sched, bool ALIGN_EPI = false, bool SP2 = false>
; __device__ __forceinline__ void gemm_phase(PG8_LAS unsigned char* lds, const Gemm g, const Sched& S, const Epi& E) {
;     ...
;             PG8_WAIT_V(8); PG8_WAIT_L(0); PG8_BAR; PG8_MMA(1, 0, At, B0); PG8_MMA(1, 1, At, B1); PG8_BAR; PG8_SCHED;
;             PG8_LDB(B0, 1, 0); PG8_LDB(B1, 1, 1); PG8_SCHED; PG8_LDA(At, 1, 0); PG8_STAGE(PG8_SA(0, 1), a2 + hstep, voffA);
;             PG8_WAIT_V(8); PG8_WAIT_L(0); PG8_BAR; PG8_MMA(0, 0, At, B0); PG8_MMA(0, 1, At, B1); PG8_BAR; PG8_SCHED;
;             PG8_LDA(At, 1, 1); PG8_STAGE(PG8_SB(1, 0), b3, voffB); PG8_STAGE(PG8_SB(1, 1), b3 + hstep, voffB); PG8_STAGE(PG8_SA(1, 0), a3, voffA);
	s_setprio 1
	s_waitcnt lgkmcnt(0)
	v_mfma_f32_16x16x32_bf16 v[60:63], v[128:131], v[174:177], 0
	v_mfma_f32_16x16x32_bf16 v[56:59], v[136:139], v[174:177], 0
	v_mfma_f32_16x16x32_bf16 v[48:51], v[128:131], v[182:185], 0
	v_mfma_f32_16x16x32_bf16 v[40:43], v[136:139], v[182:185], 0
	v_mfma_f32_16x16x32_bf16 v[32:35], v[128:131], v[196:199], 0
	v_mfma_f32_16x16x32_bf16 v[24:27], v[136:139], v[196:199], 0
	v_mfma_f32_16x16x32_bf16 v[16:19], v[128:131], v[204:207], 0
	v_mfma_f32_16x16x32_bf16 v[8:11], v[136:139], v[204:207], 0
	v_mfma_f32_16x16x32_bf16 v[60:63], v[132:135], v[178:181], v[60:63]
	v_mfma_f32_16x16x32_bf16 v[56:59], v[140:143], v[178:181], v[56:59]
	v_mfma_f32_16x16x32_bf16 v[48:51], v[132:135], v[192:195], v[48:51]
	v_mfma_f32_16x16x32_bf16 v[40:43], v[140:143], v[192:195], v[40:43]
	v_mfma_f32_16x16x32_bf16 v[32:35], v[132:135], v[200:203], v[32:35]
	v_mfma_f32_16x16x32_bf16 v[24:27], v[140:143], v[200:203], v[24:27]
	v_mfma_f32_16x16x32_bf16 v[16:19], v[132:135], v[208:211], v[16:19]
	v_mfma_f32_16x16x32_bf16 v[8:11], v[140:143], v[208:211], v[8:11]
	s_setprio 0
	s_setprio 1
	v_mfma_f32_16x16x32_bf16 v[52:55], v[144:147], v[174:177], 0
	v_mfma_f32_16x16x32_bf16 v[44:47], v[152:155], v[174:177], 0
	v_mfma_f32_16x16x32_bf16 v[36:39], v[144:147], v[182:185], 0
	v_mfma_f32_16x16x32_bf16 v[28:31], v[152:155], v[182:185], 0
	v_mfma_f32_16x16x32_bf16 v[20:23], v[144:147], v[196:199], 0
	v_mfma_f32_16x16x32_bf16 v[12:15], v[152:155], v[196:199], 0
	v_mfma_f32_16x16x32_bf16 v[4:7], v[144:147], v[204:207], 0
	v_mfma_f32_16x16x32_bf16 v[0:3], v[152:155], v[204:207], 0
	v_mfma_f32_16x16x32_bf16 v[52:55], v[148:151], v[178:181], v[52:55]
	v_mfma_f32_16x16x32_bf16 v[44:47], v[156:159], v[178:181], v[44:47]
	v_mfma_f32_16x16x32_bf16 v[36:39], v[148:151], v[192:195], v[36:39]
	v_mfma_f32_16x16x32_bf16 v[28:31], v[156:159], v[192:195], v[28:31]
	v_mfma_f32_16x16x32_bf16 v[20:23], v[148:151], v[200:203], v[20:23]
	v_mfma_f32_16x16x32_bf16 v[12:15], v[156:159], v[200:203], v[12:15]
	v_mfma_f32_16x16x32_bf16 v[4:7], v[148:151], v[208:211], v[4:7]
	v_mfma_f32_16x16x32_bf16 v[0:3], v[156:159], v[208:211], v[0:3]
	s_setprio 0
	s_barrier
	s_add_i32 s44, 0, 0x18000
	s_add_i32 s45, 0, 0x1c000
	v_add_u32_e32 v140, s44, v187
	v_add_u32_e32 v156, s45, v187
	ds_read_b128 v[128:131], v140
	ds_read_b128 v[132:135], v140 offset:1024
	ds_read_b128 v[136:139], v140 offset:2048
	ds_read_b128 v[140:143], v140 offset:3072
	ds_read_b128 v[144:147], v156
	ds_read_b128 v[148:151], v156 offset:1024
	ds_read_b128 v[152:155], v156 offset:2048
	ds_read_b128 v[156:159], v156 offset:3072
	s_add_u32 s20, s20, 0xb0000
	s_addc_u32 s21, s21, 0
	s_mov_b32 m0, s28
	v_lshl_add_u64 v[220:221], s[20:21], 0, v[160:161]
	ds_read_b128 v[174:177], v191 offset:32768
	ds_read_b128 v[178:181], v191 offset:33792
	ds_read_b128 v[182:185], v191 offset:34816
	ds_read_b128 v[192:195], v191 offset:35840
	ds_read_b128 v[196:199], v191 offset:36864
	ds_read_b128 v[200:203], v191 offset:37888
	ds_read_b128 v[204:207], v191 offset:38912
	ds_read_b128 v[208:211], v191 offset:39936
	global_load_lds_dwordx4 v[220:221], off sc0
	v_lshl_add_u64 v[220:221], s[20:21], 0, v[164:165]
	s_mov_b32 m0, s29
	s_nop 0
	global_load_lds_dwordx4 v[220:221], off sc0
	s_waitcnt vmcnt(8)
	s_waitcnt lgkmcnt(0)
	s_barrier
	s_setprio 1
	s_waitcnt lgkmcnt(0)
	v_mfma_f32_16x16x32_bf16 v[124:127], v[128:131], v[174:177], v[124:127]
	v_mfma_f32_16x16x32_bf16 v[120:123], v[136:139], v[174:177], v[120:123]
	v_mfma_f32_16x16x32_bf16 v[116:119], v[128:131], v[182:185], v[116:119]
	v_mfma_f32_16x16x32_bf16 v[104:107], v[136:139], v[182:185], v[104:107]
	v_mfma_f32_16x16x32_bf16 v[96:99], v[128:131], v[196:199], v[96:99]
	v_mfma_f32_16x16x32_bf16 v[88:91], v[136:139], v[196:199], v[88:91]
	v_mfma_f32_16x16x32_bf16 v[80:83], v[128:131], v[204:207], v[80:83]
	v_mfma_f32_16x16x32_bf16 v[72:75], v[136:139], v[204:207], v[72:75]
	v_mfma_f32_16x16x32_bf16 v[124:127], v[132:135], v[178:181], v[124:127]
	v_mfma_f32_16x16x32_bf16 v[120:123], v[140:143], v[178:181], v[120:123]
	v_mfma_f32_16x16x32_bf16 v[116:119], v[132:135], v[192:195], v[116:119]
	v_mfma_f32_16x16x32_bf16 v[104:107], v[140:143], v[192:195], v[104:107]
	v_mfma_f32_16x16x32_bf16 v[96:99], v[132:135], v[200:203], v[96:99]
	v_mfma_f32_16x16x32_bf16 v[88:91], v[140:143], v[200:203], v[88:91]
	v_mfma_f32_16x16x32_bf16 v[80:83], v[132:135], v[208:211], v[80:83]
	v_mfma_f32_16x16x32_bf16 v[72:75], v[140:143], v[208:211], v[72:75]
	s_setprio 0
	s_setprio 1
	v_mfma_f32_16x16x32_bf16 v[112:115], v[144:147], v[174:177], v[112:115]
	v_mfma_f32_16x16x32_bf16 v[108:111], v[152:155], v[174:177], v[108:111]
	v_mfma_f32_16x16x32_bf16 v[100:103], v[144:147], v[182:185], v[100:103]
	v_mfma_f32_16x16x32_bf16 v[92:95], v[152:155], v[182:185], v[92:95]
	v_mfma_f32_16x16x32_bf16 v[84:87], v[144:147], v[196:199], v[84:87]
	v_mfma_f32_16x16x32_bf16 v[76:79], v[152:155], v[196:199], v[76:79]
	v_mfma_f32_16x16x32_bf16 v[68:71], v[144:147], v[204:207], v[68:71]
	v_mfma_f32_16x16x32_bf16 v[64:67], v[152:155], v[204:207], v[64:67]
	v_mfma_f32_16x16x32_bf16 v[112:115], v[148:151], v[178:181], v[112:115]
	v_mfma_f32_16x16x32_bf16 v[108:111], v[156:159], v[178:181], v[108:111]
	v_mfma_f32_16x16x32_bf16 v[100:103], v[148:151], v[192:195], v[100:103]
	v_mfma_f32_16x16x32_bf16 v[92:95], v[156:159], v[192:195], v[92:95]
	v_mfma_f32_16x16x32_bf16 v[84:87], v[148:151], v[200:203], v[84:87]
	v_mfma_f32_16x16x32_bf16 v[76:79], v[156:159], v[200:203], v[76:79]
	v_mfma_f32_16x16x32_bf16 v[68:71], v[148:151], v[208:211], v[68:71]
	v_mfma_f32_16x16x32_bf16 v[64:67], v[156:159], v[208:211], v[64:67]
	s_setprio 0
	s_barrier
; #define PG8_STAGE(bufoff, gbase, voff) do { _Pragma("unroll") for (int _i = 0; _i < 2; ++_i) \
;         __builtin_amdgcn_global_load_lds((const unsigned*)((const char*)(gbase) + (voff)[_i]), (PG8_LAS unsigned*)(lds + (bufoff) + ldsw + _i * 8192), 16, 0, 0); } while (0)
; #define PG8_LDA(dst, b, h) do { _Pragma("unroll") for (int m = 0; m < 4; ++m) _Pragma("unroll") for (int k = 0; k < 2; ++k) dst[m][k] = *(const PG8_LAS bf16x8*)(lds + PG8_SA(b, h) + aoff + m * 2048 + k * 1024); } while (0)
; #define PG8_LDB(dst, b, h) do { _Pragma("unroll") for (int n = 0; n < 2; ++n) _Pragma("unroll") for (int k = 0; k < 2; ++k) dst[n][k] = *(const PG8_LAS bf16x8*)(lds + PG8_SB(b, h) + boff + n * 2048 + k * 1024); } while (0)
; #define PG8_MMA(ai, bj, At, Bt) do { __builtin_amdgcn_s_setprio(1); _Pragma("unroll") for (int m = 0; m < 4; ++m) _Pragma("unroll") for (int n = 0; n < 2; ++n) _Pragma("unroll") for (int k = 0; k < 2; ++k) \
;         acc[ai][bj][m][n] = __builtin_amdgcn_mfma_f32_16x16x32_bf16(Bt[n][k], At[m][k], acc[ai][bj][m][n], 0, 0, 0); __builtin_amdgcn_s_setprio(0); } while (0)
; #define PG8_WAIT_V(n) asm volatile("s_waitcnt vmcnt(" #n ")" ::: "memory")
; template <class Epi, class Sched, bool ALIGN_EPI = false, bool SP2 = false>
; __device__ __forceinline__ void gemm_phase(PG8_LAS unsigned char* lds, const Gemm g, const Sched& S, const Epi& E) {
;     ...
;             PG8_LDB(B0, 0, 0); PG8_LDB(B1, 0, 1); PG8_SCHED; PG8_LDA(At, 0, 0); PG8_STAGE(PG8_SA(1, 1), a1 + hstep, voffA);
;             PG8_WAIT_V(8); PG8_WAIT_L(0); PG8_BAR; PG8_MMA(0, 0, At, B0); PG8_MMA(0, 1, At, B1); PG8_BAR; PG8_SCHED;
;             PG8_LDA(At, 0, 1); PG8_STAGE(PG8_SB(0, 0), b2, voffB); PG8_STAGE(PG8_SB(0, 1), b2 + hstep, voffB); PG8_STAGE(PG8_SA(0, 0), a2, voffA);
;             PG8_WAIT_V(8); PG8_WAIT_L(0); PG8_BAR; PG8_MMA(1, 0, At, B0); PG8_MMA(1, 1, At, B1); PG8_BAR; PG8_SCHED;
;             PG8_LDB(B0, 1, 0); PG8_LDB(B1, 1, 1); PG8_SCHED; PG8_LDA(At, 1, 0); PG8_STAGE(PG8_SA(0, 1), a2 + hstep, voffA);
;             PG8_WAIT_V(8); PG8_WAIT_L(0); PG8_BAR; PG8_MMA(0, 0, At, B0); PG8_MMA(0, 1, At, B1); PG8_BAR; PG8_SCHED;
;             PG8_LDA(At, 1, 1); PG8_STAGE(PG8_SB(1, 0), b3, voffB); PG8_STAGE(PG8_SB(1, 1), b3 + hstep, voffB); PG8_STAGE(PG8_SA(1, 0), a3, voffA);
;             PG8_WAIT_V(8); PG8_WAIT_L(0); PG8_BAR; PG8_MMA(1, 0, At, B0); PG8_MMA(1, 1, At, B1); PG8_BAR; PG8_SCHED;
	s_add_i32 s20, s44, s25
	v_lshl_add_u64 v[212:213], v[212:213], 0, s[8:9]
	s_mov_b32 m0, s20
	ds_read_b128 v[174:177], v191 offset:49152
	ds_read_b128 v[178:181], v191 offset:50176
	ds_read_b128 v[182:185], v191 offset:51200
	ds_read_b128 v[192:195], v191 offset:52224
	ds_read_b128 v[196:199], v191 offset:53248
	ds_read_b128 v[200:203], v191 offset:54272
	ds_read_b128 v[204:207], v191 offset:55296
	ds_read_b128 v[208:211], v191 offset:56320
	global_load_lds_dwordx4 v[212:213], off sc0
	s_add_i32 m0, s20, 0x2000
	s_add_u32 s18, s18, 0xb0080
	v_lshl_add_u64 v[212:213], v[214:215], 0, s[8:9]
	s_addc_u32 s19, s19, 0
	s_add_i32 s20, s45, s25
	global_load_lds_dwordx4 v[212:213], off sc0
	v_lshl_add_u64 v[212:213], s[18:19], 0, v[162:163]
	s_mov_b32 m0, s20
	s_nop 0
	global_load_lds_dwordx4 v[212:213], off sc0
	v_lshl_add_u64 v[212:213], s[18:19], 0, v[166:167]
	s_add_i32 m0, s20, 0x2000
	s_nop 0
	global_load_lds_dwordx4 v[212:213], off sc0
	v_lshl_add_u64 v[212:213], v[216:217], 0, s[8:9]
	s_mov_b32 m0, s33
	s_nop 0
	global_load_lds_dwordx4 v[212:213], off sc0
	v_lshl_add_u64 v[212:213], v[218:219], 0, s[8:9]
	s_mov_b32 m0, s34
	s_nop 0
	global_load_lds_dwordx4 v[212:213], off sc0
	s_waitcnt vmcnt(8)
	s_waitcnt lgkmcnt(0)
	s_barrier
	s_setprio 1
	s_waitcnt lgkmcnt(0)
	v_mfma_f32_16x16x32_bf16 v[60:63], v[128:131], v[174:177], v[60:63]
	v_mfma_f32_16x16x32_bf16 v[56:59], v[136:139], v[174:177], v[56:59]
	v_mfma_f32_16x16x32_bf16 v[48:51], v[128:131], v[182:185], v[48:51]
	v_mfma_f32_16x16x32_bf16 v[40:43], v[136:139], v[182:185], v[40:43]
	v_mfma_f32_16x16x32_bf16 v[32:35], v[128:131], v[196:199], v[32:35]
	v_mfma_f32_16x16x32_bf16 v[24:27], v[136:139], v[196:199], v[24:27]
	v_mfma_f32_16x16x32_bf16 v[16:19], v[128:131], v[204:207], v[16:19]
	v_mfma_f32_16x16x32_bf16 v[8:11], v[136:139], v[204:207], v[8:11]
	v_mfma_f32_16x16x32_bf16 v[60:63], v[132:135], v[178:181], v[60:63]
	v_mfma_f32_16x16x32_bf16 v[56:59], v[140:143], v[178:181], v[56:59]
	v_mfma_f32_16x16x32_bf16 v[48:51], v[132:135], v[192:195], v[48:51]
	v_mfma_f32_16x16x32_bf16 v[40:43], v[140:143], v[192:195], v[40:43]
	v_mfma_f32_16x16x32_bf16 v[32:35], v[132:135], v[200:203], v[32:35]
	v_mfma_f32_16x16x32_bf16 v[24:27], v[140:143], v[200:203], v[24:27]
	v_mfma_f32_16x16x32_bf16 v[16:19], v[132:135], v[208:211], v[16:19]
	v_mfma_f32_16x16x32_bf16 v[8:11], v[140:143], v[208:211], v[8:11]
	s_setprio 0
	s_setprio 1
	v_mfma_f32_16x16x32_bf16 v[52:55], v[144:147], v[174:177], v[52:55]
	v_mfma_f32_16x16x32_bf16 v[44:47], v[152:155], v[174:177], v[44:47]
	v_mfma_f32_16x16x32_bf16 v[36:39], v[144:147], v[182:185], v[36:39]
	v_mfma_f32_16x16x32_bf16 v[28:31], v[152:155], v[182:185], v[28:31]
	v_mfma_f32_16x16x32_bf16 v[20:23], v[144:147], v[196:199], v[20:23]
	v_mfma_f32_16x16x32_bf16 v[12:15], v[152:155], v[196:199], v[12:15]
	v_mfma_f32_16x16x32_bf16 v[4:7], v[144:147], v[204:207], v[4:7]
	v_mfma_f32_16x16x32_bf16 v[0:3], v[152:155], v[204:207], v[0:3]
	v_mfma_f32_16x16x32_bf16 v[52:55], v[148:151], v[178:181], v[52:55]
	v_mfma_f32_16x16x32_bf16 v[44:47], v[156:159], v[178:181], v[44:47]
	v_mfma_f32_16x16x32_bf16 v[36:39], v[148:151], v[192:195], v[36:39]
	v_mfma_f32_16x16x32_bf16 v[28:31], v[156:159], v[192:195], v[28:31]
	v_mfma_f32_16x16x32_bf16 v[20:23], v[148:151], v[200:203], v[20:23]
	v_mfma_f32_16x16x32_bf16 v[12:15], v[156:159], v[200:203], v[12:15]
	v_mfma_f32_16x16x32_bf16 v[4:7], v[148:151], v[208:211], v[4:7]
	v_mfma_f32_16x16x32_bf16 v[0:3], v[156:159], v[208:211], v[0:3]
	s_setprio 0
	s_barrier
	s_add_i32 s43, s43, 2
	s_add_u32 s16, s16, 0x100
	s_addc_u32 s17, s17, 0
	s_add_u32 s41, s41, 0x100
	s_addc_u32 s42, s42, 0
	s_cmp_gt_u32 s43, 41
.LBB0_1062:
	ds_read_b128 v[128:131], v189
	ds_read_b128 v[132:135], v189 offset:1024
	ds_read_b128 v[136:139], v189 offset:2048
	ds_read_b128 v[140:143], v189 offset:3072
	ds_read_b128 v[144:147], v190
	ds_read_b128 v[148:151], v190 offset:1024
	ds_read_b128 v[152:155], v190 offset:2048
	ds_read_b128 v[156:159], v190 offset:3072
	s_add_u32 s18, s16, 0xfff50080
	s_addc_u32 s19, s17, -1
	s_cmp_eq_u32 s43, 40
	s_cselect_b32 s21, s13, s19
	s_cselect_b32 s20, s12, s18
	s_cselect_b32 s19, s15, s42
	s_cselect_b32 s18, s14, s41
	v_lshl_add_u64 v[212:213], s[16:17], 0, v[168:169]
	s_add_i32 m0, s26, 0xc000
	ds_read_b128 v[174:177], v191
	ds_read_b128 v[178:181], v191 offset:1024
	ds_read_b128 v[182:185], v191 offset:2048
	ds_read_b128 v[192:195], v191 offset:3072
	ds_read_b128 v[196:199], v191 offset:4096
	ds_read_b128 v[200:203], v191 offset:5120
	ds_read_b128 v[204:207], v191 offset:6144
	ds_read_b128 v[208:211], v191 offset:7168
	global_load_lds_dwordx4 v[212:213], off sc0
	v_lshl_add_u64 v[212:213], s[16:17], 0, v[170:171]
	s_add_i32 m0, s26, 0xe000
	s_nop 0
	global_load_lds_dwordx4 v[212:213], off sc0
	s_waitcnt vmcnt(8)
	s_waitcnt lgkmcnt(0)
	s_barrier
; #define PG8_STAGE(bufoff, gbase, voff) do { _Pragma("unroll") for (int _i = 0; _i < 2; ++_i) \
;         __builtin_amdgcn_global_load_lds((const unsigned*)((const char*)(gbase) + (voff)[_i]), (PG8_LAS unsigned*)(lds + (bufoff) + ldsw + _i * 8192), 16, 0, 0); } while (0)
; #define PG8_LDA(dst, b, h) do { _Pragma("unroll") for (int m = 0; m < 4; ++m) _Pragma("unroll") for (int k = 0; k < 2; ++k) dst[m][k] = *(const PG8_LAS bf16x8*)(lds + PG8_SA(b, h) + aoff + m * 2048 + k * 1024); } while (0)
; #define PG8_LDB(dst, b, h) do { _Pragma("unroll") for (int n = 0; n < 2; ++n) _Pragma("unroll") for (int k = 0; k < 2; ++k) dst[n][k] = *(const PG8_LAS bf16x8*)(lds + PG8_SB(b, h) + boff + n * 2048 + k * 1024); } while (0)
; #define PG8_MMA(ai, bj, At, Bt) do { __builtin_amdgcn_s_setprio(1); _Pragma("unroll") for (int m = 0; m < 4; ++m) _Pragma("unroll") for (int n = 0; n < 2; ++n) _Pragma("unroll") for (int k = 0; k < 2; ++k) \
;         acc[ai][bj][m][n] = __builtin_amdgcn_mfma_f32_16x16x32_bf16(Bt[n][k], At[m][k], acc[ai][bj][m][n], 0, 0, 0); __builtin_amdgcn_s_setprio(0); } while (0)
; #define PG8_WAIT_V(n) asm volatile("s_waitcnt vmcnt(" #n ")" ::: "memory")
; #define PG8_WAIT_L(n) asm volatile("s_waitcnt lgkmcnt(" #n ")" ::: "memory")
; #define PG8_BAR __builtin_amdgcn_s_barrier()
; #define PG8_SCHED __builtin_amdgcn_sched_barrier(0)
; template <class Epi, class Sched, bool ALIGN_EPI = false, bool SP2 = false>
; __device__ __forceinline__ void gemm_phase(PG8_LAS unsigned char* lds, const Gemm g, const Sched& S, const Epi& E) {
;     ...
;             if constexpr (SP2) {
;             PG8_LDB(B0, 0, 0); PG8_LDB(B1, 0, 1); PG8_SCHED; PG8_LDA(At, 0, 0); PG8_STAGE(PG8_SA(1, 1), a1 + hstep, voffA);
;             PG8_WAIT_V(8); PG8_WAIT_L(0); PG8_BAR; PG8_MMA(0, 0, At, B0); PG8_MMA(0, 1, At, B1); PG8_BAR; PG8_SCHED;
;             PG8_LDA(At, 0, 1); PG8_STAGE(PG8_SB(0, 0), b2, voffB); PG8_STAGE(PG8_SB(0, 1), b2 + hstep, voffB); PG8_STAGE(PG8_SA(0, 0), a2, voffA);
;             PG8_WAIT_V(8); PG8_WAIT_L(0); PG8_BAR; PG8_MMA(1, 0, At, B0); PG8_MMA(1, 1, At, B1); PG8_BAR; PG8_SCHED;
	s_setprio 1
	s_waitcnt lgkmcnt(0)
	v_mfma_f32_16x16x32_bf16 v[124:127], v[128:131], v[174:177], v[124:127]
	v_mfma_f32_16x16x32_bf16 v[120:123], v[136:139], v[174:177], v[120:123]
	v_mfma_f32_16x16x32_bf16 v[116:119], v[128:131], v[182:185], v[116:119]
	v_mfma_f32_16x16x32_bf16 v[104:107], v[136:139], v[182:185], v[104:107]
	v_mfma_f32_16x16x32_bf16 v[96:99], v[128:131], v[196:199], v[96:99]
	v_mfma_f32_16x16x32_bf16 v[88:91], v[136:139], v[196:199], v[88:91]
	v_mfma_f32_16x16x32_bf16 v[80:83], v[128:131], v[204:207], v[80:83]
	v_mfma_f32_16x16x32_bf16 v[72:75], v[136:139], v[204:207], v[72:75]
	v_mfma_f32_16x16x32_bf16 v[124:127], v[132:135], v[178:181], v[124:127]
	v_mfma_f32_16x16x32_bf16 v[120:123], v[140:143], v[178:181], v[120:123]
	v_mfma_f32_16x16x32_bf16 v[116:119], v[132:135], v[192:195], v[116:119]
	v_mfma_f32_16x16x32_bf16 v[104:107], v[140:143], v[192:195], v[104:107]
	v_mfma_f32_16x16x32_bf16 v[96:99], v[132:135], v[200:203], v[96:99]
	v_mfma_f32_16x16x32_bf16 v[88:91], v[140:143], v[200:203], v[88:91]
	v_mfma_f32_16x16x32_bf16 v[80:83], v[132:135], v[208:211], v[80:83]
	v_mfma_f32_16x16x32_bf16 v[72:75], v[140:143], v[208:211], v[72:75]
	s_setprio 0
	s_setprio 1
	v_mfma_f32_16x16x32_bf16 v[112:115], v[144:147], v[174:177], v[112:115]
	v_mfma_f32_16x16x32_bf16 v[108:111], v[152:155], v[174:177], v[108:111]
	v_mfma_f32_16x16x32_bf16 v[100:103], v[144:147], v[182:185], v[100:103]
	v_mfma_f32_16x16x32_bf16 v[92:95], v[152:155], v[182:185], v[92:95]
	v_mfma_f32_16x16x32_bf16 v[84:87], v[144:147], v[196:199], v[84:87]
	v_mfma_f32_16x16x32_bf16 v[76:79], v[152:155], v[196:199], v[76:79]
	v_mfma_f32_16x16x32_bf16 v[68:71], v[144:147], v[204:207], v[68:71]
	v_mfma_f32_16x16x32_bf16 v[64:67], v[152:155], v[204:207], v[64:67]
	v_mfma_f32_16x16x32_bf16 v[112:115], v[148:151], v[178:181], v[112:115]
	v_mfma_f32_16x16x32_bf16 v[108:111], v[156:159], v[178:181], v[108:111]
	v_mfma_f32_16x16x32_bf16 v[100:103], v[148:151], v[192:195], v[100:103]
	v_mfma_f32_16x16x32_bf16 v[92:95], v[156:159], v[192:195], v[92:95]
	v_mfma_f32_16x16x32_bf16 v[84:87], v[148:151], v[200:203], v[84:87]
	v_mfma_f32_16x16x32_bf16 v[76:79], v[156:159], v[200:203], v[76:79]
	v_mfma_f32_16x16x32_bf16 v[68:71], v[148:151], v[208:211], v[68:71]
	v_mfma_f32_16x16x32_bf16 v[64:67], v[156:159], v[208:211], v[64:67]
	s_setprio 0
	s_barrier
	s_add_i32 s44, s35, s25
	v_lshl_add_u64 v[212:213], s[18:19], 0, v[162:163]
	s_mov_b32 m0, s44
	ds_read_b128 v[174:177], v191 offset:16384
	ds_read_b128 v[178:181], v191 offset:17408
	ds_read_b128 v[182:185], v191 offset:18432
	ds_read_b128 v[192:195], v191 offset:19456
	ds_read_b128 v[196:199], v191 offset:20480
	ds_read_b128 v[200:203], v191 offset:21504
	ds_read_b128 v[204:207], v191 offset:22528
	ds_read_b128 v[208:211], v191 offset:23552
	global_load_lds_dwordx4 v[212:213], off sc0
	s_add_i32 m0, s44, 0x2000
	s_add_u32 s44, s18, 0xb0000
	v_lshl_add_u64 v[214:215], s[18:19], 0, v[166:167]
	s_addc_u32 s45, s19, 0
	s_add_i32 s46, s36, s25
	global_load_lds_dwordx4 v[214:215], off sc0
	v_lshl_add_u64 v[216:217], s[44:45], 0, v[162:163]
	s_mov_b32 m0, s46
	v_lshl_add_u64 v[218:219], s[20:21], 0, v[164:165]
	global_load_lds_dwordx4 v[216:217], off sc0
	v_lshl_add_u64 v[216:217], s[44:45], 0, v[166:167]
	s_add_i32 m0, s46, 0x2000
	s_nop 0
	global_load_lds_dwordx4 v[216:217], off sc0
	v_lshl_add_u64 v[216:217], s[20:21], 0, v[160:161]
	s_mov_b32 m0, s26
	s_nop 0
	global_load_lds_dwordx4 v[216:217], off sc0
	s_mov_b32 m0, s27
	s_nop 0
	global_load_lds_dwordx4 v[218:219], off sc0
	s_waitcnt vmcnt(8)
	s_waitcnt lgkmcnt(0)
	s_barrier
	s_setprio 1
	s_waitcnt lgkmcnt(0)
	v_mfma_f32_16x16x32_bf16 v[60:63], v[128:131], v[174:177], v[60:63]
	v_mfma_f32_16x16x32_bf16 v[56:59], v[136:139], v[174:177], v[56:59]
	v_mfma_f32_16x16x32_bf16 v[48:51], v[128:131], v[182:185], v[48:51]
	v_mfma_f32_16x16x32_bf16 v[40:43], v[136:139], v[182:185], v[40:43]
	v_mfma_f32_16x16x32_bf16 v[32:35], v[128:131], v[196:199], v[32:35]
	v_mfma_f32_16x16x32_bf16 v[24:27], v[136:139], v[196:199], v[24:27]
	v_mfma_f32_16x16x32_bf16 v[16:19], v[128:131], v[204:207], v[16:19]
	v_mfma_f32_16x16x32_bf16 v[8:11], v[136:139], v[204:207], v[8:11]
	v_mfma_f32_16x16x32_bf16 v[60:63], v[132:135], v[178:181], v[60:63]
	v_mfma_f32_16x16x32_bf16 v[56:59], v[140:143], v[178:181], v[56:59]
	v_mfma_f32_16x16x32_bf16 v[48:51], v[132:135], v[192:195], v[48:51]
	v_mfma_f32_16x16x32_bf16 v[40:43], v[140:143], v[192:195], v[40:43]
	v_mfma_f32_16x16x32_bf16 v[32:35], v[132:135], v[200:203], v[32:35]
	v_mfma_f32_16x16x32_bf16 v[24:27], v[140:143], v[200:203], v[24:27]
	v_mfma_f32_16x16x32_bf16 v[16:19], v[132:135], v[208:211], v[16:19]
	v_mfma_f32_16x16x32_bf16 v[8:11], v[140:143], v[208:211], v[8:11]
	s_setprio 0
	s_setprio 1
	v_mfma_f32_16x16x32_bf16 v[52:55], v[144:147], v[174:177], v[52:55]
	v_mfma_f32_16x16x32_bf16 v[44:47], v[152:155], v[174:177], v[44:47]
	v_mfma_f32_16x16x32_bf16 v[36:39], v[144:147], v[182:185], v[36:39]
	v_mfma_f32_16x16x32_bf16 v[28:31], v[152:155], v[182:185], v[28:31]
	v_mfma_f32_16x16x32_bf16 v[20:23], v[144:147], v[196:199], v[20:23]
	v_mfma_f32_16x16x32_bf16 v[12:15], v[152:155], v[196:199], v[12:15]
	v_mfma_f32_16x16x32_bf16 v[4:7], v[144:147], v[204:207], v[4:7]
	v_mfma_f32_16x16x32_bf16 v[0:3], v[152:155], v[204:207], v[0:3]
	v_mfma_f32_16x16x32_bf16 v[52:55], v[148:151], v[178:181], v[52:55]
	v_mfma_f32_16x16x32_bf16 v[44:47], v[156:159], v[178:181], v[44:47]
	v_mfma_f32_16x16x32_bf16 v[36:39], v[148:151], v[192:195], v[36:39]
	v_mfma_f32_16x16x32_bf16 v[28:31], v[156:159], v[192:195], v[28:31]
	v_mfma_f32_16x16x32_bf16 v[20:23], v[148:151], v[200:203], v[20:23]
	v_mfma_f32_16x16x32_bf16 v[12:15], v[156:159], v[200:203], v[12:15]
	v_mfma_f32_16x16x32_bf16 v[4:7], v[148:151], v[208:211], v[4:7]
	v_mfma_f32_16x16x32_bf16 v[0:3], v[156:159], v[208:211], v[0:3]
	s_setprio 0
	s_barrier
; #define PG8_STAGE(bufoff, gbase, voff) do { _Pragma("unroll") for (int _i = 0; _i < 2; ++_i) \
;         __builtin_amdgcn_global_load_lds((const unsigned*)((const char*)(gbase) + (voff)[_i]), (PG8_LAS unsigned*)(lds + (bufoff) + ldsw + _i * 8192), 16, 0, 0); } while (0)
; #define PG8_LDA(dst, b, h) do { _Pragma("unroll") for (int m = 0; m < 4; ++m) _Pragma("unroll") for (int k = 0; k < 2; ++k) dst[m][k] = *(const PG8_LAS bf16x8*)(lds + PG8_SA(b, h) + aoff + m * 2048 + k * 1024); } while (0)
; #define PG8_LDB(dst, b, h) do { _Pragma("unroll") for (int n = 0; n < 2; ++n) _Pragma("unroll") for (int k = 0; k < 2; ++k) dst[n][k] = *(const PG8_LAS bf16x8*)(lds + PG8_SB(b, h) + boff + n * 2048 + k * 1024); } while (0)
; #define PG8_MMA(ai, bj, At, Bt) do { __builtin_amdgcn_s_setprio(1); _Pragma("unroll") for (int m = 0; m < 4; ++m) _Pragma("unroll") for (int n = 0; n < 2; ++n) _Pragma("unroll") for (int k = 0; k < 2; ++k) \
;         acc[ai][bj][m][n] = __builtin_amdgcn_mfma_f32_16x16x32_bf16(Bt[n][k], At[m][k], acc[ai][bj][m][n], 0, 0, 0); __builtin_amdgcn_s_setprio(0); } while (0)
; #define PG8_WAIT_V(n) asm volatile("s_waitcnt vmcnt(" #n ")" ::: "memory")
; #define PG8_WAIT_L(n) asm volatile("s_waitcnt lgkmcnt(" #n ")" ::: "memory")
; #define PG8_BAR __builtin_amdgcn_s_barrier()
; #define PG8_SCHED __builtin_amdgcn_sched_barrier(0)
; template <class Epi, class Sched, bool ALIGN_EPI = false, bool SP2 = false>
; __device__ __forceinline__ void gemm_phase(PG8_LAS unsigned char* lds, const Gemm g, const Sched& S, const Epi& E) {
;     ...
;             PG8_LDB(B0, 1, 0); PG8_LDB(B1, 1, 1); PG8_SCHED; PG8_LDA(At, 1, 0); PG8_STAGE(PG8_SA(0, 1), a2 + hstep, voffA);
;             PG8_WAIT_V(8); PG8_WAIT_L(0); PG8_BAR; PG8_MMA(0, 0, At, B0); PG8_MMA(0, 1, At, B1); PG8_BAR; PG8_SCHED;
	s_add_i32 s44, 0, 0x18000
	s_add_i32 s45, 0, 0x1c000
	v_add_u32_e32 v140, s44, v187
	v_add_u32_e32 v156, s45, v187
	ds_read_b128 v[128:131], v140
	ds_read_b128 v[132:135], v140 offset:1024
	ds_read_b128 v[136:139], v140 offset:2048
	ds_read_b128 v[140:143], v140 offset:3072
	ds_read_b128 v[144:147], v156
	ds_read_b128 v[148:151], v156 offset:1024
	ds_read_b128 v[152:155], v156 offset:2048
	ds_read_b128 v[156:159], v156 offset:3072
	s_add_u32 s20, s20, 0xb0000
	s_addc_u32 s21, s21, 0
	s_mov_b32 m0, s28
	v_lshl_add_u64 v[220:221], s[20:21], 0, v[160:161]
	ds_read_b128 v[174:177], v191 offset:32768
	ds_read_b128 v[178:181], v191 offset:33792
	ds_read_b128 v[182:185], v191 offset:34816
	ds_read_b128 v[192:195], v191 offset:35840
	ds_read_b128 v[196:199], v191 offset:36864
	ds_read_b128 v[200:203], v191 offset:37888
	ds_read_b128 v[204:207], v191 offset:38912
	ds_read_b128 v[208:211], v191 offset:39936
	global_load_lds_dwordx4 v[220:221], off sc0
	v_lshl_add_u64 v[220:221], s[20:21], 0, v[164:165]
	s_mov_b32 m0, s29
	s_nop 0
	global_load_lds_dwordx4 v[220:221], off sc0
	s_waitcnt vmcnt(8)
	s_waitcnt lgkmcnt(0)
	s_barrier
	s_setprio 1
	s_waitcnt lgkmcnt(0)
	v_mfma_f32_16x16x32_bf16 v[124:127], v[128:131], v[174:177], v[124:127]
	v_mfma_f32_16x16x32_bf16 v[120:123], v[136:139], v[174:177], v[120:123]
	v_mfma_f32_16x16x32_bf16 v[116:119], v[128:131], v[182:185], v[116:119]
	v_mfma_f32_16x16x32_bf16 v[104:107], v[136:139], v[182:185], v[104:107]
	v_mfma_f32_16x16x32_bf16 v[96:99], v[128:131], v[196:199], v[96:99]
	v_mfma_f32_16x16x32_bf16 v[88:91], v[136:139], v[196:199], v[88:91]
	v_mfma_f32_16x16x32_bf16 v[80:83], v[128:131], v[204:207], v[80:83]
	v_mfma_f32_16x16x32_bf16 v[72:75], v[136:139], v[204:207], v[72:75]
	v_mfma_f32_16x16x32_bf16 v[124:127], v[132:135], v[178:181], v[124:127]
	v_mfma_f32_16x16x32_bf16 v[120:123], v[140:143], v[178:181], v[120:123]
	v_mfma_f32_16x16x32_bf16 v[116:119], v[132:135], v[192:195], v[116:119]
	v_mfma_f32_16x16x32_bf16 v[104:107], v[140:143], v[192:195], v[104:107]
	v_mfma_f32_16x16x32_bf16 v[96:99], v[132:135], v[200:203], v[96:99]
	v_mfma_f32_16x16x32_bf16 v[88:91], v[140:143], v[200:203], v[88:91]
	v_mfma_f32_16x16x32_bf16 v[80:83], v[132:135], v[208:211], v[80:83]
	v_mfma_f32_16x16x32_bf16 v[72:75], v[140:143], v[208:211], v[72:75]
	s_setprio 0
	s_setprio 1
	v_mfma_f32_16x16x32_bf16 v[112:115], v[144:147], v[174:177], v[112:115]
	v_mfma_f32_16x16x32_bf16 v[108:111], v[152:155], v[174:177], v[108:111]
	v_mfma_f32_16x16x32_bf16 v[100:103], v[144:147], v[182:185], v[100:103]
	v_mfma_f32_16x16x32_bf16 v[92:95], v[152:155], v[182:185], v[92:95]
	v_mfma_f32_16x16x32_bf16 v[84:87], v[144:147], v[196:199], v[84:87]
	v_mfma_f32_16x16x32_bf16 v[76:79], v[152:155], v[196:199], v[76:79]
	v_mfma_f32_16x16x32_bf16 v[68:71], v[144:147], v[204:207], v[68:71]
	v_mfma_f32_16x16x32_bf16 v[64:67], v[152:155], v[204:207], v[64:67]
	v_mfma_f32_16x16x32_bf16 v[112:115], v[148:151], v[178:181], v[112:115]
	v_mfma_f32_16x16x32_bf16 v[108:111], v[156:159], v[178:181], v[108:111]
	v_mfma_f32_16x16x32_bf16 v[100:103], v[148:151], v[192:195], v[100:103]
	v_mfma_f32_16x16x32_bf16 v[92:95], v[156:159], v[192:195], v[92:95]
	v_mfma_f32_16x16x32_bf16 v[84:87], v[148:151], v[200:203], v[84:87]
	v_mfma_f32_16x16x32_bf16 v[76:79], v[156:159], v[200:203], v[76:79]
	v_mfma_f32_16x16x32_bf16 v[68:71], v[148:151], v[208:211], v[68:71]
	v_mfma_f32_16x16x32_bf16 v[64:67], v[156:159], v[208:211], v[64:67]
	s_setprio 0
	s_barrier
; #define PG8_STAGE(bufoff, gbase, voff) do { _Pragma("unroll") for (int _i = 0; _i < 2; ++_i) \
;         __builtin_amdgcn_global_load_lds((const unsigned*)((const char*)(gbase) + (voff)[_i]), (PG8_LAS unsigned*)(lds + (bufoff) + ldsw + _i * 8192), 16, 0, 0); } while (0)
; #define PG8_LDA(dst, b, h) do { _Pragma("unroll") for (int m = 0; m < 4; ++m) _Pragma("unroll") for (int k = 0; k < 2; ++k) dst[m][k] = *(const PG8_LAS bf16x8*)(lds + PG8_SA(b, h) + aoff + m * 2048 + k * 1024); } while (0)
; #define PG8_MMA(ai, bj, At, Bt) do { __builtin_amdgcn_s_setprio(1); _Pragma("unroll") for (int m = 0; m < 4; ++m) _Pragma("unroll") for (int n = 0; n < 2; ++n) _Pragma("unroll") for (int k = 0; k < 2; ++k) \
;         acc[ai][bj][m][n] = __builtin_amdgcn_mfma_f32_16x16x32_bf16(Bt[n][k], At[m][k], acc[ai][bj][m][n], 0, 0, 0); __builtin_amdgcn_s_setprio(0); } while (0)
; #define PG8_WAIT_V(n) asm volatile("s_waitcnt vmcnt(" #n ")" ::: "memory")
; #define PG8_WAIT_L(n) asm volatile("s_waitcnt lgkmcnt(" #n ")" ::: "memory")
; #define PG8_BAR __builtin_amdgcn_s_barrier()
; #define PG8_SCHED __builtin_amdgcn_sched_barrier(0)
; template <class Epi, class Sched, bool ALIGN_EPI = false, bool SP2 = false>
; __device__ __forceinline__ void gemm_phase(PG8_LAS unsigned char* lds, const Gemm g, const Sched& S, const Epi& E) {
;     ...
;             PG8_LDA(At, 1, 1); PG8_STAGE(PG8_SB(1, 0), b3, voffB); PG8_STAGE(PG8_SB(1, 1), b3 + hstep, voffB); PG8_STAGE(PG8_SA(1, 0), a3, voffA);
;             PG8_WAIT_V(8); PG8_WAIT_L(0); PG8_BAR; PG8_MMA(1, 0, At, B0); PG8_MMA(1, 1, At, B1); PG8_BAR; PG8_SCHED;
;     ...
;         if constexpr (ALIGN_EPI) { if (wr == 0) PG8_BAR; }
	s_add_i32 s20, s44, s25
	v_lshl_add_u64 v[212:213], v[212:213], 0, s[8:9]
	s_mov_b32 m0, s20
	ds_read_b128 v[174:177], v191 offset:49152
	ds_read_b128 v[178:181], v191 offset:50176
	ds_read_b128 v[182:185], v191 offset:51200
	ds_read_b128 v[192:195], v191 offset:52224
	ds_read_b128 v[196:199], v191 offset:53248
	ds_read_b128 v[200:203], v191 offset:54272
	ds_read_b128 v[204:207], v191 offset:55296
	ds_read_b128 v[208:211], v191 offset:56320
	global_load_lds_dwordx4 v[212:213], off sc0
	s_add_i32 m0, s20, 0x2000
	s_add_u32 s18, s18, 0xb0080
	v_lshl_add_u64 v[212:213], v[214:215], 0, s[8:9]
	s_addc_u32 s19, s19, 0
	s_add_i32 s20, s45, s25
	global_load_lds_dwordx4 v[212:213], off sc0
	v_lshl_add_u64 v[212:213], s[18:19], 0, v[162:163]
	s_mov_b32 m0, s20
	s_nop 0
	global_load_lds_dwordx4 v[212:213], off sc0
	v_lshl_add_u64 v[212:213], s[18:19], 0, v[166:167]
	s_add_i32 m0, s20, 0x2000
	s_nop 0
	global_load_lds_dwordx4 v[212:213], off sc0
	v_lshl_add_u64 v[212:213], v[216:217], 0, s[8:9]
	s_mov_b32 m0, s33
	s_nop 0
	global_load_lds_dwordx4 v[212:213], off sc0
	v_lshl_add_u64 v[212:213], v[218:219], 0, s[8:9]
	s_mov_b32 m0, s34
	s_nop 0
	global_load_lds_dwordx4 v[212:213], off sc0
	s_waitcnt vmcnt(8)
	s_waitcnt lgkmcnt(0)
	s_barrier
	s_setprio 1
	s_waitcnt lgkmcnt(0)
	v_mfma_f32_16x16x32_bf16 v[60:63], v[128:131], v[174:177], v[60:63]
	v_mfma_f32_16x16x32_bf16 v[56:59], v[136:139], v[174:177], v[56:59]
	v_mfma_f32_16x16x32_bf16 v[48:51], v[128:131], v[182:185], v[48:51]
	v_mfma_f32_16x16x32_bf16 v[40:43], v[136:139], v[182:185], v[40:43]
	v_mfma_f32_16x16x32_bf16 v[32:35], v[128:131], v[196:199], v[32:35]
	v_mfma_f32_16x16x32_bf16 v[24:27], v[136:139], v[196:199], v[24:27]
	v_mfma_f32_16x16x32_bf16 v[16:19], v[128:131], v[204:207], v[16:19]
	v_mfma_f32_16x16x32_bf16 v[8:11], v[136:139], v[204:207], v[8:11]
	v_mfma_f32_16x16x32_bf16 v[60:63], v[132:135], v[178:181], v[60:63]
	v_mfma_f32_16x16x32_bf16 v[56:59], v[140:143], v[178:181], v[56:59]
	v_mfma_f32_16x16x32_bf16 v[48:51], v[132:135], v[192:195], v[48:51]
	v_mfma_f32_16x16x32_bf16 v[40:43], v[140:143], v[192:195], v[40:43]
	v_mfma_f32_16x16x32_bf16 v[32:35], v[132:135], v[200:203], v[32:35]
	v_mfma_f32_16x16x32_bf16 v[24:27], v[140:143], v[200:203], v[24:27]
	v_mfma_f32_16x16x32_bf16 v[16:19], v[132:135], v[208:211], v[16:19]
	v_mfma_f32_16x16x32_bf16 v[8:11], v[140:143], v[208:211], v[8:11]
	s_setprio 0
	s_setprio 1
	v_mfma_f32_16x16x32_bf16 v[52:55], v[144:147], v[174:177], v[52:55]
	v_mfma_f32_16x16x32_bf16 v[44:47], v[152:155], v[174:177], v[44:47]
	v_mfma_f32_16x16x32_bf16 v[36:39], v[144:147], v[182:185], v[36:39]
	v_mfma_f32_16x16x32_bf16 v[28:31], v[152:155], v[182:185], v[28:31]
	v_mfma_f32_16x16x32_bf16 v[20:23], v[144:147], v[196:199], v[20:23]
	v_mfma_f32_16x16x32_bf16 v[12:15], v[152:155], v[196:199], v[12:15]
	v_mfma_f32_16x16x32_bf16 v[4:7], v[144:147], v[204:207], v[4:7]
	v_mfma_f32_16x16x32_bf16 v[0:3], v[152:155], v[204:207], v[0:3]
	v_mfma_f32_16x16x32_bf16 v[52:55], v[148:151], v[178:181], v[52:55]
	v_mfma_f32_16x16x32_bf16 v[44:47], v[156:159], v[178:181], v[44:47]
	v_mfma_f32_16x16x32_bf16 v[36:39], v[148:151], v[192:195], v[36:39]
	v_mfma_f32_16x16x32_bf16 v[28:31], v[156:159], v[192:195], v[28:31]
	v_mfma_f32_16x16x32_bf16 v[20:23], v[148:151], v[200:203], v[20:23]
	v_mfma_f32_16x16x32_bf16 v[12:15], v[156:159], v[200:203], v[12:15]
	v_mfma_f32_16x16x32_bf16 v[4:7], v[148:151], v[208:211], v[4:7]
	v_mfma_f32_16x16x32_bf16 v[0:3], v[156:159], v[208:211], v[0:3]
	s_setprio 0
	s_barrier
	s_add_i32 s43, s43, 2
	s_add_u32 s16, s16, 0x100
	s_addc_u32 s17, s17, 0
	s_add_u32 s41, s41, 0x100
	s_addc_u32 s42, s42, 0
	s_cmp_gt_u32 s43, 41
	s_cbranch_scc0 .LBB0_1062
	s_and_b64 vcc, exec, s[10:11]
	s_cbranch_vccz .LBB0_1065
	s_barrier
